# k6 + PEER u-side rows: one dot accumulation chain per row into the row's partial-sum register (no final add / DL-op pad)
# speedup vs baseline: 1.0010x; 1.0010x over previous
; #define P4_FOR16(M) M(0) M(1) M(2) M(3) M(4) M(5) M(6) M(7) M(8) M(9) M(10) M(11) M(12) M(13) M(14) M(15)
; #define P4_U(i) { P4_DOT(b##i, part[i]); const int nk_ = __builtin_amdgcn_readlane(ksel, nb + i); P4_LOAD(b##i, Ug, nk_); }
; #define P4_U(i) { P4_DOT(b##i, part[i]); const int nk_ = __builtin_amdgcn_readlane(kn, i); P4_LOAD(b##i, nbase, nk_); }
; __device__ __forceinline__ void peer_gather_f4p(const float* X, const int* __restrict__ IDX, const float* __restrict__ G, ...
;     ...
; #pragma unroll 1
;         for (int bt = 0; bt < 7; ++bt) {
;             const int ksel = (bt + 1 < 4) ? k0 : k1;
;             const int nb = (16 * (bt + 1)) & 63;
;     ...
;             P4_FOR16(P4_U)
.LBB0_533:
	s_mov_b32 s87, s86
	s_waitcnt vmcnt(15)
	v_cvt_scalef32_pk_bf16_fp4 v48, v64, 1.0
	v_cvt_scalef32_pk_bf16_fp4 v50, v64, 1.0 op_sel:[1,0,0]
	v_cvt_scalef32_pk_bf16_fp4 v52, v64, 1.0 op_sel:[0,1,0]
	v_cvt_scalef32_pk_bf16_fp4 v54, v64, 1.0 op_sel:[1,1,0]
	v_dot2_f32_bf16 v56, v48, v6, 0
	v_dot2_f32_bf16 v48, v50, v4, 0
	v_dot2_f32_bf16 v56, v52, v10, v56
	s_cmp_lt_u32 s29, 3
	v_dot2_f32_bf16 v48, v54, v8, v48
	v_cvt_scalef32_pk_bf16_fp4 v50, v65, 1.0
	v_cvt_scalef32_pk_bf16_fp4 v52, v65, 1.0 op_sel:[1,0,0]
	v_cvt_scalef32_pk_bf16_fp4 v54, v65, 1.0 op_sel:[0,1,0]
	v_cvt_scalef32_pk_bf16_fp4 v58, v65, 1.0 op_sel:[1,1,0]
	s_cselect_b64 s[50:51], -1, 0
	v_dot2_f32_bf16 v56, v50, v14, v56
	v_dot2_f32_bf16 v48, v52, v12, v48
	s_waitcnt lgkmcnt(1)
	v_cndmask_b32_e64 v46, v39, v38, s[50:51]
	v_dot2_f32_bf16 v56, v54, v18, v56
	v_dot2_f32_bf16 v48, v58, v16, v48
	v_cvt_scalef32_pk_bf16_fp4 v50, v66, 1.0
	v_cvt_scalef32_pk_bf16_fp4 v52, v66, 1.0 op_sel:[1,0,0]
	v_cvt_scalef32_pk_bf16_fp4 v54, v66, 1.0 op_sel:[0,1,0]
	v_cvt_scalef32_pk_bf16_fp4 v58, v66, 1.0 op_sel:[1,1,0]
	s_add_i32 s12, s28, -15
	v_dot2_f32_bf16 v56, v50, v22, v56
	v_dot2_f32_bf16 v48, v52, v20, v48
	v_readlane_b32 s12, v46, s12
	v_dot2_f32_bf16 v56, v54, v26, v56
	v_dot2_f32_bf16 v48, v58, v24, v48
	v_cvt_scalef32_pk_bf16_fp4 v50, v67, 1.0
	v_cvt_scalef32_pk_bf16_fp4 v52, v67, 1.0 op_sel:[1,0,0]
	v_cvt_scalef32_pk_bf16_fp4 v54, v67, 1.0 op_sel:[0,1,0]
	v_cvt_scalef32_pk_bf16_fp4 v58, v67, 1.0 op_sel:[1,1,0]
	s_lshr_b32 s12, s12, 7
	v_dot2_f32_bf16 v56, v50, v30, v56
	v_dot2_f32_bf16 v48, v52, v28, v48
	s_mov_b32 s13, s86
	v_dot2_f32_bf16 v56, v54, v36, v56
	v_dot2_f32_bf16 v48, v58, v34, v48
	s_lshl_b64 s[12:13], s[12:13], 10
	s_nop 2
	v_readfirstlane_b32 s100, v40
	v_readfirstlane_b32 s101, v41
	v_subrev_u32_e32 v207, s100, v40
	v_add_f32_e32 v47, v56, v48
	s_add_u32 s12, s12, s100
	s_addc_u32 s13, s13, s101
	global_load_dwordx4 v[64:67], v207, s[12:13]
	s_waitcnt vmcnt(15)
	v_cvt_scalef32_pk_bf16_fp4 v48, v68, 1.0
	v_cvt_scalef32_pk_bf16_fp4 v50, v68, 1.0 op_sel:[1,0,0]
	v_cvt_scalef32_pk_bf16_fp4 v52, v68, 1.0 op_sel:[0,1,0]
	v_cvt_scalef32_pk_bf16_fp4 v54, v68, 1.0 op_sel:[1,1,0]
	v_dot2_f32_bf16 v56, v48, v6, 0
	v_dot2_f32_bf16 v48, v50, v4, 0
	v_dot2_f32_bf16 v56, v52, v10, v56
	s_add_i32 s12, s28, -14
	v_dot2_f32_bf16 v48, v54, v8, v48
	v_cvt_scalef32_pk_bf16_fp4 v50, v69, 1.0
	v_cvt_scalef32_pk_bf16_fp4 v52, v69, 1.0 op_sel:[1,0,0]
	v_cvt_scalef32_pk_bf16_fp4 v54, v69, 1.0 op_sel:[0,1,0]
	v_cvt_scalef32_pk_bf16_fp4 v58, v69, 1.0 op_sel:[1,1,0]
	v_readlane_b32 s12, v46, s12
	v_dot2_f32_bf16 v56, v50, v14, v56
	v_dot2_f32_bf16 v48, v52, v12, v48
	s_lshr_b32 s12, s12, 7
	v_dot2_f32_bf16 v56, v54, v18, v56
	v_dot2_f32_bf16 v48, v58, v16, v48
	v_cvt_scalef32_pk_bf16_fp4 v50, v70, 1.0
	v_cvt_scalef32_pk_bf16_fp4 v52, v70, 1.0 op_sel:[1,0,0]
	v_cvt_scalef32_pk_bf16_fp4 v54, v70, 1.0 op_sel:[0,1,0]
	v_cvt_scalef32_pk_bf16_fp4 v58, v70, 1.0 op_sel:[1,1,0]
	s_mov_b32 s13, s86
	v_dot2_f32_bf16 v56, v50, v22, v56
	v_dot2_f32_bf16 v48, v52, v20, v48
	s_lshl_b64 s[12:13], s[12:13], 10
	v_dot2_f32_bf16 v56, v54, v26, v56
	v_dot2_f32_bf16 v48, v58, v24, v48
	v_cvt_scalef32_pk_bf16_fp4 v50, v71, 1.0
	v_cvt_scalef32_pk_bf16_fp4 v52, v71, 1.0 op_sel:[1,0,0]
	v_cvt_scalef32_pk_bf16_fp4 v54, v71, 1.0 op_sel:[0,1,0]
	v_cvt_scalef32_pk_bf16_fp4 v58, v71, 1.0 op_sel:[1,1,0]
	v_mov_b32_e32 v100, 0
	v_dot2_f32_bf16 v56, v50, v30, v56
	v_dot2_f32_bf16 v48, v52, v28, v48
	v_mov_b32_e32 v42, 0
	v_dot2_f32_bf16 v56, v54, v36, v56
	v_dot2_f32_bf16 v48, v58, v34, v48
	s_nop 2
	v_add_f32_e32 v48, v56, v48
	s_add_u32 s12, s12, s100
	s_addc_u32 s13, s13, s101
	global_load_dwordx4 v[68:71], v207, s[12:13]
	s_waitcnt vmcnt(15)
	v_cvt_scalef32_pk_bf16_fp4 v50, v72, 1.0
	v_cvt_scalef32_pk_bf16_fp4 v52, v72, 1.0 op_sel:[1,0,0]
	v_cvt_scalef32_pk_bf16_fp4 v54, v72, 1.0 op_sel:[0,1,0]
	v_cvt_scalef32_pk_bf16_fp4 v56, v72, 1.0 op_sel:[1,1,0]
	s_add_i32 s12, s28, -13
	v_dot2_f32_bf16 v49, v50, v6, 0
	v_dot2_f32_bf16 v49, v52, v4, v49
	v_dot2_f32_bf16 v49, v54, v10, v49
	v_readlane_b32 s12, v46, s12
	v_dot2_f32_bf16 v49, v56, v8, v49
	v_cvt_scalef32_pk_bf16_fp4 v52, v73, 1.0
	v_cvt_scalef32_pk_bf16_fp4 v54, v73, 1.0 op_sel:[1,0,0]
	v_cvt_scalef32_pk_bf16_fp4 v56, v73, 1.0 op_sel:[0,1,0]
	v_cvt_scalef32_pk_bf16_fp4 v60, v73, 1.0 op_sel:[1,1,0]
	s_lshr_b32 s12, s12, 7
	v_dot2_f32_bf16 v49, v52, v14, v49
	v_dot2_f32_bf16 v49, v54, v12, v49
	s_mov_b32 s13, s86
	v_dot2_f32_bf16 v49, v56, v18, v49
	v_dot2_f32_bf16 v49, v60, v16, v49
	v_cvt_scalef32_pk_bf16_fp4 v52, v74, 1.0
	v_cvt_scalef32_pk_bf16_fp4 v54, v74, 1.0 op_sel:[1,0,0]
	v_cvt_scalef32_pk_bf16_fp4 v56, v74, 1.0 op_sel:[0,1,0]
	v_cvt_scalef32_pk_bf16_fp4 v60, v74, 1.0 op_sel:[1,1,0]
	s_lshl_b64 s[12:13], s[12:13], 10
	v_dot2_f32_bf16 v49, v52, v22, v49
	v_dot2_f32_bf16 v49, v54, v20, v49
	s_nop 0
	v_dot2_f32_bf16 v49, v56, v26, v49
	v_dot2_f32_bf16 v49, v60, v24, v49
	v_cvt_scalef32_pk_bf16_fp4 v52, v75, 1.0
	v_cvt_scalef32_pk_bf16_fp4 v54, v75, 1.0 op_sel:[1,0,0]
	v_cvt_scalef32_pk_bf16_fp4 v56, v75, 1.0 op_sel:[0,1,0]
	v_cvt_scalef32_pk_bf16_fp4 v60, v75, 1.0 op_sel:[1,1,0]
	s_nop 0
	v_dot2_f32_bf16 v49, v52, v30, v49
	v_dot2_f32_bf16 v49, v54, v28, v49
	s_nop 0
	v_dot2_f32_bf16 v49, v56, v36, v49
	v_dot2_f32_bf16 v49, v60, v34, v49
	s_nop 0
	s_add_u32 s12, s12, s100
	s_addc_u32 s13, s13, s101
	global_load_dwordx4 v[72:75], v207, s[12:13]
	s_waitcnt vmcnt(15)
; #define P4_FOR16(M) M(0) M(1) M(2) M(3) M(4) M(5) M(6) M(7) M(8) M(9) M(10) M(11) M(12) M(13) M(14) M(15)
; #define P4_U(i) { P4_DOT(b##i, part[i]); const int nk_ = __builtin_amdgcn_readlane(ksel, nb + i); P4_LOAD(b##i, Ug, nk_); }
; #define P4_U(i) { P4_DOT(b##i, part[i]); const int nk_ = __builtin_amdgcn_readlane(kn, i); P4_LOAD(b##i, nbase, nk_); }
; __device__ __forceinline__ void peer_gather_f4p(const float* X, const int* __restrict__ IDX, const float* __restrict__ G, ...
;     ...
; #pragma unroll 1
;         for (int bt = 0; bt < 7; ++bt) {
;             const int ksel = (bt + 1 < 4) ? k0 : k1;
;             const int nb = (16 * (bt + 1)) & 63;
;     ...
;             P4_FOR16(P4_U)
;     ...
;             P4_RED(bt);
;         }
	v_cvt_scalef32_pk_bf16_fp4 v50, v76, 1.0
	v_cvt_scalef32_pk_bf16_fp4 v52, v76, 1.0 op_sel:[1,0,0]
	v_cvt_scalef32_pk_bf16_fp4 v54, v76, 1.0 op_sel:[0,1,0]
	v_cvt_scalef32_pk_bf16_fp4 v56, v76, 1.0 op_sel:[1,1,0]
	v_dot2_f32_bf16 v58, v50, v6, 0
	v_dot2_f32_bf16 v50, v52, v4, 0
	v_dot2_f32_bf16 v58, v54, v10, v58
	s_add_i32 s12, s28, -12
	v_dot2_f32_bf16 v50, v56, v8, v50
	v_cvt_scalef32_pk_bf16_fp4 v52, v77, 1.0
	v_cvt_scalef32_pk_bf16_fp4 v54, v77, 1.0 op_sel:[1,0,0]
	v_cvt_scalef32_pk_bf16_fp4 v56, v77, 1.0 op_sel:[0,1,0]
	v_cvt_scalef32_pk_bf16_fp4 v60, v77, 1.0 op_sel:[1,1,0]
	v_readlane_b32 s12, v46, s12
	v_dot2_f32_bf16 v58, v52, v14, v58
	v_dot2_f32_bf16 v50, v54, v12, v50
	s_lshr_b32 s12, s12, 7
	v_dot2_f32_bf16 v58, v56, v18, v58
	v_dot2_f32_bf16 v50, v60, v16, v50
	v_cvt_scalef32_pk_bf16_fp4 v52, v78, 1.0
	v_cvt_scalef32_pk_bf16_fp4 v54, v78, 1.0 op_sel:[1,0,0]
	v_cvt_scalef32_pk_bf16_fp4 v56, v78, 1.0 op_sel:[0,1,0]
	v_cvt_scalef32_pk_bf16_fp4 v60, v78, 1.0 op_sel:[1,1,0]
	s_mov_b32 s13, s86
	v_dot2_f32_bf16 v58, v52, v22, v58
	v_dot2_f32_bf16 v50, v54, v20, v50
	s_lshl_b64 s[12:13], s[12:13], 10
	v_dot2_f32_bf16 v58, v56, v26, v58
	v_dot2_f32_bf16 v50, v60, v24, v50
	v_cvt_scalef32_pk_bf16_fp4 v52, v79, 1.0
	v_cvt_scalef32_pk_bf16_fp4 v54, v79, 1.0 op_sel:[1,0,0]
	v_cvt_scalef32_pk_bf16_fp4 v56, v79, 1.0 op_sel:[0,1,0]
	v_cvt_scalef32_pk_bf16_fp4 v60, v79, 1.0 op_sel:[1,1,0]
	s_nop 0
	v_dot2_f32_bf16 v58, v52, v30, v58
	v_dot2_f32_bf16 v50, v54, v28, v50
	s_nop 0
	v_dot2_f32_bf16 v58, v56, v36, v58
	v_dot2_f32_bf16 v50, v60, v34, v50
	s_nop 2
	v_add_f32_e32 v50, v58, v50
	s_add_u32 s12, s12, s100
	s_addc_u32 s13, s13, s101
	global_load_dwordx4 v[76:79], v207, s[12:13]
	s_waitcnt vmcnt(15)
	v_cvt_scalef32_pk_bf16_fp4 v52, v80, 1.0
	v_cvt_scalef32_pk_bf16_fp4 v54, v80, 1.0 op_sel:[1,0,0]
	v_cvt_scalef32_pk_bf16_fp4 v56, v80, 1.0 op_sel:[0,1,0]
	v_cvt_scalef32_pk_bf16_fp4 v58, v80, 1.0 op_sel:[1,1,0]
	s_add_i32 s12, s28, -11
	v_dot2_f32_bf16 v51, v52, v6, 0
	v_dot2_f32_bf16 v51, v54, v4, v51
	v_dot2_f32_bf16 v51, v56, v10, v51
	v_readlane_b32 s12, v46, s12
	v_dot2_f32_bf16 v51, v58, v8, v51
	v_cvt_scalef32_pk_bf16_fp4 v54, v81, 1.0
	v_cvt_scalef32_pk_bf16_fp4 v56, v81, 1.0 op_sel:[1,0,0]
	v_cvt_scalef32_pk_bf16_fp4 v58, v81, 1.0 op_sel:[0,1,0]
	v_cvt_scalef32_pk_bf16_fp4 v62, v81, 1.0 op_sel:[1,1,0]
	s_lshr_b32 s12, s12, 7
	v_dot2_f32_bf16 v51, v54, v14, v51
	v_dot2_f32_bf16 v51, v56, v12, v51
	s_mov_b32 s13, s86
	v_dot2_f32_bf16 v51, v58, v18, v51
	v_dot2_f32_bf16 v51, v62, v16, v51
	v_cvt_scalef32_pk_bf16_fp4 v54, v82, 1.0
	v_cvt_scalef32_pk_bf16_fp4 v56, v82, 1.0 op_sel:[1,0,0]
	v_cvt_scalef32_pk_bf16_fp4 v58, v82, 1.0 op_sel:[0,1,0]
	v_cvt_scalef32_pk_bf16_fp4 v62, v82, 1.0 op_sel:[1,1,0]
	s_lshl_b64 s[12:13], s[12:13], 10
	v_dot2_f32_bf16 v51, v54, v22, v51
	v_dot2_f32_bf16 v51, v56, v20, v51
	s_nop 0
	v_dot2_f32_bf16 v51, v58, v26, v51
	v_dot2_f32_bf16 v51, v62, v24, v51
	v_cvt_scalef32_pk_bf16_fp4 v54, v83, 1.0
	v_cvt_scalef32_pk_bf16_fp4 v56, v83, 1.0 op_sel:[1,0,0]
	v_cvt_scalef32_pk_bf16_fp4 v58, v83, 1.0 op_sel:[0,1,0]
	v_cvt_scalef32_pk_bf16_fp4 v62, v83, 1.0 op_sel:[1,1,0]
	s_nop 0
	v_dot2_f32_bf16 v51, v54, v30, v51
	v_dot2_f32_bf16 v51, v56, v28, v51
	s_nop 0
	v_dot2_f32_bf16 v51, v58, v36, v51
	v_dot2_f32_bf16 v51, v62, v34, v51
	s_nop 0
	s_add_u32 s12, s12, s100
	s_addc_u32 s13, s13, s101
	global_load_dwordx4 v[80:83], v207, s[12:13]
	s_waitcnt vmcnt(15)
	v_cvt_scalef32_pk_bf16_fp4 v52, v84, 1.0
	v_cvt_scalef32_pk_bf16_fp4 v54, v84, 1.0 op_sel:[1,0,0]
	v_cvt_scalef32_pk_bf16_fp4 v56, v84, 1.0 op_sel:[0,1,0]
	v_cvt_scalef32_pk_bf16_fp4 v58, v84, 1.0 op_sel:[1,1,0]
	v_dot2_f32_bf16 v60, v52, v6, 0
	v_dot2_f32_bf16 v52, v54, v4, 0
	v_dot2_f32_bf16 v60, v56, v10, v60
	s_add_i32 s12, s28, -10
	v_dot2_f32_bf16 v52, v58, v8, v52
	v_cvt_scalef32_pk_bf16_fp4 v54, v85, 1.0
	v_cvt_scalef32_pk_bf16_fp4 v56, v85, 1.0 op_sel:[1,0,0]
	v_cvt_scalef32_pk_bf16_fp4 v58, v85, 1.0 op_sel:[0,1,0]
	v_cvt_scalef32_pk_bf16_fp4 v62, v85, 1.0 op_sel:[1,1,0]
	v_readlane_b32 s12, v46, s12
	v_dot2_f32_bf16 v60, v54, v14, v60
	v_dot2_f32_bf16 v52, v56, v12, v52
	s_lshr_b32 s12, s12, 7
	v_dot2_f32_bf16 v60, v58, v18, v60
	v_dot2_f32_bf16 v52, v62, v16, v52
	v_cvt_scalef32_pk_bf16_fp4 v54, v86, 1.0
	v_cvt_scalef32_pk_bf16_fp4 v56, v86, 1.0 op_sel:[1,0,0]
	v_cvt_scalef32_pk_bf16_fp4 v58, v86, 1.0 op_sel:[0,1,0]
	v_cvt_scalef32_pk_bf16_fp4 v62, v86, 1.0 op_sel:[1,1,0]
	s_mov_b32 s13, s86
	v_dot2_f32_bf16 v60, v54, v22, v60
	v_dot2_f32_bf16 v52, v56, v20, v52
	s_lshl_b64 s[12:13], s[12:13], 10
	v_dot2_f32_bf16 v60, v58, v26, v60
	v_dot2_f32_bf16 v52, v62, v24, v52
	v_cvt_scalef32_pk_bf16_fp4 v54, v87, 1.0
	v_cvt_scalef32_pk_bf16_fp4 v56, v87, 1.0 op_sel:[1,0,0]
	v_cvt_scalef32_pk_bf16_fp4 v58, v87, 1.0 op_sel:[0,1,0]
	v_cvt_scalef32_pk_bf16_fp4 v62, v87, 1.0 op_sel:[1,1,0]
	s_nop 0
	v_dot2_f32_bf16 v60, v54, v30, v60
	v_dot2_f32_bf16 v52, v56, v28, v52
	s_nop 0
	v_dot2_f32_bf16 v60, v58, v36, v60
	v_dot2_f32_bf16 v52, v62, v34, v52
	s_nop 2
	v_add_f32_e32 v52, v60, v52
	s_add_u32 s12, s12, s100
	s_addc_u32 s13, s13, s101
	global_load_dwordx4 v[84:87], v207, s[12:13]
	s_waitcnt vmcnt(15)
; #define P4_FOR16(M) M(0) M(1) M(2) M(3) M(4) M(5) M(6) M(7) M(8) M(9) M(10) M(11) M(12) M(13) M(14) M(15)
; #define P4_U(i) { P4_DOT(b##i, part[i]); const int nk_ = __builtin_amdgcn_readlane(ksel, nb + i); P4_LOAD(b##i, Ug, nk_); }
; #define P4_U(i) { P4_DOT(b##i, part[i]); const int nk_ = __builtin_amdgcn_readlane(kn, i); P4_LOAD(b##i, nbase, nk_); }
; __device__ __forceinline__ void peer_gather_f4p(const float* X, const int* __restrict__ IDX, const float* __restrict__ G, ...
;     ...
; #pragma unroll 1
;         for (int bt = 0; bt < 7; ++bt) {
;             const int ksel = (bt + 1 < 4) ? k0 : k1;
;             const int nb = (16 * (bt + 1)) & 63;
;     ...
;             P4_FOR16(P4_U)
;     ...
;             P4_RED(bt);
;         }
	v_cvt_scalef32_pk_bf16_fp4 v54, v88, 1.0
	v_cvt_scalef32_pk_bf16_fp4 v56, v88, 1.0 op_sel:[1,0,0]
	v_cvt_scalef32_pk_bf16_fp4 v58, v88, 1.0 op_sel:[0,1,0]
	v_cvt_scalef32_pk_bf16_fp4 v60, v88, 1.0 op_sel:[1,1,0]
	s_add_i32 s12, s28, -9
	v_dot2_f32_bf16 v53, v54, v6, 0
	v_dot2_f32_bf16 v53, v56, v4, v53
	v_dot2_f32_bf16 v53, v58, v10, v53
	v_readlane_b32 s12, v46, s12
	v_dot2_f32_bf16 v53, v60, v8, v53
	v_cvt_scalef32_pk_bf16_fp4 v56, v89, 1.0
	v_cvt_scalef32_pk_bf16_fp4 v58, v89, 1.0 op_sel:[1,0,0]
	v_cvt_scalef32_pk_bf16_fp4 v60, v89, 1.0 op_sel:[0,1,0]
	v_cvt_scalef32_pk_bf16_fp4 v88, v89, 1.0 op_sel:[1,1,0]
	s_lshr_b32 s12, s12, 7
	v_dot2_f32_bf16 v53, v56, v14, v53
	v_dot2_f32_bf16 v53, v58, v12, v53
	s_mov_b32 s13, s86
	v_dot2_f32_bf16 v53, v60, v18, v53
	v_dot2_f32_bf16 v53, v88, v16, v53
	v_cvt_scalef32_pk_bf16_fp4 v56, v90, 1.0
	v_cvt_scalef32_pk_bf16_fp4 v58, v90, 1.0 op_sel:[1,0,0]
	v_cvt_scalef32_pk_bf16_fp4 v60, v90, 1.0 op_sel:[0,1,0]
	v_cvt_scalef32_pk_bf16_fp4 v88, v90, 1.0 op_sel:[1,1,0]
	s_lshl_b64 s[12:13], s[12:13], 10
	v_dot2_f32_bf16 v53, v56, v22, v53
	v_dot2_f32_bf16 v53, v58, v20, v53
	s_nop 0
	v_dot2_f32_bf16 v53, v60, v26, v53
	v_dot2_f32_bf16 v53, v88, v24, v53
	v_cvt_scalef32_pk_bf16_fp4 v56, v91, 1.0
	v_cvt_scalef32_pk_bf16_fp4 v58, v91, 1.0 op_sel:[1,0,0]
	v_cvt_scalef32_pk_bf16_fp4 v60, v91, 1.0 op_sel:[0,1,0]
	v_cvt_scalef32_pk_bf16_fp4 v88, v91, 1.0 op_sel:[1,1,0]
	s_nop 0
	v_dot2_f32_bf16 v53, v56, v30, v53
	v_dot2_f32_bf16 v53, v58, v28, v53
	s_nop 0
	v_dot2_f32_bf16 v53, v60, v36, v53
	v_dot2_f32_bf16 v53, v88, v34, v53
	s_nop 0
	s_add_u32 s12, s12, s100
	s_addc_u32 s13, s13, s101
	global_load_dwordx4 v[88:91], v207, s[12:13]
	s_waitcnt vmcnt(15)
	v_cvt_scalef32_pk_bf16_fp4 v54, v92, 1.0
	v_cvt_scalef32_pk_bf16_fp4 v56, v92, 1.0 op_sel:[1,0,0]
	v_cvt_scalef32_pk_bf16_fp4 v58, v92, 1.0 op_sel:[0,1,0]
	v_cvt_scalef32_pk_bf16_fp4 v60, v92, 1.0 op_sel:[1,1,0]
	v_dot2_f32_bf16 v62, v54, v6, 0
	v_dot2_f32_bf16 v54, v56, v4, 0
	v_dot2_f32_bf16 v62, v58, v10, v62
	s_add_i32 s12, s28, -8
	v_dot2_f32_bf16 v54, v60, v8, v54
	v_cvt_scalef32_pk_bf16_fp4 v56, v93, 1.0
	v_cvt_scalef32_pk_bf16_fp4 v58, v93, 1.0 op_sel:[1,0,0]
	v_cvt_scalef32_pk_bf16_fp4 v60, v93, 1.0 op_sel:[0,1,0]
	v_cvt_scalef32_pk_bf16_fp4 v92, v93, 1.0 op_sel:[1,1,0]
	v_readlane_b32 s12, v46, s12
	v_dot2_f32_bf16 v62, v56, v14, v62
	v_dot2_f32_bf16 v54, v58, v12, v54
	s_lshr_b32 s12, s12, 7
	v_dot2_f32_bf16 v62, v60, v18, v62
	v_dot2_f32_bf16 v54, v92, v16, v54
	v_cvt_scalef32_pk_bf16_fp4 v56, v94, 1.0
	v_cvt_scalef32_pk_bf16_fp4 v58, v94, 1.0 op_sel:[1,0,0]
	v_cvt_scalef32_pk_bf16_fp4 v60, v94, 1.0 op_sel:[0,1,0]
	v_cvt_scalef32_pk_bf16_fp4 v92, v94, 1.0 op_sel:[1,1,0]
	s_mov_b32 s13, s86
	v_dot2_f32_bf16 v62, v56, v22, v62
	v_dot2_f32_bf16 v54, v58, v20, v54
	s_lshl_b64 s[12:13], s[12:13], 10
	v_dot2_f32_bf16 v62, v60, v26, v62
	v_dot2_f32_bf16 v54, v92, v24, v54
	v_cvt_scalef32_pk_bf16_fp4 v56, v95, 1.0
	v_cvt_scalef32_pk_bf16_fp4 v58, v95, 1.0 op_sel:[1,0,0]
	v_cvt_scalef32_pk_bf16_fp4 v60, v95, 1.0 op_sel:[0,1,0]
	v_cvt_scalef32_pk_bf16_fp4 v92, v95, 1.0 op_sel:[1,1,0]
	s_nop 0
	v_dot2_f32_bf16 v62, v56, v30, v62
	v_dot2_f32_bf16 v54, v58, v28, v54
	s_nop 0
	v_dot2_f32_bf16 v62, v60, v36, v62
	v_dot2_f32_bf16 v54, v92, v34, v54
	s_nop 0
	s_nop 2
	v_add_f32_e32 v54, v62, v54
	s_add_u32 s12, s12, s100
	s_addc_u32 s13, s13, s101
	global_load_dwordx4 v[92:95], v207, s[12:13]
	s_waitcnt vmcnt(15)
	v_cvt_scalef32_pk_bf16_fp4 v56, v96, 1.0
	v_cvt_scalef32_pk_bf16_fp4 v58, v96, 1.0 op_sel:[1,0,0]
	v_cvt_scalef32_pk_bf16_fp4 v60, v96, 1.0 op_sel:[0,1,0]
	v_cvt_scalef32_pk_bf16_fp4 v62, v96, 1.0 op_sel:[1,1,0]
	s_add_i32 s12, s28, -7
	v_dot2c_f32_bf16_e32 v100, v56, v6
	v_dot2_f32_bf16 v56, v58, v4, 0
	v_dot2c_f32_bf16_e32 v100, v60, v10
	v_readlane_b32 s12, v46, s12
	v_dot2_f32_bf16 v56, v62, v8, v56
	v_cvt_scalef32_pk_bf16_fp4 v58, v97, 1.0
	v_cvt_scalef32_pk_bf16_fp4 v60, v97, 1.0 op_sel:[1,0,0]
	v_cvt_scalef32_pk_bf16_fp4 v62, v97, 1.0 op_sel:[0,1,0]
	v_cvt_scalef32_pk_bf16_fp4 v96, v97, 1.0 op_sel:[1,1,0]
	s_lshr_b32 s12, s12, 7
	v_dot2c_f32_bf16_e32 v100, v58, v14
	v_dot2_f32_bf16 v56, v60, v12, v56
	s_mov_b32 s13, s86
	v_dot2c_f32_bf16_e32 v100, v62, v18
	v_dot2_f32_bf16 v56, v96, v16, v56
	v_cvt_scalef32_pk_bf16_fp4 v58, v98, 1.0
	v_cvt_scalef32_pk_bf16_fp4 v60, v98, 1.0 op_sel:[1,0,0]
	v_cvt_scalef32_pk_bf16_fp4 v62, v98, 1.0 op_sel:[0,1,0]
	v_cvt_scalef32_pk_bf16_fp4 v96, v98, 1.0 op_sel:[1,1,0]
	s_lshl_b64 s[12:13], s[12:13], 10
	v_dot2c_f32_bf16_e32 v100, v58, v22
	v_dot2_f32_bf16 v56, v60, v20, v56
	s_nop 0
	v_dot2c_f32_bf16_e32 v100, v62, v26
	v_dot2_f32_bf16 v56, v96, v24, v56
	v_cvt_scalef32_pk_bf16_fp4 v58, v99, 1.0
	v_cvt_scalef32_pk_bf16_fp4 v60, v99, 1.0 op_sel:[1,0,0]
	v_cvt_scalef32_pk_bf16_fp4 v62, v99, 1.0 op_sel:[0,1,0]
	v_cvt_scalef32_pk_bf16_fp4 v96, v99, 1.0 op_sel:[1,1,0]
	s_nop 0
	v_dot2c_f32_bf16_e32 v100, v58, v30
	v_dot2_f32_bf16 v56, v60, v28, v56
	s_nop 0
	v_dot2c_f32_bf16_e32 v100, v62, v36
	v_dot2_f32_bf16 v56, v96, v34, v56
	s_nop 0
	s_nop 2
	v_add_f32_e32 v55, v100, v56
	s_add_u32 s12, s12, s100
	s_addc_u32 s13, s13, s101
	global_load_dwordx4 v[96:99], v207, s[12:13]
	s_waitcnt vmcnt(15)
; #define P4_FOR16(M) M(0) M(1) M(2) M(3) M(4) M(5) M(6) M(7) M(8) M(9) M(10) M(11) M(12) M(13) M(14) M(15)
; #define P4_U(i) { P4_DOT(b##i, part[i]); const int nk_ = __builtin_amdgcn_readlane(ksel, nb + i); P4_LOAD(b##i, Ug, nk_); }
; #define P4_U(i) { P4_DOT(b##i, part[i]); const int nk_ = __builtin_amdgcn_readlane(kn, i); P4_LOAD(b##i, nbase, nk_); }
; __device__ __forceinline__ void peer_gather_f4p(const float* X, const int* __restrict__ IDX, const float* __restrict__ G, ...
;     ...
; #pragma unroll 1
;         for (int bt = 0; bt < 7; ++bt) {
;             const int ksel = (bt + 1 < 4) ? k0 : k1;
;             const int nb = (16 * (bt + 1)) & 63;
;     ...
;             P4_FOR16(P4_U)
;     ...
;             P4_RED(bt);
;         }
	v_cvt_scalef32_pk_bf16_fp4 v56, v104, 1.0
	v_cvt_scalef32_pk_bf16_fp4 v58, v104, 1.0 op_sel:[1,0,0]
	v_cvt_scalef32_pk_bf16_fp4 v60, v104, 1.0 op_sel:[0,1,0]
	v_cvt_scalef32_pk_bf16_fp4 v62, v104, 1.0 op_sel:[1,1,0]
	v_dot2_f32_bf16 v100, v56, v6, 0
	v_dot2_f32_bf16 v56, v58, v4, 0
	v_dot2_f32_bf16 v100, v60, v10, v100
	s_add_i32 s12, s28, -6
	v_dot2_f32_bf16 v56, v62, v8, v56
	v_cvt_scalef32_pk_bf16_fp4 v58, v105, 1.0
	v_cvt_scalef32_pk_bf16_fp4 v60, v105, 1.0 op_sel:[1,0,0]
	v_cvt_scalef32_pk_bf16_fp4 v62, v105, 1.0 op_sel:[0,1,0]
	v_cvt_scalef32_pk_bf16_fp4 v102, v105, 1.0 op_sel:[1,1,0]
	v_readlane_b32 s12, v46, s12
	v_dot2_f32_bf16 v100, v58, v14, v100
	v_dot2_f32_bf16 v56, v60, v12, v56
	s_lshr_b32 s12, s12, 7
	v_dot2_f32_bf16 v100, v62, v18, v100
	v_dot2_f32_bf16 v56, v102, v16, v56
	v_cvt_scalef32_pk_bf16_fp4 v58, v106, 1.0
	v_cvt_scalef32_pk_bf16_fp4 v60, v106, 1.0 op_sel:[1,0,0]
	v_cvt_scalef32_pk_bf16_fp4 v62, v106, 1.0 op_sel:[0,1,0]
	v_cvt_scalef32_pk_bf16_fp4 v102, v106, 1.0 op_sel:[1,1,0]
	s_mov_b32 s13, s86
	v_dot2_f32_bf16 v100, v58, v22, v100
	v_dot2_f32_bf16 v56, v60, v20, v56
	s_lshl_b64 s[12:13], s[12:13], 10
	v_dot2_f32_bf16 v100, v62, v26, v100
	v_dot2_f32_bf16 v56, v102, v24, v56
	v_cvt_scalef32_pk_bf16_fp4 v58, v107, 1.0
	v_cvt_scalef32_pk_bf16_fp4 v60, v107, 1.0 op_sel:[1,0,0]
	v_cvt_scalef32_pk_bf16_fp4 v62, v107, 1.0 op_sel:[0,1,0]
	v_cvt_scalef32_pk_bf16_fp4 v102, v107, 1.0 op_sel:[1,1,0]
	s_nop 0
	v_dot2_f32_bf16 v100, v58, v30, v100
	v_dot2_f32_bf16 v56, v60, v28, v56
	s_nop 0
	v_dot2_f32_bf16 v100, v62, v36, v100
	v_dot2_f32_bf16 v56, v102, v34, v56
	s_nop 2
	v_add_f32_e32 v56, v100, v56
	s_add_u32 s12, s12, s100
	s_addc_u32 s13, s13, s101
	global_load_dwordx4 v[104:107], v207, s[12:13]
	s_waitcnt vmcnt(15)
	v_cvt_scalef32_pk_bf16_fp4 v58, v108, 1.0
	v_cvt_scalef32_pk_bf16_fp4 v60, v108, 1.0 op_sel:[1,0,0]
	v_cvt_scalef32_pk_bf16_fp4 v62, v108, 1.0 op_sel:[0,1,0]
	v_cvt_scalef32_pk_bf16_fp4 v100, v108, 1.0 op_sel:[1,1,0]
	s_add_i32 s12, s28, -5
	v_dot2_f32_bf16 v57, v58, v6, 0
	v_dot2_f32_bf16 v57, v60, v4, v57
	v_dot2_f32_bf16 v57, v62, v10, v57
	v_readlane_b32 s12, v46, s12
	v_dot2_f32_bf16 v57, v100, v8, v57
	v_cvt_scalef32_pk_bf16_fp4 v60, v109, 1.0
	v_cvt_scalef32_pk_bf16_fp4 v62, v109, 1.0 op_sel:[1,0,0]
	v_cvt_scalef32_pk_bf16_fp4 v100, v109, 1.0 op_sel:[0,1,0]
	v_cvt_scalef32_pk_bf16_fp4 v108, v109, 1.0 op_sel:[1,1,0]
	s_lshr_b32 s12, s12, 7
	v_dot2_f32_bf16 v57, v60, v14, v57
	v_dot2_f32_bf16 v57, v62, v12, v57
	s_mov_b32 s13, s86
	v_dot2_f32_bf16 v57, v100, v18, v57
	v_dot2_f32_bf16 v57, v108, v16, v57
	v_cvt_scalef32_pk_bf16_fp4 v60, v110, 1.0
	v_cvt_scalef32_pk_bf16_fp4 v62, v110, 1.0 op_sel:[1,0,0]
	v_cvt_scalef32_pk_bf16_fp4 v100, v110, 1.0 op_sel:[0,1,0]
	v_cvt_scalef32_pk_bf16_fp4 v108, v110, 1.0 op_sel:[1,1,0]
	s_lshl_b64 s[12:13], s[12:13], 10
	v_dot2_f32_bf16 v57, v60, v22, v57
	v_dot2_f32_bf16 v57, v62, v20, v57
	s_nop 0
	v_dot2_f32_bf16 v57, v100, v26, v57
	v_dot2_f32_bf16 v57, v108, v24, v57
	v_cvt_scalef32_pk_bf16_fp4 v60, v111, 1.0
	v_cvt_scalef32_pk_bf16_fp4 v62, v111, 1.0 op_sel:[1,0,0]
	v_cvt_scalef32_pk_bf16_fp4 v100, v111, 1.0 op_sel:[0,1,0]
	v_cvt_scalef32_pk_bf16_fp4 v108, v111, 1.0 op_sel:[1,1,0]
	s_nop 0
	v_dot2_f32_bf16 v57, v60, v30, v57
	v_dot2_f32_bf16 v57, v62, v28, v57
	s_nop 0
	v_dot2_f32_bf16 v57, v100, v36, v57
	v_dot2_f32_bf16 v57, v108, v34, v57
	s_nop 0
	s_add_u32 s12, s12, s100
	s_addc_u32 s13, s13, s101
	global_load_dwordx4 v[108:111], v207, s[12:13]
	s_waitcnt vmcnt(15)
	v_cvt_scalef32_pk_bf16_fp4 v58, v112, 1.0
	v_cvt_scalef32_pk_bf16_fp4 v60, v112, 1.0 op_sel:[1,0,0]
	v_cvt_scalef32_pk_bf16_fp4 v62, v112, 1.0 op_sel:[0,1,0]
	v_cvt_scalef32_pk_bf16_fp4 v100, v112, 1.0 op_sel:[1,1,0]
	v_dot2_f32_bf16 v132, v58, v6, 0
	v_dot2_f32_bf16 v132, v60, v4, v132
	v_dot2_f32_bf16 v132, v62, v10, v132
	s_add_i32 s12, s28, -4
	v_dot2_f32_bf16 v132, v100, v8, v132
	v_cvt_scalef32_pk_bf16_fp4 v60, v113, 1.0
	v_cvt_scalef32_pk_bf16_fp4 v62, v113, 1.0 op_sel:[1,0,0]
	v_cvt_scalef32_pk_bf16_fp4 v100, v113, 1.0 op_sel:[0,1,0]
	v_cvt_scalef32_pk_bf16_fp4 v112, v113, 1.0 op_sel:[1,1,0]
	v_readlane_b32 s12, v46, s12
	v_dot2_f32_bf16 v132, v60, v14, v132
	v_dot2_f32_bf16 v132, v62, v12, v132
	s_lshr_b32 s12, s12, 7
	v_dot2_f32_bf16 v132, v100, v18, v132
	v_dot2_f32_bf16 v132, v112, v16, v132
	v_cvt_scalef32_pk_bf16_fp4 v60, v114, 1.0
	v_cvt_scalef32_pk_bf16_fp4 v62, v114, 1.0 op_sel:[1,0,0]
	v_cvt_scalef32_pk_bf16_fp4 v100, v114, 1.0 op_sel:[0,1,0]
	v_cvt_scalef32_pk_bf16_fp4 v112, v114, 1.0 op_sel:[1,1,0]
	s_mov_b32 s13, s86
	v_dot2_f32_bf16 v132, v60, v22, v132
	v_dot2_f32_bf16 v132, v62, v20, v132
	s_lshl_b64 s[12:13], s[12:13], 10
	v_dot2_f32_bf16 v132, v100, v26, v132
	v_dot2_f32_bf16 v132, v112, v24, v132
	v_cvt_scalef32_pk_bf16_fp4 v60, v115, 1.0
	v_cvt_scalef32_pk_bf16_fp4 v62, v115, 1.0 op_sel:[1,0,0]
	v_cvt_scalef32_pk_bf16_fp4 v100, v115, 1.0 op_sel:[0,1,0]
	v_cvt_scalef32_pk_bf16_fp4 v112, v115, 1.0 op_sel:[1,1,0]
	s_nop 0
	v_dot2_f32_bf16 v132, v60, v30, v132
	v_dot2_f32_bf16 v132, v62, v28, v132
	s_nop 0
	v_dot2_f32_bf16 v132, v100, v36, v132
	v_dot2_f32_bf16 v132, v112, v34, v132
	s_nop 0
	s_add_u32 s12, s12, s100
	s_addc_u32 s13, s13, s101
	global_load_dwordx4 v[112:115], v207, s[12:13]
	s_waitcnt vmcnt(15)
; #define P4_FOR16(M) M(0) M(1) M(2) M(3) M(4) M(5) M(6) M(7) M(8) M(9) M(10) M(11) M(12) M(13) M(14) M(15)
; #define P4_U(i) { P4_DOT(b##i, part[i]); const int nk_ = __builtin_amdgcn_readlane(ksel, nb + i); P4_LOAD(b##i, Ug, nk_); }
; #define P4_U(i) { P4_DOT(b##i, part[i]); const int nk_ = __builtin_amdgcn_readlane(kn, i); P4_LOAD(b##i, nbase, nk_); }
; __device__ __forceinline__ void peer_gather_f4p(const float* X, const int* __restrict__ IDX, const float* __restrict__ G, ...
;     ...
; #pragma unroll 1
;         for (int bt = 0; bt < 7; ++bt) {
;             const int ksel = (bt + 1 < 4) ? k0 : k1;
;             const int nb = (16 * (bt + 1)) & 63;
;     ...
;             P4_FOR16(P4_U)
;     ...
;             P4_RED(bt);
;         }
	v_cvt_scalef32_pk_bf16_fp4 v58, v116, 1.0
	v_cvt_scalef32_pk_bf16_fp4 v60, v116, 1.0 op_sel:[1,0,0]
	v_cvt_scalef32_pk_bf16_fp4 v62, v116, 1.0 op_sel:[0,1,0]
	v_cvt_scalef32_pk_bf16_fp4 v100, v116, 1.0 op_sel:[1,1,0]
	v_dot2_f32_bf16 v133, v58, v6, 0
	v_dot2_f32_bf16 v133, v60, v4, v133
	v_dot2_f32_bf16 v133, v62, v10, v133
	s_add_i32 s12, s28, -3
	v_dot2_f32_bf16 v133, v100, v8, v133
	v_cvt_scalef32_pk_bf16_fp4 v60, v117, 1.0
	v_cvt_scalef32_pk_bf16_fp4 v62, v117, 1.0 op_sel:[1,0,0]
	v_cvt_scalef32_pk_bf16_fp4 v100, v117, 1.0 op_sel:[0,1,0]
	v_cvt_scalef32_pk_bf16_fp4 v116, v117, 1.0 op_sel:[1,1,0]
	v_readlane_b32 s12, v46, s12
	v_dot2_f32_bf16 v133, v60, v14, v133
	v_dot2_f32_bf16 v133, v62, v12, v133
	s_lshr_b32 s12, s12, 7
	v_dot2_f32_bf16 v133, v100, v18, v133
	v_dot2_f32_bf16 v133, v116, v16, v133
	v_cvt_scalef32_pk_bf16_fp4 v60, v118, 1.0
	v_cvt_scalef32_pk_bf16_fp4 v62, v118, 1.0 op_sel:[1,0,0]
	v_cvt_scalef32_pk_bf16_fp4 v100, v118, 1.0 op_sel:[0,1,0]
	v_cvt_scalef32_pk_bf16_fp4 v116, v118, 1.0 op_sel:[1,1,0]
	s_mov_b32 s13, s86
	v_dot2_f32_bf16 v133, v60, v22, v133
	v_dot2_f32_bf16 v133, v62, v20, v133
	s_lshl_b64 s[12:13], s[12:13], 10
	v_dot2_f32_bf16 v133, v100, v26, v133
	v_dot2_f32_bf16 v133, v116, v24, v133
	v_cvt_scalef32_pk_bf16_fp4 v60, v119, 1.0
	v_cvt_scalef32_pk_bf16_fp4 v62, v119, 1.0 op_sel:[1,0,0]
	v_cvt_scalef32_pk_bf16_fp4 v100, v119, 1.0 op_sel:[0,1,0]
	v_cvt_scalef32_pk_bf16_fp4 v116, v119, 1.0 op_sel:[1,1,0]
	s_nop 0
	v_dot2_f32_bf16 v133, v60, v30, v133
	v_dot2_f32_bf16 v133, v62, v28, v133
	s_nop 0
	v_dot2_f32_bf16 v133, v100, v36, v133
	v_dot2_f32_bf16 v133, v116, v34, v133
	s_nop 0
	s_add_u32 s12, s12, s100
	s_addc_u32 s13, s13, s101
	global_load_dwordx4 v[116:119], v207, s[12:13]
	s_waitcnt vmcnt(15)
	v_cvt_scalef32_pk_bf16_fp4 v58, v120, 1.0
	v_cvt_scalef32_pk_bf16_fp4 v60, v120, 1.0 op_sel:[1,0,0]
	v_cvt_scalef32_pk_bf16_fp4 v62, v120, 1.0 op_sel:[0,1,0]
	v_cvt_scalef32_pk_bf16_fp4 v100, v120, 1.0 op_sel:[1,1,0]
	v_dot2_f32_bf16 v134, v58, v6, 0
	v_dot2_f32_bf16 v134, v60, v4, v134
	v_dot2_f32_bf16 v134, v62, v10, v134
	s_add_i32 s12, s28, -2
	v_dot2_f32_bf16 v134, v100, v8, v134
	v_cvt_scalef32_pk_bf16_fp4 v60, v121, 1.0
	v_cvt_scalef32_pk_bf16_fp4 v62, v121, 1.0 op_sel:[1,0,0]
	v_cvt_scalef32_pk_bf16_fp4 v100, v121, 1.0 op_sel:[0,1,0]
	v_cvt_scalef32_pk_bf16_fp4 v120, v121, 1.0 op_sel:[1,1,0]
	v_readlane_b32 s12, v46, s12
	v_dot2_f32_bf16 v134, v60, v14, v134
	v_dot2_f32_bf16 v134, v62, v12, v134
	s_lshr_b32 s12, s12, 7
	v_dot2_f32_bf16 v134, v100, v18, v134
	v_dot2_f32_bf16 v134, v120, v16, v134
	v_cvt_scalef32_pk_bf16_fp4 v60, v122, 1.0
	v_cvt_scalef32_pk_bf16_fp4 v62, v122, 1.0 op_sel:[1,0,0]
	v_cvt_scalef32_pk_bf16_fp4 v100, v122, 1.0 op_sel:[0,1,0]
	v_cvt_scalef32_pk_bf16_fp4 v120, v122, 1.0 op_sel:[1,1,0]
	s_mov_b32 s13, s86
	v_dot2_f32_bf16 v134, v60, v22, v134
	v_dot2_f32_bf16 v134, v62, v20, v134
	s_lshl_b64 s[12:13], s[12:13], 10
	v_dot2_f32_bf16 v134, v100, v26, v134
	v_dot2_f32_bf16 v134, v120, v24, v134
	v_cvt_scalef32_pk_bf16_fp4 v60, v123, 1.0
	v_cvt_scalef32_pk_bf16_fp4 v62, v123, 1.0 op_sel:[1,0,0]
	v_cvt_scalef32_pk_bf16_fp4 v100, v123, 1.0 op_sel:[0,1,0]
	v_cvt_scalef32_pk_bf16_fp4 v120, v123, 1.0 op_sel:[1,1,0]
	s_nop 0
	v_dot2_f32_bf16 v134, v60, v30, v134
	v_dot2_f32_bf16 v134, v62, v28, v134
	s_nop 0
	v_dot2_f32_bf16 v134, v100, v36, v134
	v_dot2_f32_bf16 v134, v120, v34, v134
	s_nop 0
	s_add_u32 s12, s12, s100
	s_addc_u32 s13, s13, s101
	global_load_dwordx4 v[120:123], v207, s[12:13]
	s_waitcnt vmcnt(15)
	v_cvt_scalef32_pk_bf16_fp4 v58, v124, 1.0
	v_cvt_scalef32_pk_bf16_fp4 v60, v124, 1.0 op_sel:[1,0,0]
	v_cvt_scalef32_pk_bf16_fp4 v62, v124, 1.0 op_sel:[0,1,0]
	v_cvt_scalef32_pk_bf16_fp4 v100, v124, 1.0 op_sel:[1,1,0]
	v_dot2_f32_bf16 v135, v58, v6, 0
	v_dot2_f32_bf16 v135, v60, v4, v135
	v_dot2_f32_bf16 v135, v62, v10, v135
	s_add_i32 s12, s28, -1
	v_dot2_f32_bf16 v135, v100, v8, v135
	v_cvt_scalef32_pk_bf16_fp4 v60, v125, 1.0
	v_cvt_scalef32_pk_bf16_fp4 v62, v125, 1.0 op_sel:[1,0,0]
	v_cvt_scalef32_pk_bf16_fp4 v100, v125, 1.0 op_sel:[0,1,0]
	v_cvt_scalef32_pk_bf16_fp4 v124, v125, 1.0 op_sel:[1,1,0]
	v_readlane_b32 s12, v46, s12
	v_dot2_f32_bf16 v135, v60, v14, v135
	v_dot2_f32_bf16 v135, v62, v12, v135
	s_lshr_b32 s12, s12, 7
	v_dot2_f32_bf16 v135, v100, v18, v135
	v_dot2_f32_bf16 v135, v124, v16, v135
	v_cvt_scalef32_pk_bf16_fp4 v60, v126, 1.0
	v_cvt_scalef32_pk_bf16_fp4 v62, v126, 1.0 op_sel:[1,0,0]
	v_cvt_scalef32_pk_bf16_fp4 v100, v126, 1.0 op_sel:[0,1,0]
	v_cvt_scalef32_pk_bf16_fp4 v124, v126, 1.0 op_sel:[1,1,0]
	s_mov_b32 s13, s86
	v_dot2_f32_bf16 v135, v60, v22, v135
	v_dot2_f32_bf16 v135, v62, v20, v135
	s_lshl_b64 s[12:13], s[12:13], 10
	v_dot2_f32_bf16 v135, v100, v26, v135
	v_dot2_f32_bf16 v135, v124, v24, v135
	v_cvt_scalef32_pk_bf16_fp4 v60, v127, 1.0
	v_cvt_scalef32_pk_bf16_fp4 v62, v127, 1.0 op_sel:[1,0,0]
	v_cvt_scalef32_pk_bf16_fp4 v100, v127, 1.0 op_sel:[0,1,0]
	v_cvt_scalef32_pk_bf16_fp4 v124, v127, 1.0 op_sel:[1,1,0]
	s_nop 0
	v_dot2_f32_bf16 v135, v60, v30, v135
	v_dot2_f32_bf16 v135, v62, v28, v135
	s_nop 0
	v_dot2_f32_bf16 v135, v100, v36, v135
	v_dot2_f32_bf16 v135, v124, v34, v135
	s_nop 0
	s_add_u32 s12, s12, s100
	s_addc_u32 s13, s13, s101
	global_load_dwordx4 v[124:127], v207, s[12:13]
	s_waitcnt vmcnt(15)
; __device__ __forceinline__ float gelu_tanh(float h) {
;     return 0.5f * h * (1.f + tanhf(0.7978845608028654f * (h + 0.044715f * h * h * h)));
; }
	v_cvt_scalef32_pk_bf16_fp4 v58, v128, 1.0
	v_cvt_scalef32_pk_bf16_fp4 v60, v128, 1.0 op_sel:[1,0,0]
	v_cvt_scalef32_pk_bf16_fp4 v62, v128, 1.0 op_sel:[0,1,0]
	v_cvt_scalef32_pk_bf16_fp4 v100, v128, 1.0 op_sel:[1,1,0]
	v_readlane_b32 s12, v46, s28
	v_dot2_f32_bf16 v102, v58, v6, 0
	v_dot2c_f32_bf16_e32 v42, v60, v4
	s_lshr_b32 s12, s12, 7
	v_dot2_f32_bf16 v102, v62, v10, v102
	v_dot2c_f32_bf16_e32 v42, v100, v8
	v_cvt_scalef32_pk_bf16_fp4 v58, v129, 1.0
	v_cvt_scalef32_pk_bf16_fp4 v60, v129, 1.0 op_sel:[1,0,0]
	v_cvt_scalef32_pk_bf16_fp4 v62, v129, 1.0 op_sel:[0,1,0]
	v_cvt_scalef32_pk_bf16_fp4 v100, v129, 1.0 op_sel:[1,1,0]
	s_mov_b32 s13, s86
	v_dot2_f32_bf16 v102, v58, v14, v102
	v_dot2c_f32_bf16_e32 v42, v60, v12
	s_lshl_b64 s[12:13], s[12:13], 10
	v_dot2_f32_bf16 v102, v62, v18, v102
	v_dot2c_f32_bf16_e32 v42, v100, v16
	v_cvt_scalef32_pk_bf16_fp4 v58, v130, 1.0
	v_cvt_scalef32_pk_bf16_fp4 v60, v130, 1.0 op_sel:[1,0,0]
	v_cvt_scalef32_pk_bf16_fp4 v62, v130, 1.0 op_sel:[0,1,0]
	v_cvt_scalef32_pk_bf16_fp4 v100, v130, 1.0 op_sel:[1,1,0]
	v_cndmask_b32_e64 v46, v48, v56, s[48:49]
	v_dot2_f32_bf16 v102, v58, v22, v102
	v_dot2c_f32_bf16_e32 v42, v60, v20
	ds_swizzle_b32 v46, v46 offset:swizzle(SWAP,8)
	v_dot2_f32_bf16 v102, v62, v26, v102
	v_dot2c_f32_bf16_e32 v42, v100, v24
	v_cvt_scalef32_pk_bf16_fp4 v58, v131, 1.0
	v_cvt_scalef32_pk_bf16_fp4 v60, v131, 1.0 op_sel:[1,0,0]
	v_cvt_scalef32_pk_bf16_fp4 v62, v131, 1.0 op_sel:[0,1,0]
	v_cvt_scalef32_pk_bf16_fp4 v100, v131, 1.0 op_sel:[1,1,0]
	s_nop 0
	v_dot2_f32_bf16 v102, v58, v30, v102
	v_dot2c_f32_bf16_e32 v42, v60, v28
	s_nop 0
	v_dot2_f32_bf16 v102, v62, v36, v102
	v_dot2c_f32_bf16_e32 v42, v100, v34
	s_nop 0
	s_nop 2
	v_add_f32_e32 v58, v102, v42
	v_lshl_add_u64 v[42:43], v[40:41], 0, s[12:13]
	global_load_dwordx4 v[128:131], v[42:43], off
	v_cndmask_b32_e64 v43, v47, v55, s[48:49]
	ds_swizzle_b32 v43, v43 offset:swizzle(SWAP,8)
	v_cndmask_b32_e64 v42, v55, v47, s[48:49]
	v_cndmask_b32_e64 v47, v49, v57, s[48:49]
	ds_swizzle_b32 v47, v47 offset:swizzle(SWAP,8)
	s_waitcnt lgkmcnt(1)
	v_add_f32_e32 v42, v42, v43
	v_cndmask_b32_e64 v43, v56, v48, s[48:49]
	v_cndmask_b32_e64 v48, v50, v132, s[48:49]
	v_add_f32_e32 v43, v43, v46
	v_cndmask_b32_e64 v46, v57, v49, s[48:49]
	ds_swizzle_b32 v48, v48 offset:swizzle(SWAP,8)
	v_cndmask_b32_e64 v49, v51, v133, s[48:49]
	ds_swizzle_b32 v49, v49 offset:swizzle(SWAP,8)
	s_waitcnt lgkmcnt(2)
	v_add_f32_e32 v46, v46, v47
	v_cndmask_b32_e64 v47, v132, v50, s[48:49]
	v_cndmask_b32_e64 v50, v52, v134, s[48:49]
	ds_swizzle_b32 v50, v50 offset:swizzle(SWAP,8)
	s_waitcnt lgkmcnt(2)
	v_add_f32_e32 v47, v47, v48
	v_cndmask_b32_e64 v48, v133, v51, s[48:49]
	v_cndmask_b32_e64 v51, v53, v135, s[48:49]
	s_waitcnt lgkmcnt(1)
	v_add_f32_e32 v48, v48, v49
	v_cndmask_b32_e64 v49, v134, v52, s[48:49]
	ds_swizzle_b32 v51, v51 offset:swizzle(SWAP,8)
	v_cndmask_b32_e64 v52, v54, v58, s[48:49]
	ds_swizzle_b32 v52, v52 offset:swizzle(SWAP,8)
	s_waitcnt lgkmcnt(2)
	v_add_f32_e32 v49, v49, v50
	v_cndmask_b32_e64 v50, v135, v53, s[48:49]
	s_waitcnt lgkmcnt(1)
	v_add_f32_e32 v50, v50, v51
	v_cndmask_b32_e64 v51, v58, v54, s[48:49]
	s_waitcnt lgkmcnt(0)
	v_add_f32_e32 v51, v51, v52
	v_cndmask_b32_e64 v53, v42, v48, s[46:47]
	v_cndmask_b32_e64 v42, v48, v42, s[46:47]
	v_cndmask_b32_e64 v48, v49, v43, s[46:47]
	v_cndmask_b32_e64 v43, v43, v49, s[46:47]
	v_cndmask_b32_e64 v49, v46, v50, s[46:47]
	v_cndmask_b32_e64 v52, v47, v51, s[46:47]
	ds_swizzle_b32 v53, v53 offset:swizzle(SWAP,4)
	ds_swizzle_b32 v43, v43 offset:swizzle(SWAP,4)
	ds_swizzle_b32 v49, v49 offset:swizzle(SWAP,4)
	ds_swizzle_b32 v52, v52 offset:swizzle(SWAP,4)
	v_cndmask_b32_e64 v46, v50, v46, s[46:47]
	v_cndmask_b32_e64 v47, v51, v47, s[46:47]
	s_waitcnt lgkmcnt(3)
	v_add_f32_e32 v42, v42, v53
	s_waitcnt lgkmcnt(2)
	v_add_f32_e32 v43, v48, v43
	s_waitcnt lgkmcnt(1)
	v_add_f32_e32 v46, v46, v49
	s_waitcnt lgkmcnt(0)
	v_add_f32_e32 v47, v47, v52
	v_cndmask_b32_e64 v48, v42, v46, s[44:45]
	v_cndmask_b32_e64 v49, v43, v47, s[44:45]
	ds_swizzle_b32 v48, v48 offset:swizzle(SWAP,2)
	ds_swizzle_b32 v49, v49 offset:swizzle(SWAP,2)
	v_cndmask_b32_e64 v42, v46, v42, s[44:45]
	v_cndmask_b32_e64 v43, v47, v43, s[44:45]
	s_waitcnt lgkmcnt(1)
	v_add_f32_e32 v42, v42, v48
	s_waitcnt lgkmcnt(0)
	v_add_f32_e32 v43, v43, v49
	v_cndmask_b32_e64 v46, v42, v43, s[42:43]
	ds_swizzle_b32 v46, v46 offset:swizzle(SWAP,1)
	v_cndmask_b32_e64 v42, v43, v42, s[42:43]
	s_waitcnt lgkmcnt(0)
	v_add_f32_e32 v42, v42, v46
	ds_swizzle_b32 v43, v42 offset:swizzle(SWAP,16)
	s_waitcnt lgkmcnt(0)
	v_add_f32_e32 v46, v42, v43
	ds_read2st64_b32 v[42:43], v45 offset1:8
	v_mov_b32_e32 v47, v46
	s_nop 1
	v_permlane32_swap_b32_e32 v46, v47
	v_add_f32_e32 v46, v46, v47
	s_waitcnt lgkmcnt(0)
	v_mul_f32_e32 v42, v42, v46
	v_mul_f32_e32 v46, 0x3d372713, v42
	v_mul_f32_e32 v46, v42, v46
	v_fma_f32 v46, v42, v46, v42
	v_mul_f32_e32 v46, 0x3f4c422a, v46
	v_cmp_nlt_f32_e64 s[12:13], |v46|, s25
	s_and_saveexec_b64 s[40:41], s[12:13]
	s_xor_b64 s[12:13], exec, s[40:41]
	s_cbranch_execz .LBB0_536
	v_add_f32_e64 v47, |v46|, |v46|
	v_mul_f32_e32 v48, 0x3fb8aa3b, v47
	v_rndne_f32_e32 v49, v48
	v_sub_f32_e32 v50, v48, v49
	v_fma_f32 v48, v47, s70, -v48
	v_fmac_f32_e32 v48, 0x32a5705f, v47
	v_add_f32_e32 v48, v50, v48
	v_cvt_i32_f32_e32 v49, v49
	v_exp_f32_e32 v48, v48
	v_cmp_ngt_f32_e64 s[50:51], s67, v47
	v_ldexp_f32 v48, v48, v49
	s_nop 0
	v_cndmask_b32_e64 v48, 0, v48, s[50:51]
	v_cmp_nlt_f32_e64 s[50:51], s68, v47
	s_nop 1
	v_cndmask_b32_e64 v47, v205, v48, s[50:51]
	v_add_f32_e32 v47, 1.0, v47
	v_rcp_f32_e32 v47, v47
	s_nop 0
	v_fma_f32 v47, v47, -2.0, 1.0
	s_andn2_saveexec_b64 s[12:13], s[12:13]
	s_cbranch_execnz .LBB0_537

; #define P4_FOR16(M) M(0) M(1) M(2) M(3) M(4) M(5) M(6) M(7) M(8) M(9) M(10) M(11) M(12) M(13) M(14) M(15)
; #define P4_U(i) { P4_DOT(b##i, part[i]); const int nk_ = __builtin_amdgcn_readlane(ksel, nb + i); P4_LOAD(b##i, Ug, nk_); }
; #define P4_U(i) { P4_DOT(b##i, part[i]); const int nk_ = __builtin_amdgcn_readlane(kn, i); P4_LOAD(b##i, nbase, nk_); }
; __device__ __forceinline__ void peer_gather_f4p(const float* X, const int* __restrict__ IDX, const float* __restrict__ G, ...
;     ...
;         {
;     ...
;             P4_FOR16(P4_U)
;     ...
;             P4_RED(7);
;         }
.LBB0_539:
	s_mov_b32 s87, s86
	s_waitcnt vmcnt(15)
	v_cvt_scalef32_pk_bf16_fp4 v42, v64, 1.0
	v_or_b32_e32 v40, s27, v44
	v_cvt_scalef32_pk_bf16_fp4 v44, v64, 1.0 op_sel:[1,0,0]
	v_cvt_scalef32_pk_bf16_fp4 v46, v64, 1.0 op_sel:[0,1,0]
	v_cvt_scalef32_pk_bf16_fp4 v48, v64, 1.0 op_sel:[1,1,0]
	v_dot2_f32_bf16 v41, v42, v6, 0
	v_dot2_f32_bf16 v41, v44, v4, v41
	v_dot2_f32_bf16 v41, v46, v10, v41
	s_cmp_eq_u32 s26, 3
	v_dot2_f32_bf16 v41, v48, v8, v41
	v_cvt_scalef32_pk_bf16_fp4 v44, v65, 1.0
	v_cvt_scalef32_pk_bf16_fp4 v46, v65, 1.0 op_sel:[1,0,0]
	v_cvt_scalef32_pk_bf16_fp4 v48, v65, 1.0 op_sel:[0,1,0]
	v_cvt_scalef32_pk_bf16_fp4 v52, v65, 1.0 op_sel:[1,1,0]
	v_readlane_b32 s26, v2, 0
	v_dot2_f32_bf16 v41, v44, v14, v41
	v_dot2_f32_bf16 v41, v46, v12, v41
	s_cselect_b32 s12, s53, s55
	v_dot2_f32_bf16 v41, v48, v18, v41
	v_dot2_f32_bf16 v41, v52, v16, v41
	v_cvt_scalef32_pk_bf16_fp4 v44, v66, 1.0
	v_cvt_scalef32_pk_bf16_fp4 v46, v66, 1.0 op_sel:[1,0,0]
	v_cvt_scalef32_pk_bf16_fp4 v48, v66, 1.0 op_sel:[0,1,0]
	v_cvt_scalef32_pk_bf16_fp4 v52, v66, 1.0 op_sel:[1,1,0]
	s_cselect_b32 s13, s52, s54
	v_dot2_f32_bf16 v41, v44, v22, v41
	v_dot2_f32_bf16 v41, v46, v20, v41
	s_lshr_b32 s26, s26, 7
	v_dot2_f32_bf16 v41, v48, v26, v41
	v_dot2_f32_bf16 v41, v52, v24, v41
	s_mov_b32 s27, s86
	v_cvt_scalef32_pk_bf16_fp4 v44, v67, 1.0
	v_cvt_scalef32_pk_bf16_fp4 v46, v67, 1.0 op_sel:[1,0,0]
	v_cvt_scalef32_pk_bf16_fp4 v48, v67, 1.0 op_sel:[0,1,0]
	v_cvt_scalef32_pk_bf16_fp4 v52, v67, 1.0 op_sel:[1,1,0]
	s_lshl_b64 s[26:27], s[26:27], 10
	v_dot2_f32_bf16 v41, v44, v30, v41
	v_dot2_f32_bf16 v41, v46, v28, v41
	s_add_u32 s26, s13, s26
	v_dot2_f32_bf16 v41, v48, v36, v41
	v_dot2_f32_bf16 v41, v52, v34, v41
	s_addc_u32 s27, s12, s27
	global_load_dwordx4 v[64:67], v32, s[26:27]
	s_waitcnt vmcnt(15)
	v_cvt_scalef32_pk_bf16_fp4 v42, v68, 1.0
	v_cvt_scalef32_pk_bf16_fp4 v44, v68, 1.0 op_sel:[1,0,0]
	v_cvt_scalef32_pk_bf16_fp4 v46, v68, 1.0 op_sel:[0,1,0]
	v_cvt_scalef32_pk_bf16_fp4 v48, v68, 1.0 op_sel:[1,1,0]
	v_dot2_f32_bf16 v50, v42, v6, 0
	v_dot2_f32_bf16 v42, v44, v4, 0
	v_dot2_f32_bf16 v50, v46, v10, v50
	v_readlane_b32 s26, v2, 1
	v_dot2_f32_bf16 v42, v48, v8, v42
	v_cvt_scalef32_pk_bf16_fp4 v44, v69, 1.0
	v_cvt_scalef32_pk_bf16_fp4 v46, v69, 1.0 op_sel:[1,0,0]
	v_cvt_scalef32_pk_bf16_fp4 v48, v69, 1.0 op_sel:[0,1,0]
	v_cvt_scalef32_pk_bf16_fp4 v52, v69, 1.0 op_sel:[1,1,0]
	s_lshr_b32 s26, s26, 7
	v_dot2_f32_bf16 v50, v44, v14, v50
	v_dot2_f32_bf16 v42, v46, v12, v42
	s_mov_b32 s27, s86
	v_dot2_f32_bf16 v50, v48, v18, v50
	v_dot2_f32_bf16 v42, v52, v16, v42
	v_cvt_scalef32_pk_bf16_fp4 v44, v70, 1.0
	v_cvt_scalef32_pk_bf16_fp4 v46, v70, 1.0 op_sel:[1,0,0]
	v_cvt_scalef32_pk_bf16_fp4 v48, v70, 1.0 op_sel:[0,1,0]
	v_cvt_scalef32_pk_bf16_fp4 v52, v70, 1.0 op_sel:[1,1,0]
	s_lshl_b64 s[26:27], s[26:27], 10
	v_dot2_f32_bf16 v50, v44, v22, v50
	v_dot2_f32_bf16 v42, v46, v20, v42
	s_add_u32 s26, s13, s26
	v_dot2_f32_bf16 v50, v48, v26, v50
	v_dot2_f32_bf16 v42, v52, v24, v42
	v_cvt_scalef32_pk_bf16_fp4 v44, v71, 1.0
	v_cvt_scalef32_pk_bf16_fp4 v46, v71, 1.0 op_sel:[1,0,0]
	v_cvt_scalef32_pk_bf16_fp4 v48, v71, 1.0 op_sel:[0,1,0]
	v_cvt_scalef32_pk_bf16_fp4 v52, v71, 1.0 op_sel:[1,1,0]
	s_addc_u32 s27, s12, s27
	v_dot2_f32_bf16 v50, v44, v30, v50
	v_dot2_f32_bf16 v42, v46, v28, v42
	v_mov_b32_e32 v38, 0
	v_dot2_f32_bf16 v50, v48, v36, v50
	v_dot2_f32_bf16 v42, v52, v34, v42
	s_nop 2
	v_add_f32_e32 v42, v50, v42
	global_load_dwordx4 v[68:71], v32, s[26:27]
	s_waitcnt vmcnt(15)
	v_cvt_scalef32_pk_bf16_fp4 v44, v72, 1.0
	v_cvt_scalef32_pk_bf16_fp4 v46, v72, 1.0 op_sel:[1,0,0]
	v_cvt_scalef32_pk_bf16_fp4 v48, v72, 1.0 op_sel:[0,1,0]
	v_cvt_scalef32_pk_bf16_fp4 v50, v72, 1.0 op_sel:[1,1,0]
	v_readlane_b32 s26, v2, 2
	v_dot2_f32_bf16 v43, v44, v6, 0
	v_dot2_f32_bf16 v43, v46, v4, v43
	v_dot2_f32_bf16 v43, v48, v10, v43
	s_lshr_b32 s26, s26, 7
	v_dot2_f32_bf16 v43, v50, v8, v43
	v_cvt_scalef32_pk_bf16_fp4 v46, v73, 1.0
	v_cvt_scalef32_pk_bf16_fp4 v48, v73, 1.0 op_sel:[1,0,0]
	v_cvt_scalef32_pk_bf16_fp4 v50, v73, 1.0 op_sel:[0,1,0]
	v_cvt_scalef32_pk_bf16_fp4 v54, v73, 1.0 op_sel:[1,1,0]
	s_mov_b32 s27, s86
	v_dot2_f32_bf16 v43, v46, v14, v43
	v_dot2_f32_bf16 v43, v48, v12, v43
	s_lshl_b64 s[26:27], s[26:27], 10
	v_dot2_f32_bf16 v43, v50, v18, v43
	v_dot2_f32_bf16 v43, v54, v16, v43
	v_cvt_scalef32_pk_bf16_fp4 v46, v74, 1.0
	v_cvt_scalef32_pk_bf16_fp4 v48, v74, 1.0 op_sel:[1,0,0]
	v_cvt_scalef32_pk_bf16_fp4 v50, v74, 1.0 op_sel:[0,1,0]
	v_cvt_scalef32_pk_bf16_fp4 v54, v74, 1.0 op_sel:[1,1,0]
	s_add_u32 s26, s13, s26
	v_dot2_f32_bf16 v43, v46, v22, v43
	v_dot2_f32_bf16 v43, v48, v20, v43
	s_addc_u32 s27, s12, s27
	v_dot2_f32_bf16 v43, v50, v26, v43
	v_dot2_f32_bf16 v43, v54, v24, v43
	v_cvt_scalef32_pk_bf16_fp4 v46, v75, 1.0
	v_cvt_scalef32_pk_bf16_fp4 v48, v75, 1.0 op_sel:[1,0,0]
	v_cvt_scalef32_pk_bf16_fp4 v50, v75, 1.0 op_sel:[0,1,0]
	v_cvt_scalef32_pk_bf16_fp4 v54, v75, 1.0 op_sel:[1,1,0]
	s_nop 0
	v_dot2_f32_bf16 v43, v46, v30, v43
	v_dot2_f32_bf16 v43, v48, v28, v43
	s_nop 0
	v_dot2_f32_bf16 v43, v50, v36, v43
	v_dot2_f32_bf16 v43, v54, v34, v43
	s_nop 0
	global_load_dwordx4 v[72:75], v32, s[26:27]
	s_waitcnt vmcnt(15)
; #define P4_FOR16(M) M(0) M(1) M(2) M(3) M(4) M(5) M(6) M(7) M(8) M(9) M(10) M(11) M(12) M(13) M(14) M(15)
; #define P4_U(i) { P4_DOT(b##i, part[i]); const int nk_ = __builtin_amdgcn_readlane(ksel, nb + i); P4_LOAD(b##i, Ug, nk_); }
; #define P4_U(i) { P4_DOT(b##i, part[i]); const int nk_ = __builtin_amdgcn_readlane(kn, i); P4_LOAD(b##i, nbase, nk_); }
; __device__ __forceinline__ void peer_gather_f4p(const float* X, const int* __restrict__ IDX, const float* __restrict__ G, ...
;     ...
;         {
;     ...
;             P4_FOR16(P4_U)
;     ...
;             P4_RED(7);
;         }
	v_cvt_scalef32_pk_bf16_fp4 v44, v76, 1.0
	v_cvt_scalef32_pk_bf16_fp4 v46, v76, 1.0 op_sel:[1,0,0]
	v_cvt_scalef32_pk_bf16_fp4 v48, v76, 1.0 op_sel:[0,1,0]
	v_cvt_scalef32_pk_bf16_fp4 v50, v76, 1.0 op_sel:[1,1,0]
	v_dot2_f32_bf16 v52, v44, v6, 0
	v_dot2_f32_bf16 v44, v46, v4, 0
	v_dot2_f32_bf16 v52, v48, v10, v52
	v_readlane_b32 s26, v2, 3
	v_dot2_f32_bf16 v44, v50, v8, v44
	v_cvt_scalef32_pk_bf16_fp4 v46, v77, 1.0
	v_cvt_scalef32_pk_bf16_fp4 v48, v77, 1.0 op_sel:[1,0,0]
	v_cvt_scalef32_pk_bf16_fp4 v50, v77, 1.0 op_sel:[0,1,0]
	v_cvt_scalef32_pk_bf16_fp4 v54, v77, 1.0 op_sel:[1,1,0]
	s_lshr_b32 s26, s26, 7
	v_dot2_f32_bf16 v52, v46, v14, v52
	v_dot2_f32_bf16 v44, v48, v12, v44
	s_mov_b32 s27, s86
	v_dot2_f32_bf16 v52, v50, v18, v52
	v_dot2_f32_bf16 v44, v54, v16, v44
	v_cvt_scalef32_pk_bf16_fp4 v46, v78, 1.0
	v_cvt_scalef32_pk_bf16_fp4 v48, v78, 1.0 op_sel:[1,0,0]
	v_cvt_scalef32_pk_bf16_fp4 v50, v78, 1.0 op_sel:[0,1,0]
	v_cvt_scalef32_pk_bf16_fp4 v54, v78, 1.0 op_sel:[1,1,0]
	s_lshl_b64 s[26:27], s[26:27], 10
	v_dot2_f32_bf16 v52, v46, v22, v52
	v_dot2_f32_bf16 v44, v48, v20, v44
	s_add_u32 s26, s13, s26
	v_dot2_f32_bf16 v52, v50, v26, v52
	v_dot2_f32_bf16 v44, v54, v24, v44
	v_cvt_scalef32_pk_bf16_fp4 v46, v79, 1.0
	v_cvt_scalef32_pk_bf16_fp4 v48, v79, 1.0 op_sel:[1,0,0]
	v_cvt_scalef32_pk_bf16_fp4 v50, v79, 1.0 op_sel:[0,1,0]
	v_cvt_scalef32_pk_bf16_fp4 v54, v79, 1.0 op_sel:[1,1,0]
	s_addc_u32 s27, s12, s27
	v_dot2_f32_bf16 v52, v46, v30, v52
	v_dot2_f32_bf16 v44, v48, v28, v44
	s_nop 0
	v_dot2_f32_bf16 v52, v50, v36, v52
	v_dot2_f32_bf16 v44, v54, v34, v44
	s_nop 2
	v_add_f32_e32 v44, v52, v44
	global_load_dwordx4 v[76:79], v32, s[26:27]
	s_waitcnt vmcnt(15)
	v_cvt_scalef32_pk_bf16_fp4 v46, v80, 1.0
	v_cvt_scalef32_pk_bf16_fp4 v48, v80, 1.0 op_sel:[1,0,0]
	v_cvt_scalef32_pk_bf16_fp4 v50, v80, 1.0 op_sel:[0,1,0]
	v_cvt_scalef32_pk_bf16_fp4 v52, v80, 1.0 op_sel:[1,1,0]
	v_readlane_b32 s26, v2, 4
	v_dot2_f32_bf16 v45, v46, v6, 0
	v_dot2_f32_bf16 v45, v48, v4, v45
	v_dot2_f32_bf16 v45, v50, v10, v45
	s_lshr_b32 s26, s26, 7
	v_dot2_f32_bf16 v45, v52, v8, v45
	v_cvt_scalef32_pk_bf16_fp4 v48, v81, 1.0
	v_cvt_scalef32_pk_bf16_fp4 v50, v81, 1.0 op_sel:[1,0,0]
	v_cvt_scalef32_pk_bf16_fp4 v52, v81, 1.0 op_sel:[0,1,0]
	v_cvt_scalef32_pk_bf16_fp4 v56, v81, 1.0 op_sel:[1,1,0]
	s_mov_b32 s27, s86
	v_dot2_f32_bf16 v45, v48, v14, v45
	v_dot2_f32_bf16 v45, v50, v12, v45
	s_lshl_b64 s[26:27], s[26:27], 10
	v_dot2_f32_bf16 v45, v52, v18, v45
	v_dot2_f32_bf16 v45, v56, v16, v45
	v_cvt_scalef32_pk_bf16_fp4 v48, v82, 1.0
	v_cvt_scalef32_pk_bf16_fp4 v50, v82, 1.0 op_sel:[1,0,0]
	v_cvt_scalef32_pk_bf16_fp4 v52, v82, 1.0 op_sel:[0,1,0]
	v_cvt_scalef32_pk_bf16_fp4 v56, v82, 1.0 op_sel:[1,1,0]
	s_add_u32 s26, s13, s26
	v_dot2_f32_bf16 v45, v48, v22, v45
	v_dot2_f32_bf16 v45, v50, v20, v45
	s_addc_u32 s27, s12, s27
	v_dot2_f32_bf16 v45, v52, v26, v45
	v_dot2_f32_bf16 v45, v56, v24, v45
	v_cvt_scalef32_pk_bf16_fp4 v48, v83, 1.0
	v_cvt_scalef32_pk_bf16_fp4 v50, v83, 1.0 op_sel:[1,0,0]
	v_cvt_scalef32_pk_bf16_fp4 v52, v83, 1.0 op_sel:[0,1,0]
	v_cvt_scalef32_pk_bf16_fp4 v56, v83, 1.0 op_sel:[1,1,0]
	s_nop 0
	v_dot2_f32_bf16 v45, v48, v30, v45
	v_dot2_f32_bf16 v45, v50, v28, v45
	s_nop 0
	v_dot2_f32_bf16 v45, v52, v36, v45
	v_dot2_f32_bf16 v45, v56, v34, v45
	s_nop 0
	global_load_dwordx4 v[80:83], v32, s[26:27]
	s_waitcnt vmcnt(15)
	v_cvt_scalef32_pk_bf16_fp4 v46, v84, 1.0
	v_cvt_scalef32_pk_bf16_fp4 v48, v84, 1.0 op_sel:[1,0,0]
	v_cvt_scalef32_pk_bf16_fp4 v50, v84, 1.0 op_sel:[0,1,0]
	v_cvt_scalef32_pk_bf16_fp4 v52, v84, 1.0 op_sel:[1,1,0]
	v_dot2_f32_bf16 v54, v46, v6, 0
	v_dot2_f32_bf16 v46, v48, v4, 0
	v_dot2_f32_bf16 v54, v50, v10, v54
	v_readlane_b32 s26, v2, 5
	v_dot2_f32_bf16 v46, v52, v8, v46
	v_cvt_scalef32_pk_bf16_fp4 v48, v85, 1.0
	v_cvt_scalef32_pk_bf16_fp4 v50, v85, 1.0 op_sel:[1,0,0]
	v_cvt_scalef32_pk_bf16_fp4 v52, v85, 1.0 op_sel:[0,1,0]
	v_cvt_scalef32_pk_bf16_fp4 v56, v85, 1.0 op_sel:[1,1,0]
	s_lshr_b32 s26, s26, 7
	v_dot2_f32_bf16 v54, v48, v14, v54
	v_dot2_f32_bf16 v46, v50, v12, v46
	s_mov_b32 s27, s86
	v_dot2_f32_bf16 v54, v52, v18, v54
	v_dot2_f32_bf16 v46, v56, v16, v46
	v_cvt_scalef32_pk_bf16_fp4 v48, v86, 1.0
	v_cvt_scalef32_pk_bf16_fp4 v50, v86, 1.0 op_sel:[1,0,0]
	v_cvt_scalef32_pk_bf16_fp4 v52, v86, 1.0 op_sel:[0,1,0]
	v_cvt_scalef32_pk_bf16_fp4 v56, v86, 1.0 op_sel:[1,1,0]
	s_lshl_b64 s[26:27], s[26:27], 10
	v_dot2_f32_bf16 v54, v48, v22, v54
	v_dot2_f32_bf16 v46, v50, v20, v46
	s_add_u32 s26, s13, s26
	v_dot2_f32_bf16 v54, v52, v26, v54
	v_dot2_f32_bf16 v46, v56, v24, v46
	v_cvt_scalef32_pk_bf16_fp4 v48, v87, 1.0
	v_cvt_scalef32_pk_bf16_fp4 v50, v87, 1.0 op_sel:[1,0,0]
	v_cvt_scalef32_pk_bf16_fp4 v52, v87, 1.0 op_sel:[0,1,0]
	v_cvt_scalef32_pk_bf16_fp4 v56, v87, 1.0 op_sel:[1,1,0]
	s_addc_u32 s27, s12, s27
	v_dot2_f32_bf16 v54, v48, v30, v54
	v_dot2_f32_bf16 v46, v50, v28, v46
	s_nop 0
	v_dot2_f32_bf16 v54, v52, v36, v54
	v_dot2_f32_bf16 v46, v56, v34, v46
	s_nop 2
	v_add_f32_e32 v46, v54, v46
	global_load_dwordx4 v[84:87], v32, s[26:27]
	s_waitcnt vmcnt(15)
; #define P4_FOR16(M) M(0) M(1) M(2) M(3) M(4) M(5) M(6) M(7) M(8) M(9) M(10) M(11) M(12) M(13) M(14) M(15)
; #define P4_U(i) { P4_DOT(b##i, part[i]); const int nk_ = __builtin_amdgcn_readlane(ksel, nb + i); P4_LOAD(b##i, Ug, nk_); }
; #define P4_U(i) { P4_DOT(b##i, part[i]); const int nk_ = __builtin_amdgcn_readlane(kn, i); P4_LOAD(b##i, nbase, nk_); }
; __device__ __forceinline__ void peer_gather_f4p(const float* X, const int* __restrict__ IDX, const float* __restrict__ G, ...
;     ...
;         {
;     ...
;             P4_FOR16(P4_U)
;     ...
;             P4_RED(7);
;         }
	v_cvt_scalef32_pk_bf16_fp4 v48, v88, 1.0
	v_cvt_scalef32_pk_bf16_fp4 v50, v88, 1.0 op_sel:[1,0,0]
	v_cvt_scalef32_pk_bf16_fp4 v52, v88, 1.0 op_sel:[0,1,0]
	v_cvt_scalef32_pk_bf16_fp4 v54, v88, 1.0 op_sel:[1,1,0]
	v_readlane_b32 s26, v2, 6
	v_dot2_f32_bf16 v47, v48, v6, 0
	v_dot2_f32_bf16 v47, v50, v4, v47
	v_dot2_f32_bf16 v47, v52, v10, v47
	s_lshr_b32 s26, s26, 7
	v_dot2_f32_bf16 v47, v54, v8, v47
	v_cvt_scalef32_pk_bf16_fp4 v50, v89, 1.0
	v_cvt_scalef32_pk_bf16_fp4 v52, v89, 1.0 op_sel:[1,0,0]
	v_cvt_scalef32_pk_bf16_fp4 v54, v89, 1.0 op_sel:[0,1,0]
	v_cvt_scalef32_pk_bf16_fp4 v58, v89, 1.0 op_sel:[1,1,0]
	s_mov_b32 s27, s86
	v_dot2_f32_bf16 v47, v50, v14, v47
	v_dot2_f32_bf16 v47, v52, v12, v47
	s_lshl_b64 s[26:27], s[26:27], 10
	v_dot2_f32_bf16 v47, v54, v18, v47
	v_dot2_f32_bf16 v47, v58, v16, v47
	v_cvt_scalef32_pk_bf16_fp4 v50, v90, 1.0
	v_cvt_scalef32_pk_bf16_fp4 v52, v90, 1.0 op_sel:[1,0,0]
	v_cvt_scalef32_pk_bf16_fp4 v54, v90, 1.0 op_sel:[0,1,0]
	v_cvt_scalef32_pk_bf16_fp4 v58, v90, 1.0 op_sel:[1,1,0]
	s_add_u32 s26, s13, s26
	v_dot2_f32_bf16 v47, v50, v22, v47
	v_dot2_f32_bf16 v47, v52, v20, v47
	s_addc_u32 s27, s12, s27
	v_dot2_f32_bf16 v47, v54, v26, v47
	v_dot2_f32_bf16 v47, v58, v24, v47
	v_cvt_scalef32_pk_bf16_fp4 v50, v91, 1.0
	v_cvt_scalef32_pk_bf16_fp4 v52, v91, 1.0 op_sel:[1,0,0]
	v_cvt_scalef32_pk_bf16_fp4 v54, v91, 1.0 op_sel:[0,1,0]
	v_cvt_scalef32_pk_bf16_fp4 v58, v91, 1.0 op_sel:[1,1,0]
	s_nop 0
	v_dot2_f32_bf16 v47, v50, v30, v47
	v_dot2_f32_bf16 v47, v52, v28, v47
	s_nop 0
	v_dot2_f32_bf16 v47, v54, v36, v47
	v_dot2_f32_bf16 v47, v58, v34, v47
	s_nop 0
	global_load_dwordx4 v[88:91], v32, s[26:27]
	s_waitcnt vmcnt(15)
	v_cvt_scalef32_pk_bf16_fp4 v48, v92, 1.0
	v_cvt_scalef32_pk_bf16_fp4 v50, v92, 1.0 op_sel:[1,0,0]
	v_cvt_scalef32_pk_bf16_fp4 v52, v92, 1.0 op_sel:[0,1,0]
	v_cvt_scalef32_pk_bf16_fp4 v54, v92, 1.0 op_sel:[1,1,0]
	v_dot2_f32_bf16 v56, v48, v6, 0
	v_dot2_f32_bf16 v48, v50, v4, 0
	v_dot2_f32_bf16 v56, v52, v10, v56
	v_readlane_b32 s26, v2, 7
	v_dot2_f32_bf16 v48, v54, v8, v48
	v_cvt_scalef32_pk_bf16_fp4 v50, v93, 1.0
	v_cvt_scalef32_pk_bf16_fp4 v52, v93, 1.0 op_sel:[1,0,0]
	v_cvt_scalef32_pk_bf16_fp4 v54, v93, 1.0 op_sel:[0,1,0]
	v_cvt_scalef32_pk_bf16_fp4 v58, v93, 1.0 op_sel:[1,1,0]
	s_lshr_b32 s26, s26, 7
	v_dot2_f32_bf16 v56, v50, v14, v56
	v_dot2_f32_bf16 v48, v52, v12, v48
	s_mov_b32 s27, s86
	v_dot2_f32_bf16 v56, v54, v18, v56
	v_dot2_f32_bf16 v48, v58, v16, v48
	v_cvt_scalef32_pk_bf16_fp4 v50, v94, 1.0
	v_cvt_scalef32_pk_bf16_fp4 v52, v94, 1.0 op_sel:[1,0,0]
	v_cvt_scalef32_pk_bf16_fp4 v54, v94, 1.0 op_sel:[0,1,0]
	v_cvt_scalef32_pk_bf16_fp4 v58, v94, 1.0 op_sel:[1,1,0]
	s_lshl_b64 s[26:27], s[26:27], 10
	v_dot2_f32_bf16 v56, v50, v22, v56
	v_dot2_f32_bf16 v48, v52, v20, v48
	s_add_u32 s26, s13, s26
	v_dot2_f32_bf16 v56, v54, v26, v56
	v_dot2_f32_bf16 v48, v58, v24, v48
	v_cvt_scalef32_pk_bf16_fp4 v50, v95, 1.0
	v_cvt_scalef32_pk_bf16_fp4 v52, v95, 1.0 op_sel:[1,0,0]
	v_cvt_scalef32_pk_bf16_fp4 v54, v95, 1.0 op_sel:[0,1,0]
	v_cvt_scalef32_pk_bf16_fp4 v58, v95, 1.0 op_sel:[1,1,0]
	s_addc_u32 s27, s12, s27
	v_dot2_f32_bf16 v56, v50, v30, v56
	v_dot2_f32_bf16 v48, v52, v28, v48
	s_nop 0
	v_dot2_f32_bf16 v56, v54, v36, v56
	v_dot2_f32_bf16 v48, v58, v34, v48
	s_nop 2
	v_add_f32_e32 v48, v56, v48
	global_load_dwordx4 v[92:95], v32, s[26:27]
	s_waitcnt vmcnt(15)
	v_cvt_scalef32_pk_bf16_fp4 v50, v96, 1.0
	v_cvt_scalef32_pk_bf16_fp4 v52, v96, 1.0 op_sel:[1,0,0]
	v_cvt_scalef32_pk_bf16_fp4 v54, v96, 1.0 op_sel:[0,1,0]
	v_cvt_scalef32_pk_bf16_fp4 v56, v96, 1.0 op_sel:[1,1,0]
	v_readlane_b32 s26, v2, 8
	v_dot2_f32_bf16 v49, v50, v6, 0
	v_dot2_f32_bf16 v49, v52, v4, v49
	v_dot2_f32_bf16 v49, v54, v10, v49
	s_lshr_b32 s26, s26, 7
	v_dot2_f32_bf16 v49, v56, v8, v49
	v_cvt_scalef32_pk_bf16_fp4 v52, v97, 1.0
	v_cvt_scalef32_pk_bf16_fp4 v54, v97, 1.0 op_sel:[1,0,0]
	v_cvt_scalef32_pk_bf16_fp4 v56, v97, 1.0 op_sel:[0,1,0]
	v_cvt_scalef32_pk_bf16_fp4 v60, v97, 1.0 op_sel:[1,1,0]
	s_mov_b32 s27, s86
	v_dot2_f32_bf16 v49, v52, v14, v49
	v_dot2_f32_bf16 v49, v54, v12, v49
	s_lshl_b64 s[26:27], s[26:27], 10
	v_dot2_f32_bf16 v49, v56, v18, v49
	v_dot2_f32_bf16 v49, v60, v16, v49
	v_cvt_scalef32_pk_bf16_fp4 v52, v98, 1.0
	v_cvt_scalef32_pk_bf16_fp4 v54, v98, 1.0 op_sel:[1,0,0]
	v_cvt_scalef32_pk_bf16_fp4 v56, v98, 1.0 op_sel:[0,1,0]
	v_cvt_scalef32_pk_bf16_fp4 v60, v98, 1.0 op_sel:[1,1,0]
	s_add_u32 s26, s13, s26
	v_dot2_f32_bf16 v49, v52, v22, v49
	v_dot2_f32_bf16 v49, v54, v20, v49
	s_addc_u32 s27, s12, s27
	v_dot2_f32_bf16 v49, v56, v26, v49
	v_dot2_f32_bf16 v49, v60, v24, v49
	v_cvt_scalef32_pk_bf16_fp4 v52, v99, 1.0
	v_cvt_scalef32_pk_bf16_fp4 v54, v99, 1.0 op_sel:[1,0,0]
	v_cvt_scalef32_pk_bf16_fp4 v56, v99, 1.0 op_sel:[0,1,0]
	v_cvt_scalef32_pk_bf16_fp4 v60, v99, 1.0 op_sel:[1,1,0]
	s_nop 0
	v_dot2_f32_bf16 v49, v52, v30, v49
	v_dot2_f32_bf16 v49, v54, v28, v49
	s_nop 0
	v_dot2_f32_bf16 v49, v56, v36, v49
	v_dot2_f32_bf16 v49, v60, v34, v49
	s_nop 0
	global_load_dwordx4 v[96:99], v32, s[26:27]
	s_waitcnt vmcnt(15)
; #define P4_FOR16(M) M(0) M(1) M(2) M(3) M(4) M(5) M(6) M(7) M(8) M(9) M(10) M(11) M(12) M(13) M(14) M(15)
; #define P4_U(i) { P4_DOT(b##i, part[i]); const int nk_ = __builtin_amdgcn_readlane(ksel, nb + i); P4_LOAD(b##i, Ug, nk_); }
; #define P4_U(i) { P4_DOT(b##i, part[i]); const int nk_ = __builtin_amdgcn_readlane(kn, i); P4_LOAD(b##i, nbase, nk_); }
; __device__ __forceinline__ void peer_gather_f4p(const float* X, const int* __restrict__ IDX, const float* __restrict__ G, ...
;     ...
;         {
;     ...
;             P4_FOR16(P4_U)
;     ...
;             P4_RED(7);
;         }
	v_cvt_scalef32_pk_bf16_fp4 v50, v104, 1.0
	v_cvt_scalef32_pk_bf16_fp4 v52, v104, 1.0 op_sel:[1,0,0]
	v_cvt_scalef32_pk_bf16_fp4 v54, v104, 1.0 op_sel:[0,1,0]
	v_cvt_scalef32_pk_bf16_fp4 v56, v104, 1.0 op_sel:[1,1,0]
	v_dot2_f32_bf16 v58, v50, v6, 0
	v_dot2_f32_bf16 v50, v52, v4, 0
	v_dot2_f32_bf16 v58, v54, v10, v58
	v_readlane_b32 s26, v2, 9
	v_dot2_f32_bf16 v50, v56, v8, v50
	v_cvt_scalef32_pk_bf16_fp4 v52, v105, 1.0
	v_cvt_scalef32_pk_bf16_fp4 v54, v105, 1.0 op_sel:[1,0,0]
	v_cvt_scalef32_pk_bf16_fp4 v56, v105, 1.0 op_sel:[0,1,0]
	v_cvt_scalef32_pk_bf16_fp4 v60, v105, 1.0 op_sel:[1,1,0]
	s_lshr_b32 s26, s26, 7
	v_dot2_f32_bf16 v58, v52, v14, v58
	v_dot2_f32_bf16 v50, v54, v12, v50
	s_mov_b32 s27, s86
	v_dot2_f32_bf16 v58, v56, v18, v58
	v_dot2_f32_bf16 v50, v60, v16, v50
	v_cvt_scalef32_pk_bf16_fp4 v52, v106, 1.0
	v_cvt_scalef32_pk_bf16_fp4 v54, v106, 1.0 op_sel:[1,0,0]
	v_cvt_scalef32_pk_bf16_fp4 v56, v106, 1.0 op_sel:[0,1,0]
	v_cvt_scalef32_pk_bf16_fp4 v60, v106, 1.0 op_sel:[1,1,0]
	s_lshl_b64 s[26:27], s[26:27], 10
	v_dot2_f32_bf16 v58, v52, v22, v58
	v_dot2_f32_bf16 v50, v54, v20, v50
	s_add_u32 s26, s13, s26
	v_dot2_f32_bf16 v58, v56, v26, v58
	v_dot2_f32_bf16 v50, v60, v24, v50
	v_cvt_scalef32_pk_bf16_fp4 v52, v107, 1.0
	v_cvt_scalef32_pk_bf16_fp4 v54, v107, 1.0 op_sel:[1,0,0]
	v_cvt_scalef32_pk_bf16_fp4 v56, v107, 1.0 op_sel:[0,1,0]
	v_cvt_scalef32_pk_bf16_fp4 v60, v107, 1.0 op_sel:[1,1,0]
	s_addc_u32 s27, s12, s27
	v_dot2_f32_bf16 v58, v52, v30, v58
	v_dot2_f32_bf16 v50, v54, v28, v50
	s_nop 0
	v_dot2_f32_bf16 v58, v56, v36, v58
	v_dot2_f32_bf16 v50, v60, v34, v50
	s_nop 2
	v_add_f32_e32 v50, v58, v50
	global_load_dwordx4 v[104:107], v32, s[26:27]
	s_waitcnt vmcnt(15)
	v_cvt_scalef32_pk_bf16_fp4 v52, v108, 1.0
	v_cvt_scalef32_pk_bf16_fp4 v54, v108, 1.0 op_sel:[1,0,0]
	v_cvt_scalef32_pk_bf16_fp4 v56, v108, 1.0 op_sel:[0,1,0]
	v_cvt_scalef32_pk_bf16_fp4 v58, v108, 1.0 op_sel:[1,1,0]
	v_readlane_b32 s26, v2, 10
	v_dot2_f32_bf16 v51, v52, v6, 0
	v_dot2_f32_bf16 v51, v54, v4, v51
	v_dot2_f32_bf16 v51, v56, v10, v51
	s_lshr_b32 s26, s26, 7
	v_dot2_f32_bf16 v51, v58, v8, v51
	v_cvt_scalef32_pk_bf16_fp4 v54, v109, 1.0
	v_cvt_scalef32_pk_bf16_fp4 v56, v109, 1.0 op_sel:[1,0,0]
	v_cvt_scalef32_pk_bf16_fp4 v58, v109, 1.0 op_sel:[0,1,0]
	v_cvt_scalef32_pk_bf16_fp4 v62, v109, 1.0 op_sel:[1,1,0]
	s_mov_b32 s27, s86
	v_dot2_f32_bf16 v51, v54, v14, v51
	v_dot2_f32_bf16 v51, v56, v12, v51
	s_lshl_b64 s[26:27], s[26:27], 10
	v_dot2_f32_bf16 v51, v58, v18, v51
	v_dot2_f32_bf16 v51, v62, v16, v51
	v_cvt_scalef32_pk_bf16_fp4 v54, v110, 1.0
	v_cvt_scalef32_pk_bf16_fp4 v56, v110, 1.0 op_sel:[1,0,0]
	v_cvt_scalef32_pk_bf16_fp4 v58, v110, 1.0 op_sel:[0,1,0]
	v_cvt_scalef32_pk_bf16_fp4 v62, v110, 1.0 op_sel:[1,1,0]
	s_add_u32 s26, s13, s26
	v_dot2_f32_bf16 v51, v54, v22, v51
	v_dot2_f32_bf16 v51, v56, v20, v51
	s_addc_u32 s27, s12, s27
	v_dot2_f32_bf16 v51, v58, v26, v51
	v_dot2_f32_bf16 v51, v62, v24, v51
	v_cvt_scalef32_pk_bf16_fp4 v54, v111, 1.0
	v_cvt_scalef32_pk_bf16_fp4 v56, v111, 1.0 op_sel:[1,0,0]
	v_cvt_scalef32_pk_bf16_fp4 v58, v111, 1.0 op_sel:[0,1,0]
	v_cvt_scalef32_pk_bf16_fp4 v62, v111, 1.0 op_sel:[1,1,0]
	s_nop 0
	v_dot2_f32_bf16 v51, v54, v30, v51
	v_dot2_f32_bf16 v51, v56, v28, v51
	s_nop 0
	v_dot2_f32_bf16 v51, v58, v36, v51
	v_dot2_f32_bf16 v51, v62, v34, v51
	s_nop 0
	global_load_dwordx4 v[108:111], v32, s[26:27]
	s_waitcnt vmcnt(15)
	v_cvt_scalef32_pk_bf16_fp4 v52, v112, 1.0
	v_cvt_scalef32_pk_bf16_fp4 v54, v112, 1.0 op_sel:[1,0,0]
	v_cvt_scalef32_pk_bf16_fp4 v56, v112, 1.0 op_sel:[0,1,0]
	v_cvt_scalef32_pk_bf16_fp4 v58, v112, 1.0 op_sel:[1,1,0]
	v_dot2_f32_bf16 v100, v52, v6, 0
	v_dot2_f32_bf16 v100, v54, v4, v100
	v_dot2_f32_bf16 v100, v56, v10, v100
	v_readlane_b32 s26, v2, 11
	v_dot2_f32_bf16 v100, v58, v8, v100
	v_cvt_scalef32_pk_bf16_fp4 v54, v113, 1.0
	v_cvt_scalef32_pk_bf16_fp4 v56, v113, 1.0 op_sel:[1,0,0]
	v_cvt_scalef32_pk_bf16_fp4 v58, v113, 1.0 op_sel:[0,1,0]
	v_cvt_scalef32_pk_bf16_fp4 v62, v113, 1.0 op_sel:[1,1,0]
	s_lshr_b32 s26, s26, 7
	v_dot2_f32_bf16 v100, v54, v14, v100
	v_dot2_f32_bf16 v100, v56, v12, v100
	s_mov_b32 s27, s86
	v_dot2_f32_bf16 v100, v58, v18, v100
	v_dot2_f32_bf16 v100, v62, v16, v100
	v_cvt_scalef32_pk_bf16_fp4 v54, v114, 1.0
	v_cvt_scalef32_pk_bf16_fp4 v56, v114, 1.0 op_sel:[1,0,0]
	v_cvt_scalef32_pk_bf16_fp4 v58, v114, 1.0 op_sel:[0,1,0]
	v_cvt_scalef32_pk_bf16_fp4 v62, v114, 1.0 op_sel:[1,1,0]
	s_lshl_b64 s[26:27], s[26:27], 10
	v_dot2_f32_bf16 v100, v54, v22, v100
	v_dot2_f32_bf16 v100, v56, v20, v100
	s_add_u32 s26, s13, s26
	v_dot2_f32_bf16 v100, v58, v26, v100
	v_dot2_f32_bf16 v100, v62, v24, v100
	v_cvt_scalef32_pk_bf16_fp4 v54, v115, 1.0
	v_cvt_scalef32_pk_bf16_fp4 v56, v115, 1.0 op_sel:[1,0,0]
	v_cvt_scalef32_pk_bf16_fp4 v58, v115, 1.0 op_sel:[0,1,0]
	v_cvt_scalef32_pk_bf16_fp4 v62, v115, 1.0 op_sel:[1,1,0]
	s_addc_u32 s27, s12, s27
	v_dot2_f32_bf16 v100, v54, v30, v100
	v_dot2_f32_bf16 v100, v56, v28, v100
	s_nop 0
	v_dot2_f32_bf16 v100, v58, v36, v100
	v_dot2_f32_bf16 v100, v62, v34, v100
	s_nop 0
	global_load_dwordx4 v[112:115], v32, s[26:27]
	s_waitcnt vmcnt(15)
; #define P4_FOR16(M) M(0) M(1) M(2) M(3) M(4) M(5) M(6) M(7) M(8) M(9) M(10) M(11) M(12) M(13) M(14) M(15)
; #define P4_U(i) { P4_DOT(b##i, part[i]); const int nk_ = __builtin_amdgcn_readlane(ksel, nb + i); P4_LOAD(b##i, Ug, nk_); }
; #define P4_U(i) { P4_DOT(b##i, part[i]); const int nk_ = __builtin_amdgcn_readlane(kn, i); P4_LOAD(b##i, nbase, nk_); }
; __device__ __forceinline__ void peer_gather_f4p(const float* X, const int* __restrict__ IDX, const float* __restrict__ G, ...
;     ...
;         {
;     ...
;             P4_FOR16(P4_U)
;     ...
;             P4_RED(7);
;         }
	v_cvt_scalef32_pk_bf16_fp4 v52, v116, 1.0
	v_cvt_scalef32_pk_bf16_fp4 v54, v116, 1.0 op_sel:[1,0,0]
	v_cvt_scalef32_pk_bf16_fp4 v56, v116, 1.0 op_sel:[0,1,0]
	v_cvt_scalef32_pk_bf16_fp4 v58, v116, 1.0 op_sel:[1,1,0]
	v_dot2_f32_bf16 v101, v52, v6, 0
	v_dot2_f32_bf16 v101, v54, v4, v101
	v_dot2_f32_bf16 v101, v56, v10, v101
	v_readlane_b32 s26, v2, 12
	v_dot2_f32_bf16 v101, v58, v8, v101
	v_cvt_scalef32_pk_bf16_fp4 v54, v117, 1.0
	v_cvt_scalef32_pk_bf16_fp4 v56, v117, 1.0 op_sel:[1,0,0]
	v_cvt_scalef32_pk_bf16_fp4 v58, v117, 1.0 op_sel:[0,1,0]
	v_cvt_scalef32_pk_bf16_fp4 v62, v117, 1.0 op_sel:[1,1,0]
	s_lshr_b32 s26, s26, 7
	v_dot2_f32_bf16 v101, v54, v14, v101
	v_dot2_f32_bf16 v101, v56, v12, v101
	s_mov_b32 s27, s86
	v_dot2_f32_bf16 v101, v58, v18, v101
	v_dot2_f32_bf16 v101, v62, v16, v101
	v_cvt_scalef32_pk_bf16_fp4 v54, v118, 1.0
	v_cvt_scalef32_pk_bf16_fp4 v56, v118, 1.0 op_sel:[1,0,0]
	v_cvt_scalef32_pk_bf16_fp4 v58, v118, 1.0 op_sel:[0,1,0]
	v_cvt_scalef32_pk_bf16_fp4 v62, v118, 1.0 op_sel:[1,1,0]
	s_lshl_b64 s[26:27], s[26:27], 10
	v_dot2_f32_bf16 v101, v54, v22, v101
	v_dot2_f32_bf16 v101, v56, v20, v101
	s_add_u32 s26, s13, s26
	v_dot2_f32_bf16 v101, v58, v26, v101
	v_dot2_f32_bf16 v101, v62, v24, v101
	v_cvt_scalef32_pk_bf16_fp4 v54, v119, 1.0
	v_cvt_scalef32_pk_bf16_fp4 v56, v119, 1.0 op_sel:[1,0,0]
	v_cvt_scalef32_pk_bf16_fp4 v58, v119, 1.0 op_sel:[0,1,0]
	v_cvt_scalef32_pk_bf16_fp4 v62, v119, 1.0 op_sel:[1,1,0]
	s_addc_u32 s27, s12, s27
	v_dot2_f32_bf16 v101, v54, v30, v101
	v_dot2_f32_bf16 v101, v56, v28, v101
	s_nop 0
	v_dot2_f32_bf16 v101, v58, v36, v101
	v_dot2_f32_bf16 v101, v62, v34, v101
	s_nop 0
	global_load_dwordx4 v[116:119], v32, s[26:27]
	s_waitcnt vmcnt(15)
	v_cvt_scalef32_pk_bf16_fp4 v52, v120, 1.0
	v_cvt_scalef32_pk_bf16_fp4 v54, v120, 1.0 op_sel:[1,0,0]
	v_cvt_scalef32_pk_bf16_fp4 v56, v120, 1.0 op_sel:[0,1,0]
	v_cvt_scalef32_pk_bf16_fp4 v58, v120, 1.0 op_sel:[1,1,0]
	v_dot2_f32_bf16 v102, v52, v6, 0
	v_dot2_f32_bf16 v102, v54, v4, v102
	v_dot2_f32_bf16 v102, v56, v10, v102
	v_readlane_b32 s26, v2, 13
	v_dot2_f32_bf16 v102, v58, v8, v102
	v_cvt_scalef32_pk_bf16_fp4 v54, v121, 1.0
	v_cvt_scalef32_pk_bf16_fp4 v56, v121, 1.0 op_sel:[1,0,0]
	v_cvt_scalef32_pk_bf16_fp4 v58, v121, 1.0 op_sel:[0,1,0]
	v_cvt_scalef32_pk_bf16_fp4 v62, v121, 1.0 op_sel:[1,1,0]
	s_lshr_b32 s26, s26, 7
	v_dot2_f32_bf16 v102, v54, v14, v102
	v_dot2_f32_bf16 v102, v56, v12, v102
	s_mov_b32 s27, s86
	v_dot2_f32_bf16 v102, v58, v18, v102
	v_dot2_f32_bf16 v102, v62, v16, v102
	v_cvt_scalef32_pk_bf16_fp4 v54, v122, 1.0
	v_cvt_scalef32_pk_bf16_fp4 v56, v122, 1.0 op_sel:[1,0,0]
	v_cvt_scalef32_pk_bf16_fp4 v58, v122, 1.0 op_sel:[0,1,0]
	v_cvt_scalef32_pk_bf16_fp4 v62, v122, 1.0 op_sel:[1,1,0]
	s_lshl_b64 s[26:27], s[26:27], 10
	v_dot2_f32_bf16 v102, v54, v22, v102
	v_dot2_f32_bf16 v102, v56, v20, v102
	s_add_u32 s26, s13, s26
	v_dot2_f32_bf16 v102, v58, v26, v102
	v_dot2_f32_bf16 v102, v62, v24, v102
	v_cvt_scalef32_pk_bf16_fp4 v54, v123, 1.0
	v_cvt_scalef32_pk_bf16_fp4 v56, v123, 1.0 op_sel:[1,0,0]
	v_cvt_scalef32_pk_bf16_fp4 v58, v123, 1.0 op_sel:[0,1,0]
	v_cvt_scalef32_pk_bf16_fp4 v62, v123, 1.0 op_sel:[1,1,0]
	s_addc_u32 s27, s12, s27
	v_dot2_f32_bf16 v102, v54, v30, v102
	v_dot2_f32_bf16 v102, v56, v28, v102
	s_nop 0
	v_dot2_f32_bf16 v102, v58, v36, v102
	v_dot2_f32_bf16 v102, v62, v34, v102
	s_nop 0
	global_load_dwordx4 v[120:123], v32, s[26:27]
	s_waitcnt vmcnt(15)
	v_cvt_scalef32_pk_bf16_fp4 v52, v124, 1.0
	v_cvt_scalef32_pk_bf16_fp4 v54, v124, 1.0 op_sel:[1,0,0]
	v_cvt_scalef32_pk_bf16_fp4 v56, v124, 1.0 op_sel:[0,1,0]
	v_cvt_scalef32_pk_bf16_fp4 v58, v124, 1.0 op_sel:[1,1,0]
	v_dot2_f32_bf16 v60, v52, v6, 0
	v_dot2_f32_bf16 v52, v54, v4, 0
	v_dot2_f32_bf16 v60, v56, v10, v60
	v_readlane_b32 s26, v2, 14
	v_dot2_f32_bf16 v52, v58, v8, v52
	v_cvt_scalef32_pk_bf16_fp4 v54, v125, 1.0
	v_cvt_scalef32_pk_bf16_fp4 v56, v125, 1.0 op_sel:[1,0,0]
	v_cvt_scalef32_pk_bf16_fp4 v58, v125, 1.0 op_sel:[0,1,0]
	v_cvt_scalef32_pk_bf16_fp4 v62, v125, 1.0 op_sel:[1,1,0]
	s_lshr_b32 s26, s26, 7
	v_dot2_f32_bf16 v60, v54, v14, v60
	v_dot2_f32_bf16 v52, v56, v12, v52
	s_mov_b32 s27, s86
	v_dot2_f32_bf16 v60, v58, v18, v60
	v_dot2_f32_bf16 v52, v62, v16, v52
	v_cvt_scalef32_pk_bf16_fp4 v54, v126, 1.0
	v_cvt_scalef32_pk_bf16_fp4 v56, v126, 1.0 op_sel:[1,0,0]
	v_cvt_scalef32_pk_bf16_fp4 v58, v126, 1.0 op_sel:[0,1,0]
	v_cvt_scalef32_pk_bf16_fp4 v62, v126, 1.0 op_sel:[1,1,0]
	s_lshl_b64 s[26:27], s[26:27], 10
	v_dot2_f32_bf16 v60, v54, v22, v60
	v_dot2_f32_bf16 v52, v56, v20, v52
	s_add_u32 s26, s13, s26
	v_dot2_f32_bf16 v60, v58, v26, v60
	v_dot2_f32_bf16 v52, v62, v24, v52
	v_cvt_scalef32_pk_bf16_fp4 v54, v127, 1.0
	v_cvt_scalef32_pk_bf16_fp4 v56, v127, 1.0 op_sel:[1,0,0]
	v_cvt_scalef32_pk_bf16_fp4 v58, v127, 1.0 op_sel:[0,1,0]
	v_cvt_scalef32_pk_bf16_fp4 v62, v127, 1.0 op_sel:[1,1,0]
	s_addc_u32 s27, s12, s27
	v_dot2_f32_bf16 v60, v54, v30, v60
	v_dot2_f32_bf16 v52, v56, v28, v52
	s_nop 0
	v_dot2_f32_bf16 v60, v58, v36, v60
	v_dot2_f32_bf16 v52, v62, v34, v52
	s_nop 0
	s_nop 2
	v_add_f32_e32 v62, v60, v52
	global_load_dwordx4 v[124:127], v32, s[26:27]
	s_waitcnt vmcnt(15)
; #define P4_FOR16(M) M(0) M(1) M(2) M(3) M(4) M(5) M(6) M(7) M(8) M(9) M(10) M(11) M(12) M(13) M(14) M(15)
; #define P4_U(i) { P4_DOT(b##i, part[i]); const int nk_ = __builtin_amdgcn_readlane(ksel, nb + i); P4_LOAD(b##i, Ug, nk_); }
; #define P4_U(i) { P4_DOT(b##i, part[i]); const int nk_ = __builtin_amdgcn_readlane(kn, i); P4_LOAD(b##i, nbase, nk_); }
; __device__ __forceinline__ float gelu_tanh(float h) {
;     return 0.5f * h * (1.f + tanhf(0.7978845608028654f * (h + 0.044715f * h * h * h)));
; }
; __device__ __forceinline__ void peer_gather_f4p(const float* X, const int* __restrict__ IDX, const float* __restrict__ G, ...
;     ...
;         {
;     ...
;             P4_FOR16(P4_U)
;     ...
;             P4_RED(7);
;         }
	v_cvt_scalef32_pk_bf16_fp4 v52, v128, 1.0
	v_cvt_scalef32_pk_bf16_fp4 v54, v128, 1.0 op_sel:[1,0,0]
	v_cvt_scalef32_pk_bf16_fp4 v56, v128, 1.0 op_sel:[0,1,0]
	v_cvt_scalef32_pk_bf16_fp4 v58, v128, 1.0 op_sel:[1,1,0]
	v_readlane_b32 s26, v2, 15
	v_dot2_f32_bf16 v60, v52, v6, 0
	v_dot2c_f32_bf16_e32 v38, v54, v4
	s_lshr_b32 s26, s26, 7
	v_dot2_f32_bf16 v60, v56, v10, v60
	v_dot2c_f32_bf16_e32 v38, v58, v8
	v_cvt_scalef32_pk_bf16_fp4 v4, v129, 1.0
	v_cvt_scalef32_pk_bf16_fp4 v6, v129, 1.0 op_sel:[1,0,0]
	v_cvt_scalef32_pk_bf16_fp4 v8, v129, 1.0 op_sel:[0,1,0]
	v_cvt_scalef32_pk_bf16_fp4 v10, v129, 1.0 op_sel:[1,1,0]
	s_mov_b32 s27, s86
	v_dot2_f32_bf16 v60, v4, v14, v60
	v_dot2c_f32_bf16_e32 v38, v6, v12
	s_lshl_b64 s[26:27], s[26:27], 10
	v_dot2_f32_bf16 v60, v8, v18, v60
	v_dot2c_f32_bf16_e32 v38, v10, v16
	v_cvt_scalef32_pk_bf16_fp4 v4, v130, 1.0
	v_cvt_scalef32_pk_bf16_fp4 v6, v130, 1.0 op_sel:[1,0,0]
	v_cvt_scalef32_pk_bf16_fp4 v8, v130, 1.0 op_sel:[0,1,0]
	v_cvt_scalef32_pk_bf16_fp4 v10, v130, 1.0 op_sel:[1,1,0]
	s_add_u32 s26, s13, s26
	v_dot2_f32_bf16 v60, v4, v22, v60
	v_dot2c_f32_bf16_e32 v38, v6, v20
	s_addc_u32 s27, s12, s27
	v_dot2_f32_bf16 v60, v8, v26, v60
	v_dot2c_f32_bf16_e32 v38, v10, v24
	v_cvt_scalef32_pk_bf16_fp4 v4, v131, 1.0
	v_cvt_scalef32_pk_bf16_fp4 v6, v131, 1.0 op_sel:[1,0,0]
	v_cvt_scalef32_pk_bf16_fp4 v8, v131, 1.0 op_sel:[0,1,0]
	v_cvt_scalef32_pk_bf16_fp4 v10, v131, 1.0 op_sel:[1,1,0]
	v_cndmask_b32_e64 v2, v49, v41, s[48:49]
	v_dot2_f32_bf16 v60, v4, v30, v60
	v_dot2c_f32_bf16_e32 v38, v6, v28
	v_cndmask_b32_e64 v7, v43, v51, s[48:49]
	v_dot2_f32_bf16 v60, v8, v36, v60
	v_dot2c_f32_bf16_e32 v38, v10, v34
	ds_swizzle_b32 v7, v7 offset:swizzle(SWAP,8)
	s_nop 2
	v_add_f32_e32 v6, v60, v38
	global_load_dwordx4 v[128:131], v32, s[26:27]
	v_cndmask_b32_e64 v4, v41, v49, s[48:49]
	ds_swizzle_b32 v4, v4 offset:swizzle(SWAP,8)
	v_cndmask_b32_e64 v5, v42, v50, s[48:49]
	ds_swizzle_b32 v5, v5 offset:swizzle(SWAP,8)
	v_cndmask_b32_e64 v8, v44, v100, s[48:49]
	ds_swizzle_b32 v8, v8 offset:swizzle(SWAP,8)
	v_cndmask_b32_e64 v9, v45, v101, s[48:49]
	ds_swizzle_b32 v9, v9 offset:swizzle(SWAP,8)
	v_cndmask_b32_e64 v10, v46, v102, s[48:49]
	s_waitcnt lgkmcnt(3)
	v_add_f32_e32 v2, v2, v4
	v_cndmask_b32_e64 v4, v50, v42, s[48:49]
	ds_swizzle_b32 v10, v10 offset:swizzle(SWAP,8)
	v_cndmask_b32_e64 v11, v47, v62, s[48:49]
	s_waitcnt lgkmcnt(3)
	v_add_f32_e32 v4, v4, v5
	v_cndmask_b32_e64 v5, v51, v43, s[48:49]
	ds_swizzle_b32 v11, v11 offset:swizzle(SWAP,8)
	v_add_f32_e32 v5, v5, v7
	v_cndmask_b32_e64 v7, v100, v44, s[48:49]
	s_waitcnt lgkmcnt(3)
	v_add_f32_e32 v7, v7, v8
	v_cndmask_b32_e64 v8, v101, v45, s[48:49]
	s_waitcnt lgkmcnt(2)
	v_add_f32_e32 v8, v8, v9
	v_cndmask_b32_e64 v9, v102, v46, s[48:49]
	s_waitcnt lgkmcnt(1)
	v_add_f32_e32 v9, v9, v10
	v_cndmask_b32_e64 v10, v62, v47, s[48:49]
	s_waitcnt lgkmcnt(0)
	v_add_f32_e32 v10, v10, v11
	v_cndmask_b32_e64 v11, v6, v48, s[48:49]
	v_cndmask_b32_e64 v6, v48, v6, s[48:49]
	ds_swizzle_b32 v6, v6 offset:swizzle(SWAP,8)
	s_waitcnt lgkmcnt(0)
	v_add_f32_e32 v6, v11, v6
	v_cndmask_b32_e64 v11, v8, v2, s[46:47]
	v_cndmask_b32_e64 v2, v2, v8, s[46:47]
	v_cndmask_b32_e64 v8, v9, v4, s[46:47]
	v_cndmask_b32_e64 v4, v4, v9, s[46:47]
	ds_swizzle_b32 v4, v4 offset:swizzle(SWAP,4)
	ds_swizzle_b32 v2, v2 offset:swizzle(SWAP,4)
	s_waitcnt lgkmcnt(1)
	v_add_f32_e32 v4, v8, v4
	v_cndmask_b32_e64 v8, v10, v5, s[46:47]
	v_cndmask_b32_e64 v5, v5, v10, s[46:47]
	ds_swizzle_b32 v5, v5 offset:swizzle(SWAP,4)
	s_waitcnt lgkmcnt(1)
	v_add_f32_e32 v2, v11, v2
	s_waitcnt lgkmcnt(0)
	v_add_f32_e32 v5, v8, v5
	v_cndmask_b32_e64 v8, v6, v7, s[46:47]
	v_cndmask_b32_e64 v6, v7, v6, s[46:47]
	ds_swizzle_b32 v6, v6 offset:swizzle(SWAP,4)
	v_cndmask_b32_e64 v7, v5, v2, s[44:45]
	v_cndmask_b32_e64 v2, v2, v5, s[44:45]
	ds_swizzle_b32 v2, v2 offset:swizzle(SWAP,2)
	s_waitcnt lgkmcnt(1)
	v_add_f32_e32 v6, v8, v6
	v_cndmask_b32_e64 v5, v6, v4, s[44:45]
	v_cndmask_b32_e64 v4, v4, v6, s[44:45]
	ds_swizzle_b32 v4, v4 offset:swizzle(SWAP,2)
	s_waitcnt lgkmcnt(1)
	v_add_f32_e32 v2, v7, v2
	s_waitcnt lgkmcnt(0)
	v_add_f32_e32 v4, v5, v4
	v_cndmask_b32_e64 v5, v4, v2, s[42:43]
	v_cndmask_b32_e64 v2, v2, v4, s[42:43]
	ds_swizzle_b32 v2, v2 offset:swizzle(SWAP,1)
	s_waitcnt lgkmcnt(0)
	v_add_f32_e32 v2, v5, v2
	ds_swizzle_b32 v4, v2 offset:swizzle(SWAP,16)
	s_waitcnt lgkmcnt(0)
	v_add_f32_e32 v2, v2, v4
	v_mov_b32_e32 v4, v2
	s_nop 1
	v_permlane32_swap_b32_e32 v2, v4
	v_add_f32_e32 v6, v2, v4
	v_lshl_add_u32 v2, v40, 2, s14
	v_add_u32_e32 v4, 0xc0, v2
	ds_read2st64_b32 v[4:5], v4 offset0:9 offset1:17
	s_waitcnt lgkmcnt(0)
	v_mul_f32_e32 v4, v4, v6
	v_mul_f32_e32 v6, 0x3d372713, v4
	v_mul_f32_e32 v6, v4, v6
	v_fma_f32 v6, v4, v6, v4
	v_mul_f32_e32 v6, 0x3f4c422a, v6
	v_cmp_nlt_f32_e64 s[12:13], |v6|, s25
	s_and_saveexec_b64 s[26:27], s[12:13]
	s_xor_b64 s[12:13], exec, s[26:27]
	s_cbranch_execz .LBB0_543
	v_add_f32_e64 v7, |v6|, |v6|
	v_mul_f32_e32 v8, 0x3fb8aa3b, v7
	v_rndne_f32_e32 v9, v8
	v_sub_f32_e32 v10, v8, v9
	v_fma_f32 v8, v7, s70, -v8
	v_fmac_f32_e32 v8, 0x32a5705f, v7
	v_add_f32_e32 v8, v10, v8
	v_cvt_i32_f32_e32 v9, v9
	v_exp_f32_e32 v8, v8
	v_cmp_ngt_f32_e64 s[42:43], s67, v7
	v_ldexp_f32 v8, v8, v9
	s_nop 0
	v_cndmask_b32_e64 v8, 0, v8, s[42:43]
	v_cmp_nlt_f32_e64 s[42:43], s68, v7
	s_nop 1
	v_cndmask_b32_e64 v7, v205, v8, s[42:43]
	v_add_f32_e32 v7, 1.0, v7
	v_rcp_f32_e32 v7, v7
	s_nop 0
	v_fma_f32 v7, v7, -2.0, 1.0
	s_andn2_saveexec_b64 s[12:13], s[12:13]
	s_cbranch_execnz .LBB0_544

; #define P4_FOR16(M) M(0) M(1) M(2) M(3) M(4) M(5) M(6) M(7) M(8) M(9) M(10) M(11) M(12) M(13) M(14) M(15)
; #define P4_U(i) { P4_DOT(b##i, part[i]); const int nk_ = __builtin_amdgcn_readlane(ksel, nb + i); P4_LOAD(b##i, Ug, nk_); }
; #define P4_U(i) { P4_DOT(b##i, part[i]); const int nk_ = __builtin_amdgcn_readlane(kn, i); P4_LOAD(b##i, nbase, nk_); }
; __device__ __forceinline__ void peer_gather_f4p(const float* X, const int* __restrict__ IDX, const float* __restrict__ G, ...
;     ...
; #pragma unroll 1
;         for (int bt = 0; bt < 7; ++bt) {
;             const int ksel = (bt + 1 < 4) ? k0 : k1;
;             const int nb = (16 * (bt + 1)) & 63;
;     ...
;             P4_FOR16(P4_U)
;     ...
;             P4_RED(bt);
;         }
.LBB0_1230:
	s_mov_b32 s87, s86
	s_waitcnt vmcnt(15)
	v_cvt_scalef32_pk_bf16_fp4 v48, v64, 1.0
	v_cvt_scalef32_pk_bf16_fp4 v50, v64, 1.0 op_sel:[1,0,0]
	v_cvt_scalef32_pk_bf16_fp4 v52, v64, 1.0 op_sel:[0,1,0]
	v_cvt_scalef32_pk_bf16_fp4 v54, v64, 1.0 op_sel:[1,1,0]
	v_dot2_f32_bf16 v56, v48, v6, 0
	v_dot2_f32_bf16 v48, v50, v4, 0
	v_dot2_f32_bf16 v56, v52, v10, v56
	s_cmp_lt_u32 s29, 3
	v_dot2_f32_bf16 v48, v54, v8, v48
	v_cvt_scalef32_pk_bf16_fp4 v50, v65, 1.0
	v_cvt_scalef32_pk_bf16_fp4 v52, v65, 1.0 op_sel:[1,0,0]
	v_cvt_scalef32_pk_bf16_fp4 v54, v65, 1.0 op_sel:[0,1,0]
	v_cvt_scalef32_pk_bf16_fp4 v58, v65, 1.0 op_sel:[1,1,0]
	s_cselect_b64 s[48:49], -1, 0
	v_dot2_f32_bf16 v56, v50, v14, v56
	v_dot2_f32_bf16 v48, v52, v12, v48
	s_waitcnt lgkmcnt(1)
	v_cndmask_b32_e64 v46, v39, v38, s[48:49]
	v_dot2_f32_bf16 v56, v54, v18, v56
	v_dot2_f32_bf16 v48, v58, v16, v48
	v_cvt_scalef32_pk_bf16_fp4 v50, v66, 1.0
	v_cvt_scalef32_pk_bf16_fp4 v52, v66, 1.0 op_sel:[1,0,0]
	v_cvt_scalef32_pk_bf16_fp4 v54, v66, 1.0 op_sel:[0,1,0]
	v_cvt_scalef32_pk_bf16_fp4 v58, v66, 1.0 op_sel:[1,1,0]
	s_add_i32 s12, s28, -15
	v_dot2_f32_bf16 v56, v50, v22, v56
	v_dot2_f32_bf16 v48, v52, v20, v48
	v_readlane_b32 s12, v46, s12
	v_dot2_f32_bf16 v56, v54, v26, v56
	v_dot2_f32_bf16 v48, v58, v24, v48
	v_cvt_scalef32_pk_bf16_fp4 v50, v67, 1.0
	v_cvt_scalef32_pk_bf16_fp4 v52, v67, 1.0 op_sel:[1,0,0]
	v_cvt_scalef32_pk_bf16_fp4 v54, v67, 1.0 op_sel:[0,1,0]
	v_cvt_scalef32_pk_bf16_fp4 v58, v67, 1.0 op_sel:[1,1,0]
	s_lshr_b32 s12, s12, 7
	v_dot2_f32_bf16 v56, v50, v30, v56
	v_dot2_f32_bf16 v48, v52, v28, v48
	s_mov_b32 s13, s86
	v_dot2_f32_bf16 v56, v54, v36, v56
	v_dot2_f32_bf16 v48, v58, v34, v48
	s_lshl_b64 s[12:13], s[12:13], 10
	s_nop 2
	v_readfirstlane_b32 s100, v40
	v_readfirstlane_b32 s101, v41
	v_subrev_u32_e32 v207, s100, v40
	v_add_f32_e32 v47, v56, v48
	s_add_u32 s12, s12, s100
	s_addc_u32 s13, s13, s101
	global_load_dwordx4 v[64:67], v207, s[12:13]
	s_waitcnt vmcnt(15)
	v_cvt_scalef32_pk_bf16_fp4 v48, v68, 1.0
	v_cvt_scalef32_pk_bf16_fp4 v50, v68, 1.0 op_sel:[1,0,0]
	v_cvt_scalef32_pk_bf16_fp4 v52, v68, 1.0 op_sel:[0,1,0]
	v_cvt_scalef32_pk_bf16_fp4 v54, v68, 1.0 op_sel:[1,1,0]
	v_dot2_f32_bf16 v56, v48, v6, 0
	v_dot2_f32_bf16 v48, v50, v4, 0
	v_dot2_f32_bf16 v56, v52, v10, v56
	s_add_i32 s12, s28, -14
	v_dot2_f32_bf16 v48, v54, v8, v48
	v_cvt_scalef32_pk_bf16_fp4 v50, v69, 1.0
	v_cvt_scalef32_pk_bf16_fp4 v52, v69, 1.0 op_sel:[1,0,0]
	v_cvt_scalef32_pk_bf16_fp4 v54, v69, 1.0 op_sel:[0,1,0]
	v_cvt_scalef32_pk_bf16_fp4 v58, v69, 1.0 op_sel:[1,1,0]
	v_readlane_b32 s12, v46, s12
	v_dot2_f32_bf16 v56, v50, v14, v56
	v_dot2_f32_bf16 v48, v52, v12, v48
	s_lshr_b32 s12, s12, 7
	v_dot2_f32_bf16 v56, v54, v18, v56
	v_dot2_f32_bf16 v48, v58, v16, v48
	v_cvt_scalef32_pk_bf16_fp4 v50, v70, 1.0
	v_cvt_scalef32_pk_bf16_fp4 v52, v70, 1.0 op_sel:[1,0,0]
	v_cvt_scalef32_pk_bf16_fp4 v54, v70, 1.0 op_sel:[0,1,0]
	v_cvt_scalef32_pk_bf16_fp4 v58, v70, 1.0 op_sel:[1,1,0]
	s_mov_b32 s13, s86
	v_dot2_f32_bf16 v56, v50, v22, v56
	v_dot2_f32_bf16 v48, v52, v20, v48
	s_lshl_b64 s[12:13], s[12:13], 10
	v_dot2_f32_bf16 v56, v54, v26, v56
	v_dot2_f32_bf16 v48, v58, v24, v48
	v_cvt_scalef32_pk_bf16_fp4 v50, v71, 1.0
	v_cvt_scalef32_pk_bf16_fp4 v52, v71, 1.0 op_sel:[1,0,0]
	v_cvt_scalef32_pk_bf16_fp4 v54, v71, 1.0 op_sel:[0,1,0]
	v_cvt_scalef32_pk_bf16_fp4 v58, v71, 1.0 op_sel:[1,1,0]
	v_mov_b32_e32 v42, 0
	v_dot2_f32_bf16 v56, v50, v30, v56
	v_dot2_f32_bf16 v48, v52, v28, v48
	s_nop 0
	v_dot2_f32_bf16 v56, v54, v36, v56
	v_dot2_f32_bf16 v48, v58, v34, v48
	s_nop 2
	v_add_f32_e32 v48, v56, v48
	s_add_u32 s12, s12, s100
	s_addc_u32 s13, s13, s101
	global_load_dwordx4 v[68:71], v207, s[12:13]
	s_waitcnt vmcnt(15)
	v_cvt_scalef32_pk_bf16_fp4 v50, v72, 1.0
	v_cvt_scalef32_pk_bf16_fp4 v52, v72, 1.0 op_sel:[1,0,0]
	v_cvt_scalef32_pk_bf16_fp4 v54, v72, 1.0 op_sel:[0,1,0]
	v_cvt_scalef32_pk_bf16_fp4 v56, v72, 1.0 op_sel:[1,1,0]
	s_add_i32 s12, s28, -13
	v_dot2_f32_bf16 v49, v50, v6, 0
	v_dot2_f32_bf16 v49, v52, v4, v49
	v_dot2_f32_bf16 v49, v54, v10, v49
	v_readlane_b32 s12, v46, s12
	v_dot2_f32_bf16 v49, v56, v8, v49
	v_cvt_scalef32_pk_bf16_fp4 v52, v73, 1.0
	v_cvt_scalef32_pk_bf16_fp4 v54, v73, 1.0 op_sel:[1,0,0]
	v_cvt_scalef32_pk_bf16_fp4 v56, v73, 1.0 op_sel:[0,1,0]
	v_cvt_scalef32_pk_bf16_fp4 v60, v73, 1.0 op_sel:[1,1,0]
	s_lshr_b32 s12, s12, 7
	v_dot2_f32_bf16 v49, v52, v14, v49
	v_dot2_f32_bf16 v49, v54, v12, v49
	s_mov_b32 s13, s86
	v_dot2_f32_bf16 v49, v56, v18, v49
	v_dot2_f32_bf16 v49, v60, v16, v49
	v_cvt_scalef32_pk_bf16_fp4 v52, v74, 1.0
	v_cvt_scalef32_pk_bf16_fp4 v54, v74, 1.0 op_sel:[1,0,0]
	v_cvt_scalef32_pk_bf16_fp4 v56, v74, 1.0 op_sel:[0,1,0]
	v_cvt_scalef32_pk_bf16_fp4 v60, v74, 1.0 op_sel:[1,1,0]
	s_lshl_b64 s[12:13], s[12:13], 10
	v_dot2_f32_bf16 v49, v52, v22, v49
	v_dot2_f32_bf16 v49, v54, v20, v49
	s_nop 0
	v_dot2_f32_bf16 v49, v56, v26, v49
	v_dot2_f32_bf16 v49, v60, v24, v49
	v_cvt_scalef32_pk_bf16_fp4 v52, v75, 1.0
	v_cvt_scalef32_pk_bf16_fp4 v54, v75, 1.0 op_sel:[1,0,0]
	v_cvt_scalef32_pk_bf16_fp4 v56, v75, 1.0 op_sel:[0,1,0]
	v_cvt_scalef32_pk_bf16_fp4 v60, v75, 1.0 op_sel:[1,1,0]
	s_nop 0
	v_dot2_f32_bf16 v49, v52, v30, v49
	v_dot2_f32_bf16 v49, v54, v28, v49
	s_nop 0
	v_dot2_f32_bf16 v49, v56, v36, v49
	v_dot2_f32_bf16 v49, v60, v34, v49
	s_nop 0
	s_add_u32 s12, s12, s100
	s_addc_u32 s13, s13, s101
	global_load_dwordx4 v[72:75], v207, s[12:13]
	s_waitcnt vmcnt(15)
; #define P4_FOR16(M) M(0) M(1) M(2) M(3) M(4) M(5) M(6) M(7) M(8) M(9) M(10) M(11) M(12) M(13) M(14) M(15)
; #define P4_U(i) { P4_DOT(b##i, part[i]); const int nk_ = __builtin_amdgcn_readlane(ksel, nb + i); P4_LOAD(b##i, Ug, nk_); }
; #define P4_U(i) { P4_DOT(b##i, part[i]); const int nk_ = __builtin_amdgcn_readlane(kn, i); P4_LOAD(b##i, nbase, nk_); }
; __device__ __forceinline__ void peer_gather_f4p(const float* X, const int* __restrict__ IDX, const float* __restrict__ G, ...
;     ...
; #pragma unroll 1
;         for (int bt = 0; bt < 7; ++bt) {
;             const int ksel = (bt + 1 < 4) ? k0 : k1;
;             const int nb = (16 * (bt + 1)) & 63;
;     ...
;             P4_FOR16(P4_U)
;     ...
;             P4_RED(bt);
;         }
	v_cvt_scalef32_pk_bf16_fp4 v50, v76, 1.0
	v_cvt_scalef32_pk_bf16_fp4 v52, v76, 1.0 op_sel:[1,0,0]
	v_cvt_scalef32_pk_bf16_fp4 v54, v76, 1.0 op_sel:[0,1,0]
	v_cvt_scalef32_pk_bf16_fp4 v56, v76, 1.0 op_sel:[1,1,0]
	v_dot2_f32_bf16 v58, v50, v6, 0
	v_dot2_f32_bf16 v50, v52, v4, 0
	v_dot2_f32_bf16 v58, v54, v10, v58
	s_add_i32 s12, s28, -12
	v_dot2_f32_bf16 v50, v56, v8, v50
	v_cvt_scalef32_pk_bf16_fp4 v52, v77, 1.0
	v_cvt_scalef32_pk_bf16_fp4 v54, v77, 1.0 op_sel:[1,0,0]
	v_cvt_scalef32_pk_bf16_fp4 v56, v77, 1.0 op_sel:[0,1,0]
	v_cvt_scalef32_pk_bf16_fp4 v60, v77, 1.0 op_sel:[1,1,0]
	v_readlane_b32 s12, v46, s12
	v_dot2_f32_bf16 v58, v52, v14, v58
	v_dot2_f32_bf16 v50, v54, v12, v50
	s_lshr_b32 s12, s12, 7
	v_dot2_f32_bf16 v58, v56, v18, v58
	v_dot2_f32_bf16 v50, v60, v16, v50
	v_cvt_scalef32_pk_bf16_fp4 v52, v78, 1.0
	v_cvt_scalef32_pk_bf16_fp4 v54, v78, 1.0 op_sel:[1,0,0]
	v_cvt_scalef32_pk_bf16_fp4 v56, v78, 1.0 op_sel:[0,1,0]
	v_cvt_scalef32_pk_bf16_fp4 v60, v78, 1.0 op_sel:[1,1,0]
	s_mov_b32 s13, s86
	v_dot2_f32_bf16 v58, v52, v22, v58
	v_dot2_f32_bf16 v50, v54, v20, v50
	s_lshl_b64 s[12:13], s[12:13], 10
	v_dot2_f32_bf16 v58, v56, v26, v58
	v_dot2_f32_bf16 v50, v60, v24, v50
	v_cvt_scalef32_pk_bf16_fp4 v52, v79, 1.0
	v_cvt_scalef32_pk_bf16_fp4 v54, v79, 1.0 op_sel:[1,0,0]
	v_cvt_scalef32_pk_bf16_fp4 v56, v79, 1.0 op_sel:[0,1,0]
	v_cvt_scalef32_pk_bf16_fp4 v60, v79, 1.0 op_sel:[1,1,0]
	s_nop 0
	v_dot2_f32_bf16 v58, v52, v30, v58
	v_dot2_f32_bf16 v50, v54, v28, v50
	s_nop 0
	v_dot2_f32_bf16 v58, v56, v36, v58
	v_dot2_f32_bf16 v50, v60, v34, v50
	s_nop 2
	v_add_f32_e32 v50, v58, v50
	s_add_u32 s12, s12, s100
	s_addc_u32 s13, s13, s101
	global_load_dwordx4 v[76:79], v207, s[12:13]
	s_waitcnt vmcnt(15)
	v_cvt_scalef32_pk_bf16_fp4 v52, v84, 1.0
	v_cvt_scalef32_pk_bf16_fp4 v54, v84, 1.0 op_sel:[1,0,0]
	v_cvt_scalef32_pk_bf16_fp4 v56, v84, 1.0 op_sel:[0,1,0]
	v_cvt_scalef32_pk_bf16_fp4 v58, v84, 1.0 op_sel:[1,1,0]
	s_add_i32 s12, s28, -11
	v_dot2_f32_bf16 v51, v52, v6, 0
	v_dot2_f32_bf16 v51, v54, v4, v51
	v_dot2_f32_bf16 v51, v56, v10, v51
	v_readlane_b32 s12, v46, s12
	v_dot2_f32_bf16 v51, v58, v8, v51
	v_cvt_scalef32_pk_bf16_fp4 v54, v85, 1.0
	v_cvt_scalef32_pk_bf16_fp4 v56, v85, 1.0 op_sel:[1,0,0]
	v_cvt_scalef32_pk_bf16_fp4 v58, v85, 1.0 op_sel:[0,1,0]
	v_cvt_scalef32_pk_bf16_fp4 v62, v85, 1.0 op_sel:[1,1,0]
	s_lshr_b32 s12, s12, 7
	v_dot2_f32_bf16 v51, v54, v14, v51
	v_dot2_f32_bf16 v51, v56, v12, v51
	s_mov_b32 s13, s86
	v_dot2_f32_bf16 v51, v58, v18, v51
	v_dot2_f32_bf16 v51, v62, v16, v51
	v_cvt_scalef32_pk_bf16_fp4 v54, v86, 1.0
	v_cvt_scalef32_pk_bf16_fp4 v56, v86, 1.0 op_sel:[1,0,0]
	v_cvt_scalef32_pk_bf16_fp4 v58, v86, 1.0 op_sel:[0,1,0]
	v_cvt_scalef32_pk_bf16_fp4 v62, v86, 1.0 op_sel:[1,1,0]
	s_lshl_b64 s[12:13], s[12:13], 10
	v_dot2_f32_bf16 v51, v54, v22, v51
	v_dot2_f32_bf16 v51, v56, v20, v51
	s_nop 0
	v_dot2_f32_bf16 v51, v58, v26, v51
	v_dot2_f32_bf16 v51, v62, v24, v51
	v_cvt_scalef32_pk_bf16_fp4 v54, v87, 1.0
	v_cvt_scalef32_pk_bf16_fp4 v56, v87, 1.0 op_sel:[1,0,0]
	v_cvt_scalef32_pk_bf16_fp4 v58, v87, 1.0 op_sel:[0,1,0]
	v_cvt_scalef32_pk_bf16_fp4 v62, v87, 1.0 op_sel:[1,1,0]
	s_nop 0
	v_dot2_f32_bf16 v51, v54, v30, v51
	v_dot2_f32_bf16 v51, v56, v28, v51
	s_nop 0
	v_dot2_f32_bf16 v51, v58, v36, v51
	v_dot2_f32_bf16 v51, v62, v34, v51
	s_nop 0
	s_add_u32 s12, s12, s100
	s_addc_u32 s13, s13, s101
	global_load_dwordx4 v[84:87], v207, s[12:13]
	s_waitcnt vmcnt(15)
	v_cvt_scalef32_pk_bf16_fp4 v52, v88, 1.0
	v_cvt_scalef32_pk_bf16_fp4 v54, v88, 1.0 op_sel:[1,0,0]
	v_cvt_scalef32_pk_bf16_fp4 v56, v88, 1.0 op_sel:[0,1,0]
	v_cvt_scalef32_pk_bf16_fp4 v58, v88, 1.0 op_sel:[1,1,0]
	v_dot2_f32_bf16 v60, v52, v6, 0
	v_dot2_f32_bf16 v52, v54, v4, 0
	v_dot2_f32_bf16 v60, v56, v10, v60
	s_add_i32 s12, s28, -10
	v_dot2_f32_bf16 v52, v58, v8, v52
	v_cvt_scalef32_pk_bf16_fp4 v54, v89, 1.0
	v_cvt_scalef32_pk_bf16_fp4 v56, v89, 1.0 op_sel:[1,0,0]
	v_cvt_scalef32_pk_bf16_fp4 v58, v89, 1.0 op_sel:[0,1,0]
	v_cvt_scalef32_pk_bf16_fp4 v62, v89, 1.0 op_sel:[1,1,0]
	v_readlane_b32 s12, v46, s12
	v_dot2_f32_bf16 v60, v54, v14, v60
	v_dot2_f32_bf16 v52, v56, v12, v52
	s_lshr_b32 s12, s12, 7
	v_dot2_f32_bf16 v60, v58, v18, v60
	v_dot2_f32_bf16 v52, v62, v16, v52
	v_cvt_scalef32_pk_bf16_fp4 v54, v90, 1.0
	v_cvt_scalef32_pk_bf16_fp4 v56, v90, 1.0 op_sel:[1,0,0]
	v_cvt_scalef32_pk_bf16_fp4 v58, v90, 1.0 op_sel:[0,1,0]
	v_cvt_scalef32_pk_bf16_fp4 v62, v90, 1.0 op_sel:[1,1,0]
	s_mov_b32 s13, s86
	v_dot2_f32_bf16 v60, v54, v22, v60
	v_dot2_f32_bf16 v52, v56, v20, v52
	s_lshl_b64 s[12:13], s[12:13], 10
	v_dot2_f32_bf16 v60, v58, v26, v60
	v_dot2_f32_bf16 v52, v62, v24, v52
	v_cvt_scalef32_pk_bf16_fp4 v54, v91, 1.0
	v_cvt_scalef32_pk_bf16_fp4 v56, v91, 1.0 op_sel:[1,0,0]
	v_cvt_scalef32_pk_bf16_fp4 v58, v91, 1.0 op_sel:[0,1,0]
	v_cvt_scalef32_pk_bf16_fp4 v62, v91, 1.0 op_sel:[1,1,0]
	s_nop 0
	v_dot2_f32_bf16 v60, v54, v30, v60
	v_dot2_f32_bf16 v52, v56, v28, v52
	s_nop 0
	v_dot2_f32_bf16 v60, v58, v36, v60
	v_dot2_f32_bf16 v52, v62, v34, v52
	s_nop 2
	v_add_f32_e32 v52, v60, v52
	s_add_u32 s12, s12, s100
	s_addc_u32 s13, s13, s101
	global_load_dwordx4 v[88:91], v207, s[12:13]
	s_waitcnt vmcnt(15)
; #define P4_FOR16(M) M(0) M(1) M(2) M(3) M(4) M(5) M(6) M(7) M(8) M(9) M(10) M(11) M(12) M(13) M(14) M(15)
; #define P4_U(i) { P4_DOT(b##i, part[i]); const int nk_ = __builtin_amdgcn_readlane(ksel, nb + i); P4_LOAD(b##i, Ug, nk_); }
; #define P4_U(i) { P4_DOT(b##i, part[i]); const int nk_ = __builtin_amdgcn_readlane(kn, i); P4_LOAD(b##i, nbase, nk_); }
; __device__ __forceinline__ void peer_gather_f4p(const float* X, const int* __restrict__ IDX, const float* __restrict__ G, ...
;     ...
; #pragma unroll 1
;         for (int bt = 0; bt < 7; ++bt) {
;             const int ksel = (bt + 1 < 4) ? k0 : k1;
;             const int nb = (16 * (bt + 1)) & 63;
;     ...
;             P4_FOR16(P4_U)
;     ...
;             P4_RED(bt);
;         }
	v_cvt_scalef32_pk_bf16_fp4 v54, v92, 1.0
	v_cvt_scalef32_pk_bf16_fp4 v56, v92, 1.0 op_sel:[1,0,0]
	v_cvt_scalef32_pk_bf16_fp4 v58, v92, 1.0 op_sel:[0,1,0]
	v_cvt_scalef32_pk_bf16_fp4 v60, v92, 1.0 op_sel:[1,1,0]
	s_add_i32 s12, s28, -9
	v_dot2_f32_bf16 v53, v54, v6, 0
	v_dot2_f32_bf16 v53, v56, v4, v53
	v_dot2_f32_bf16 v53, v58, v10, v53
	v_readlane_b32 s12, v46, s12
	v_dot2_f32_bf16 v53, v60, v8, v53
	v_cvt_scalef32_pk_bf16_fp4 v56, v93, 1.0
	v_cvt_scalef32_pk_bf16_fp4 v58, v93, 1.0 op_sel:[1,0,0]
	v_cvt_scalef32_pk_bf16_fp4 v60, v93, 1.0 op_sel:[0,1,0]
	v_cvt_scalef32_pk_bf16_fp4 v80, v93, 1.0 op_sel:[1,1,0]
	s_lshr_b32 s12, s12, 7
	v_dot2_f32_bf16 v53, v56, v14, v53
	v_dot2_f32_bf16 v53, v58, v12, v53
	s_mov_b32 s13, s86
	v_dot2_f32_bf16 v53, v60, v18, v53
	v_dot2_f32_bf16 v53, v80, v16, v53
	v_cvt_scalef32_pk_bf16_fp4 v56, v94, 1.0
	v_cvt_scalef32_pk_bf16_fp4 v58, v94, 1.0 op_sel:[1,0,0]
	v_cvt_scalef32_pk_bf16_fp4 v60, v94, 1.0 op_sel:[0,1,0]
	v_cvt_scalef32_pk_bf16_fp4 v80, v94, 1.0 op_sel:[1,1,0]
	s_lshl_b64 s[12:13], s[12:13], 10
	v_dot2_f32_bf16 v53, v56, v22, v53
	v_dot2_f32_bf16 v53, v58, v20, v53
	s_nop 0
	v_dot2_f32_bf16 v53, v60, v26, v53
	v_dot2_f32_bf16 v53, v80, v24, v53
	v_cvt_scalef32_pk_bf16_fp4 v56, v95, 1.0
	v_cvt_scalef32_pk_bf16_fp4 v58, v95, 1.0 op_sel:[1,0,0]
	v_cvt_scalef32_pk_bf16_fp4 v60, v95, 1.0 op_sel:[0,1,0]
	v_cvt_scalef32_pk_bf16_fp4 v80, v95, 1.0 op_sel:[1,1,0]
	s_nop 0
	v_dot2_f32_bf16 v53, v56, v30, v53
	v_dot2_f32_bf16 v53, v58, v28, v53
	s_nop 0
	v_dot2_f32_bf16 v53, v60, v36, v53
	v_dot2_f32_bf16 v53, v80, v34, v53
	s_nop 0
	s_add_u32 s12, s12, s100
	s_addc_u32 s13, s13, s101
	global_load_dwordx4 v[92:95], v207, s[12:13]
	s_waitcnt vmcnt(15)
	v_cvt_scalef32_pk_bf16_fp4 v54, v96, 1.0
	v_cvt_scalef32_pk_bf16_fp4 v56, v96, 1.0 op_sel:[1,0,0]
	v_cvt_scalef32_pk_bf16_fp4 v58, v96, 1.0 op_sel:[0,1,0]
	v_cvt_scalef32_pk_bf16_fp4 v60, v96, 1.0 op_sel:[1,1,0]
	v_dot2_f32_bf16 v62, v54, v6, 0
	v_dot2_f32_bf16 v54, v56, v4, 0
	v_dot2_f32_bf16 v62, v58, v10, v62
	s_add_i32 s12, s28, -8
	v_dot2_f32_bf16 v54, v60, v8, v54
	v_cvt_scalef32_pk_bf16_fp4 v56, v97, 1.0
	v_cvt_scalef32_pk_bf16_fp4 v58, v97, 1.0 op_sel:[1,0,0]
	v_cvt_scalef32_pk_bf16_fp4 v60, v97, 1.0 op_sel:[0,1,0]
	v_cvt_scalef32_pk_bf16_fp4 v80, v97, 1.0 op_sel:[1,1,0]
	v_readlane_b32 s12, v46, s12
	v_dot2_f32_bf16 v62, v56, v14, v62
	v_dot2_f32_bf16 v54, v58, v12, v54
	s_lshr_b32 s12, s12, 7
	v_dot2_f32_bf16 v62, v60, v18, v62
	v_dot2_f32_bf16 v54, v80, v16, v54
	v_cvt_scalef32_pk_bf16_fp4 v56, v98, 1.0
	v_cvt_scalef32_pk_bf16_fp4 v58, v98, 1.0 op_sel:[1,0,0]
	v_cvt_scalef32_pk_bf16_fp4 v60, v98, 1.0 op_sel:[0,1,0]
	v_cvt_scalef32_pk_bf16_fp4 v80, v98, 1.0 op_sel:[1,1,0]
	s_mov_b32 s13, s86
	v_dot2_f32_bf16 v62, v56, v22, v62
	v_dot2_f32_bf16 v54, v58, v20, v54
	s_lshl_b64 s[12:13], s[12:13], 10
	v_dot2_f32_bf16 v62, v60, v26, v62
	v_dot2_f32_bf16 v54, v80, v24, v54
	v_cvt_scalef32_pk_bf16_fp4 v56, v99, 1.0
	v_cvt_scalef32_pk_bf16_fp4 v58, v99, 1.0 op_sel:[1,0,0]
	v_cvt_scalef32_pk_bf16_fp4 v60, v99, 1.0 op_sel:[0,1,0]
	v_cvt_scalef32_pk_bf16_fp4 v80, v99, 1.0 op_sel:[1,1,0]
	s_nop 0
	v_dot2_f32_bf16 v62, v56, v30, v62
	v_dot2_f32_bf16 v54, v58, v28, v54
	s_nop 0
	v_dot2_f32_bf16 v62, v60, v36, v62
	v_dot2_f32_bf16 v54, v80, v34, v54
	s_nop 2
	v_add_f32_e32 v54, v62, v54
	s_add_u32 s12, s12, s100
	s_addc_u32 s13, s13, s101
	global_load_dwordx4 v[96:99], v207, s[12:13]
	s_waitcnt vmcnt(15)
	v_cvt_scalef32_pk_bf16_fp4 v56, v100, 1.0
	v_cvt_scalef32_pk_bf16_fp4 v58, v100, 1.0 op_sel:[1,0,0]
	v_cvt_scalef32_pk_bf16_fp4 v60, v100, 1.0 op_sel:[0,1,0]
	v_cvt_scalef32_pk_bf16_fp4 v62, v100, 1.0 op_sel:[1,1,0]
	s_add_i32 s12, s28, -7
	v_dot2_f32_bf16 v55, v56, v6, 0
	v_dot2_f32_bf16 v55, v58, v4, v55
	v_dot2_f32_bf16 v55, v60, v10, v55
	v_readlane_b32 s12, v46, s12
	v_dot2_f32_bf16 v55, v62, v8, v55
	v_cvt_scalef32_pk_bf16_fp4 v58, v101, 1.0
	v_cvt_scalef32_pk_bf16_fp4 v60, v101, 1.0 op_sel:[1,0,0]
	v_cvt_scalef32_pk_bf16_fp4 v62, v101, 1.0 op_sel:[0,1,0]
	v_cvt_scalef32_pk_bf16_fp4 v82, v101, 1.0 op_sel:[1,1,0]
	s_lshr_b32 s12, s12, 7
	v_dot2_f32_bf16 v55, v58, v14, v55
	v_dot2_f32_bf16 v55, v60, v12, v55
	s_mov_b32 s13, s86
	v_dot2_f32_bf16 v55, v62, v18, v55
	v_dot2_f32_bf16 v55, v82, v16, v55
	v_cvt_scalef32_pk_bf16_fp4 v58, v102, 1.0
	v_cvt_scalef32_pk_bf16_fp4 v60, v102, 1.0 op_sel:[1,0,0]
	v_cvt_scalef32_pk_bf16_fp4 v62, v102, 1.0 op_sel:[0,1,0]
	v_cvt_scalef32_pk_bf16_fp4 v82, v102, 1.0 op_sel:[1,1,0]
	s_lshl_b64 s[12:13], s[12:13], 10
	v_dot2_f32_bf16 v55, v58, v22, v55
	v_dot2_f32_bf16 v55, v60, v20, v55
	s_nop 0
	v_dot2_f32_bf16 v55, v62, v26, v55
	v_dot2_f32_bf16 v55, v82, v24, v55
	v_cvt_scalef32_pk_bf16_fp4 v58, v103, 1.0
	v_cvt_scalef32_pk_bf16_fp4 v60, v103, 1.0 op_sel:[1,0,0]
	v_cvt_scalef32_pk_bf16_fp4 v62, v103, 1.0 op_sel:[0,1,0]
	v_cvt_scalef32_pk_bf16_fp4 v82, v103, 1.0 op_sel:[1,1,0]
	s_nop 0
	v_dot2_f32_bf16 v55, v58, v30, v55
	v_dot2_f32_bf16 v55, v60, v28, v55
	s_nop 0
	v_dot2_f32_bf16 v55, v62, v36, v55
	v_dot2_f32_bf16 v55, v82, v34, v55
	s_nop 0
	s_add_u32 s12, s12, s100
	s_addc_u32 s13, s13, s101
	global_load_dwordx4 v[100:103], v207, s[12:13]
	s_waitcnt vmcnt(15)
; #define P4_FOR16(M) M(0) M(1) M(2) M(3) M(4) M(5) M(6) M(7) M(8) M(9) M(10) M(11) M(12) M(13) M(14) M(15)
; #define P4_U(i) { P4_DOT(b##i, part[i]); const int nk_ = __builtin_amdgcn_readlane(ksel, nb + i); P4_LOAD(b##i, Ug, nk_); }
; #define P4_U(i) { P4_DOT(b##i, part[i]); const int nk_ = __builtin_amdgcn_readlane(kn, i); P4_LOAD(b##i, nbase, nk_); }
; __device__ __forceinline__ void peer_gather_f4p(const float* X, const int* __restrict__ IDX, const float* __restrict__ G, ...
;     ...
; #pragma unroll 1
;         for (int bt = 0; bt < 7; ++bt) {
;             const int ksel = (bt + 1 < 4) ? k0 : k1;
;             const int nb = (16 * (bt + 1)) & 63;
;     ...
;             P4_FOR16(P4_U)
;     ...
;             P4_RED(bt);
;         }
	v_cvt_scalef32_pk_bf16_fp4 v56, v104, 1.0
	v_cvt_scalef32_pk_bf16_fp4 v58, v104, 1.0 op_sel:[1,0,0]
	v_cvt_scalef32_pk_bf16_fp4 v60, v104, 1.0 op_sel:[0,1,0]
	v_cvt_scalef32_pk_bf16_fp4 v62, v104, 1.0 op_sel:[1,1,0]
	v_dot2_f32_bf16 v80, v56, v6, 0
	v_dot2_f32_bf16 v56, v58, v4, 0
	v_dot2_f32_bf16 v80, v60, v10, v80
	s_add_i32 s12, s28, -6
	v_dot2_f32_bf16 v56, v62, v8, v56
	v_cvt_scalef32_pk_bf16_fp4 v58, v105, 1.0
	v_cvt_scalef32_pk_bf16_fp4 v60, v105, 1.0 op_sel:[1,0,0]
	v_cvt_scalef32_pk_bf16_fp4 v62, v105, 1.0 op_sel:[0,1,0]
	v_cvt_scalef32_pk_bf16_fp4 v82, v105, 1.0 op_sel:[1,1,0]
	v_readlane_b32 s12, v46, s12
	v_dot2_f32_bf16 v80, v58, v14, v80
	v_dot2_f32_bf16 v56, v60, v12, v56
	s_lshr_b32 s12, s12, 7
	v_dot2_f32_bf16 v80, v62, v18, v80
	v_dot2_f32_bf16 v56, v82, v16, v56
	v_cvt_scalef32_pk_bf16_fp4 v58, v106, 1.0
	v_cvt_scalef32_pk_bf16_fp4 v60, v106, 1.0 op_sel:[1,0,0]
	v_cvt_scalef32_pk_bf16_fp4 v62, v106, 1.0 op_sel:[0,1,0]
	v_cvt_scalef32_pk_bf16_fp4 v82, v106, 1.0 op_sel:[1,1,0]
	s_mov_b32 s13, s86
	v_dot2_f32_bf16 v80, v58, v22, v80
	v_dot2_f32_bf16 v56, v60, v20, v56
	s_lshl_b64 s[12:13], s[12:13], 10
	v_dot2_f32_bf16 v80, v62, v26, v80
	v_dot2_f32_bf16 v56, v82, v24, v56
	v_cvt_scalef32_pk_bf16_fp4 v58, v107, 1.0
	v_cvt_scalef32_pk_bf16_fp4 v60, v107, 1.0 op_sel:[1,0,0]
	v_cvt_scalef32_pk_bf16_fp4 v62, v107, 1.0 op_sel:[0,1,0]
	v_cvt_scalef32_pk_bf16_fp4 v82, v107, 1.0 op_sel:[1,1,0]
	s_nop 0
	v_dot2_f32_bf16 v80, v58, v30, v80
	v_dot2_f32_bf16 v56, v60, v28, v56
	s_nop 0
	v_dot2_f32_bf16 v80, v62, v36, v80
	v_dot2_f32_bf16 v56, v82, v34, v56
	s_nop 2
	v_add_f32_e32 v56, v80, v56
	s_add_u32 s12, s12, s100
	s_addc_u32 s13, s13, s101
	global_load_dwordx4 v[104:107], v207, s[12:13]
	s_waitcnt vmcnt(15)
	v_cvt_scalef32_pk_bf16_fp4 v58, v108, 1.0
	v_cvt_scalef32_pk_bf16_fp4 v60, v108, 1.0 op_sel:[1,0,0]
	v_cvt_scalef32_pk_bf16_fp4 v62, v108, 1.0 op_sel:[0,1,0]
	v_cvt_scalef32_pk_bf16_fp4 v80, v108, 1.0 op_sel:[1,1,0]
	s_add_i32 s12, s28, -5
	v_dot2_f32_bf16 v57, v58, v6, 0
	v_dot2_f32_bf16 v57, v60, v4, v57
	v_dot2_f32_bf16 v57, v62, v10, v57
	v_readlane_b32 s12, v46, s12
	v_dot2_f32_bf16 v57, v80, v8, v57
	v_cvt_scalef32_pk_bf16_fp4 v60, v109, 1.0
	v_cvt_scalef32_pk_bf16_fp4 v62, v109, 1.0 op_sel:[1,0,0]
	v_cvt_scalef32_pk_bf16_fp4 v80, v109, 1.0 op_sel:[0,1,0]
	v_cvt_scalef32_pk_bf16_fp4 v108, v109, 1.0 op_sel:[1,1,0]
	s_lshr_b32 s12, s12, 7
	v_dot2_f32_bf16 v57, v60, v14, v57
	v_dot2_f32_bf16 v57, v62, v12, v57
	s_mov_b32 s13, s86
	v_dot2_f32_bf16 v57, v80, v18, v57
	v_dot2_f32_bf16 v57, v108, v16, v57
	v_cvt_scalef32_pk_bf16_fp4 v60, v110, 1.0
	v_cvt_scalef32_pk_bf16_fp4 v62, v110, 1.0 op_sel:[1,0,0]
	v_cvt_scalef32_pk_bf16_fp4 v80, v110, 1.0 op_sel:[0,1,0]
	v_cvt_scalef32_pk_bf16_fp4 v108, v110, 1.0 op_sel:[1,1,0]
	s_lshl_b64 s[12:13], s[12:13], 10
	v_dot2_f32_bf16 v57, v60, v22, v57
	v_dot2_f32_bf16 v57, v62, v20, v57
	s_nop 0
	v_dot2_f32_bf16 v57, v80, v26, v57
	v_dot2_f32_bf16 v57, v108, v24, v57
	v_cvt_scalef32_pk_bf16_fp4 v60, v111, 1.0
	v_cvt_scalef32_pk_bf16_fp4 v62, v111, 1.0 op_sel:[1,0,0]
	v_cvt_scalef32_pk_bf16_fp4 v80, v111, 1.0 op_sel:[0,1,0]
	v_cvt_scalef32_pk_bf16_fp4 v108, v111, 1.0 op_sel:[1,1,0]
	s_nop 0
	v_dot2_f32_bf16 v57, v60, v30, v57
	v_dot2_f32_bf16 v57, v62, v28, v57
	s_nop 0
	v_dot2_f32_bf16 v57, v80, v36, v57
	v_dot2_f32_bf16 v57, v108, v34, v57
	s_nop 0
	s_add_u32 s12, s12, s100
	s_addc_u32 s13, s13, s101
	global_load_dwordx4 v[108:111], v207, s[12:13]
	s_waitcnt vmcnt(15)
	v_cvt_scalef32_pk_bf16_fp4 v58, v112, 1.0
	v_cvt_scalef32_pk_bf16_fp4 v60, v112, 1.0 op_sel:[1,0,0]
	v_cvt_scalef32_pk_bf16_fp4 v62, v112, 1.0 op_sel:[0,1,0]
	v_cvt_scalef32_pk_bf16_fp4 v80, v112, 1.0 op_sel:[1,1,0]
	v_dot2_f32_bf16 v132, v58, v6, 0
	v_dot2_f32_bf16 v132, v60, v4, v132
	v_dot2_f32_bf16 v132, v62, v10, v132
	s_add_i32 s12, s28, -4
	v_dot2_f32_bf16 v132, v80, v8, v132
	v_cvt_scalef32_pk_bf16_fp4 v60, v113, 1.0
	v_cvt_scalef32_pk_bf16_fp4 v62, v113, 1.0 op_sel:[1,0,0]
	v_cvt_scalef32_pk_bf16_fp4 v80, v113, 1.0 op_sel:[0,1,0]
	v_cvt_scalef32_pk_bf16_fp4 v112, v113, 1.0 op_sel:[1,1,0]
	v_readlane_b32 s12, v46, s12
	v_dot2_f32_bf16 v132, v60, v14, v132
	v_dot2_f32_bf16 v132, v62, v12, v132
	s_lshr_b32 s12, s12, 7
	v_dot2_f32_bf16 v132, v80, v18, v132
	v_dot2_f32_bf16 v132, v112, v16, v132
	v_cvt_scalef32_pk_bf16_fp4 v60, v114, 1.0
	v_cvt_scalef32_pk_bf16_fp4 v62, v114, 1.0 op_sel:[1,0,0]
	v_cvt_scalef32_pk_bf16_fp4 v80, v114, 1.0 op_sel:[0,1,0]
	v_cvt_scalef32_pk_bf16_fp4 v112, v114, 1.0 op_sel:[1,1,0]
	s_mov_b32 s13, s86
	v_dot2_f32_bf16 v132, v60, v22, v132
	v_dot2_f32_bf16 v132, v62, v20, v132
	s_lshl_b64 s[12:13], s[12:13], 10
	v_dot2_f32_bf16 v132, v80, v26, v132
	v_dot2_f32_bf16 v132, v112, v24, v132
	v_cvt_scalef32_pk_bf16_fp4 v60, v115, 1.0
	v_cvt_scalef32_pk_bf16_fp4 v62, v115, 1.0 op_sel:[1,0,0]
	v_cvt_scalef32_pk_bf16_fp4 v80, v115, 1.0 op_sel:[0,1,0]
	v_cvt_scalef32_pk_bf16_fp4 v112, v115, 1.0 op_sel:[1,1,0]
	s_nop 0
	v_dot2_f32_bf16 v132, v60, v30, v132
	v_dot2_f32_bf16 v132, v62, v28, v132
	s_nop 0
	v_dot2_f32_bf16 v132, v80, v36, v132
	v_dot2_f32_bf16 v132, v112, v34, v132
	s_nop 0
	s_add_u32 s12, s12, s100
	s_addc_u32 s13, s13, s101
	global_load_dwordx4 v[112:115], v207, s[12:13]
	s_waitcnt vmcnt(15)
; #define P4_FOR16(M) M(0) M(1) M(2) M(3) M(4) M(5) M(6) M(7) M(8) M(9) M(10) M(11) M(12) M(13) M(14) M(15)
; #define P4_U(i) { P4_DOT(b##i, part[i]); const int nk_ = __builtin_amdgcn_readlane(ksel, nb + i); P4_LOAD(b##i, Ug, nk_); }
; #define P4_U(i) { P4_DOT(b##i, part[i]); const int nk_ = __builtin_amdgcn_readlane(kn, i); P4_LOAD(b##i, nbase, nk_); }
; __device__ __forceinline__ void peer_gather_f4p(const float* X, const int* __restrict__ IDX, const float* __restrict__ G, ...
;     ...
; #pragma unroll 1
;         for (int bt = 0; bt < 7; ++bt) {
;             const int ksel = (bt + 1 < 4) ? k0 : k1;
;             const int nb = (16 * (bt + 1)) & 63;
;     ...
;             P4_FOR16(P4_U)
;     ...
;             P4_RED(bt);
;         }
	v_cvt_scalef32_pk_bf16_fp4 v58, v116, 1.0
	v_cvt_scalef32_pk_bf16_fp4 v60, v116, 1.0 op_sel:[1,0,0]
	v_cvt_scalef32_pk_bf16_fp4 v62, v116, 1.0 op_sel:[0,1,0]
	v_cvt_scalef32_pk_bf16_fp4 v80, v116, 1.0 op_sel:[1,1,0]
	v_dot2_f32_bf16 v133, v58, v6, 0
	v_dot2_f32_bf16 v133, v60, v4, v133
	v_dot2_f32_bf16 v133, v62, v10, v133
	s_add_i32 s12, s28, -3
	v_dot2_f32_bf16 v133, v80, v8, v133
	v_cvt_scalef32_pk_bf16_fp4 v60, v117, 1.0
	v_cvt_scalef32_pk_bf16_fp4 v62, v117, 1.0 op_sel:[1,0,0]
	v_cvt_scalef32_pk_bf16_fp4 v80, v117, 1.0 op_sel:[0,1,0]
	v_cvt_scalef32_pk_bf16_fp4 v116, v117, 1.0 op_sel:[1,1,0]
	v_readlane_b32 s12, v46, s12
	v_dot2_f32_bf16 v133, v60, v14, v133
	v_dot2_f32_bf16 v133, v62, v12, v133
	s_lshr_b32 s12, s12, 7
	v_dot2_f32_bf16 v133, v80, v18, v133
	v_dot2_f32_bf16 v133, v116, v16, v133
	v_cvt_scalef32_pk_bf16_fp4 v60, v118, 1.0
	v_cvt_scalef32_pk_bf16_fp4 v62, v118, 1.0 op_sel:[1,0,0]
	v_cvt_scalef32_pk_bf16_fp4 v80, v118, 1.0 op_sel:[0,1,0]
	v_cvt_scalef32_pk_bf16_fp4 v116, v118, 1.0 op_sel:[1,1,0]
	s_mov_b32 s13, s86
	v_dot2_f32_bf16 v133, v60, v22, v133
	v_dot2_f32_bf16 v133, v62, v20, v133
	s_lshl_b64 s[12:13], s[12:13], 10
	v_dot2_f32_bf16 v133, v80, v26, v133
	v_dot2_f32_bf16 v133, v116, v24, v133
	v_cvt_scalef32_pk_bf16_fp4 v60, v119, 1.0
	v_cvt_scalef32_pk_bf16_fp4 v62, v119, 1.0 op_sel:[1,0,0]
	v_cvt_scalef32_pk_bf16_fp4 v80, v119, 1.0 op_sel:[0,1,0]
	v_cvt_scalef32_pk_bf16_fp4 v116, v119, 1.0 op_sel:[1,1,0]
	s_nop 0
	v_dot2_f32_bf16 v133, v60, v30, v133
	v_dot2_f32_bf16 v133, v62, v28, v133
	s_nop 0
	v_dot2_f32_bf16 v133, v80, v36, v133
	v_dot2_f32_bf16 v133, v116, v34, v133
	s_nop 0
	s_add_u32 s12, s12, s100
	s_addc_u32 s13, s13, s101
	global_load_dwordx4 v[116:119], v207, s[12:13]
	s_waitcnt vmcnt(15)
	v_cvt_scalef32_pk_bf16_fp4 v58, v120, 1.0
	v_cvt_scalef32_pk_bf16_fp4 v60, v120, 1.0 op_sel:[1,0,0]
	v_cvt_scalef32_pk_bf16_fp4 v62, v120, 1.0 op_sel:[0,1,0]
	v_cvt_scalef32_pk_bf16_fp4 v80, v120, 1.0 op_sel:[1,1,0]
	v_dot2_f32_bf16 v134, v58, v6, 0
	v_dot2_f32_bf16 v134, v60, v4, v134
	v_dot2_f32_bf16 v134, v62, v10, v134
	s_add_i32 s12, s28, -2
	v_dot2_f32_bf16 v134, v80, v8, v134
	v_cvt_scalef32_pk_bf16_fp4 v60, v121, 1.0
	v_cvt_scalef32_pk_bf16_fp4 v62, v121, 1.0 op_sel:[1,0,0]
	v_cvt_scalef32_pk_bf16_fp4 v80, v121, 1.0 op_sel:[0,1,0]
	v_cvt_scalef32_pk_bf16_fp4 v120, v121, 1.0 op_sel:[1,1,0]
	v_readlane_b32 s12, v46, s12
	v_dot2_f32_bf16 v134, v60, v14, v134
	v_dot2_f32_bf16 v134, v62, v12, v134
	s_lshr_b32 s12, s12, 7
	v_dot2_f32_bf16 v134, v80, v18, v134
	v_dot2_f32_bf16 v134, v120, v16, v134
	v_cvt_scalef32_pk_bf16_fp4 v60, v122, 1.0
	v_cvt_scalef32_pk_bf16_fp4 v62, v122, 1.0 op_sel:[1,0,0]
	v_cvt_scalef32_pk_bf16_fp4 v80, v122, 1.0 op_sel:[0,1,0]
	v_cvt_scalef32_pk_bf16_fp4 v120, v122, 1.0 op_sel:[1,1,0]
	s_mov_b32 s13, s86
	v_dot2_f32_bf16 v134, v60, v22, v134
	v_dot2_f32_bf16 v134, v62, v20, v134
	s_lshl_b64 s[12:13], s[12:13], 10
	v_dot2_f32_bf16 v134, v80, v26, v134
	v_dot2_f32_bf16 v134, v120, v24, v134
	v_cvt_scalef32_pk_bf16_fp4 v60, v123, 1.0
	v_cvt_scalef32_pk_bf16_fp4 v62, v123, 1.0 op_sel:[1,0,0]
	v_cvt_scalef32_pk_bf16_fp4 v80, v123, 1.0 op_sel:[0,1,0]
	v_cvt_scalef32_pk_bf16_fp4 v120, v123, 1.0 op_sel:[1,1,0]
	s_nop 0
	v_dot2_f32_bf16 v134, v60, v30, v134
	v_dot2_f32_bf16 v134, v62, v28, v134
	s_nop 0
	v_dot2_f32_bf16 v134, v80, v36, v134
	v_dot2_f32_bf16 v134, v120, v34, v134
	s_nop 0
	s_add_u32 s12, s12, s100
	s_addc_u32 s13, s13, s101
	global_load_dwordx4 v[120:123], v207, s[12:13]
	s_waitcnt vmcnt(15)
	v_cvt_scalef32_pk_bf16_fp4 v58, v124, 1.0
	v_cvt_scalef32_pk_bf16_fp4 v60, v124, 1.0 op_sel:[1,0,0]
	v_cvt_scalef32_pk_bf16_fp4 v62, v124, 1.0 op_sel:[0,1,0]
	v_cvt_scalef32_pk_bf16_fp4 v80, v124, 1.0 op_sel:[1,1,0]
	v_dot2_f32_bf16 v135, v58, v6, 0
	v_dot2_f32_bf16 v135, v60, v4, v135
	v_dot2_f32_bf16 v135, v62, v10, v135
	s_add_i32 s12, s28, -1
	v_dot2_f32_bf16 v135, v80, v8, v135
	v_cvt_scalef32_pk_bf16_fp4 v60, v125, 1.0
	v_cvt_scalef32_pk_bf16_fp4 v62, v125, 1.0 op_sel:[1,0,0]
	v_cvt_scalef32_pk_bf16_fp4 v80, v125, 1.0 op_sel:[0,1,0]
	v_cvt_scalef32_pk_bf16_fp4 v124, v125, 1.0 op_sel:[1,1,0]
	v_readlane_b32 s12, v46, s12
	v_dot2_f32_bf16 v135, v60, v14, v135
	v_dot2_f32_bf16 v135, v62, v12, v135
	s_lshr_b32 s12, s12, 7
	v_dot2_f32_bf16 v135, v80, v18, v135
	v_dot2_f32_bf16 v135, v124, v16, v135
	v_cvt_scalef32_pk_bf16_fp4 v60, v126, 1.0
	v_cvt_scalef32_pk_bf16_fp4 v62, v126, 1.0 op_sel:[1,0,0]
	v_cvt_scalef32_pk_bf16_fp4 v80, v126, 1.0 op_sel:[0,1,0]
	v_cvt_scalef32_pk_bf16_fp4 v124, v126, 1.0 op_sel:[1,1,0]
	s_mov_b32 s13, s86
	v_dot2_f32_bf16 v135, v60, v22, v135
	v_dot2_f32_bf16 v135, v62, v20, v135
	s_lshl_b64 s[12:13], s[12:13], 10
	v_dot2_f32_bf16 v135, v80, v26, v135
	v_dot2_f32_bf16 v135, v124, v24, v135
	v_cvt_scalef32_pk_bf16_fp4 v60, v127, 1.0
	v_cvt_scalef32_pk_bf16_fp4 v62, v127, 1.0 op_sel:[1,0,0]
	v_cvt_scalef32_pk_bf16_fp4 v80, v127, 1.0 op_sel:[0,1,0]
	v_cvt_scalef32_pk_bf16_fp4 v124, v127, 1.0 op_sel:[1,1,0]
	s_nop 0
	v_dot2_f32_bf16 v135, v60, v30, v135
	v_dot2_f32_bf16 v135, v62, v28, v135
	s_nop 0
	v_dot2_f32_bf16 v135, v80, v36, v135
	v_dot2_f32_bf16 v135, v124, v34, v135
	s_nop 0
	s_add_u32 s12, s12, s100
	s_addc_u32 s13, s13, s101
	global_load_dwordx4 v[124:127], v207, s[12:13]
	s_waitcnt vmcnt(15)
; __device__ __forceinline__ float gelu_tanh(float h) {
;     return 0.5f * h * (1.f + tanhf(0.7978845608028654f * (h + 0.044715f * h * h * h)));
; }
	v_cvt_scalef32_pk_bf16_fp4 v58, v128, 1.0
	v_cvt_scalef32_pk_bf16_fp4 v60, v128, 1.0 op_sel:[1,0,0]
	v_cvt_scalef32_pk_bf16_fp4 v62, v128, 1.0 op_sel:[0,1,0]
	v_cvt_scalef32_pk_bf16_fp4 v80, v128, 1.0 op_sel:[1,1,0]
	v_readlane_b32 s12, v46, s28
	v_dot2_f32_bf16 v82, v58, v6, 0
	v_dot2c_f32_bf16_e32 v42, v60, v4
	s_lshr_b32 s12, s12, 7
	v_dot2_f32_bf16 v82, v62, v10, v82
	v_dot2c_f32_bf16_e32 v42, v80, v8
	v_cvt_scalef32_pk_bf16_fp4 v58, v129, 1.0
	v_cvt_scalef32_pk_bf16_fp4 v60, v129, 1.0 op_sel:[1,0,0]
	v_cvt_scalef32_pk_bf16_fp4 v62, v129, 1.0 op_sel:[0,1,0]
	v_cvt_scalef32_pk_bf16_fp4 v80, v129, 1.0 op_sel:[1,1,0]
	s_mov_b32 s13, s86
	v_dot2_f32_bf16 v82, v58, v14, v82
	v_dot2c_f32_bf16_e32 v42, v60, v12
	s_lshl_b64 s[12:13], s[12:13], 10
	v_dot2_f32_bf16 v82, v62, v18, v82
	v_dot2c_f32_bf16_e32 v42, v80, v16
	v_cvt_scalef32_pk_bf16_fp4 v58, v130, 1.0
	v_cvt_scalef32_pk_bf16_fp4 v60, v130, 1.0 op_sel:[1,0,0]
	v_cvt_scalef32_pk_bf16_fp4 v62, v130, 1.0 op_sel:[0,1,0]
	v_cvt_scalef32_pk_bf16_fp4 v80, v130, 1.0 op_sel:[1,1,0]
	v_cndmask_b32_e64 v46, v48, v56, s[46:47]
	v_dot2_f32_bf16 v82, v58, v22, v82
	v_dot2c_f32_bf16_e32 v42, v60, v20
	ds_swizzle_b32 v46, v46 offset:swizzle(SWAP,8)
	v_dot2_f32_bf16 v82, v62, v26, v82
	v_dot2c_f32_bf16_e32 v42, v80, v24
	v_cvt_scalef32_pk_bf16_fp4 v58, v131, 1.0
	v_cvt_scalef32_pk_bf16_fp4 v60, v131, 1.0 op_sel:[1,0,0]
	v_cvt_scalef32_pk_bf16_fp4 v62, v131, 1.0 op_sel:[0,1,0]
	v_cvt_scalef32_pk_bf16_fp4 v80, v131, 1.0 op_sel:[1,1,0]
	s_nop 0
	v_dot2_f32_bf16 v82, v58, v30, v82
	v_dot2c_f32_bf16_e32 v42, v60, v28
	s_nop 0
	v_dot2_f32_bf16 v82, v62, v36, v82
	v_dot2c_f32_bf16_e32 v42, v80, v34
	s_nop 0
	s_nop 2
	v_add_f32_e32 v58, v82, v42
	v_lshl_add_u64 v[42:43], v[40:41], 0, s[12:13]
	global_load_dwordx4 v[128:131], v[42:43], off
	v_cndmask_b32_e64 v43, v47, v55, s[46:47]
	ds_swizzle_b32 v43, v43 offset:swizzle(SWAP,8)
	v_cndmask_b32_e64 v42, v55, v47, s[46:47]
	v_cndmask_b32_e64 v47, v49, v57, s[46:47]
	ds_swizzle_b32 v47, v47 offset:swizzle(SWAP,8)
	s_waitcnt lgkmcnt(1)
	v_add_f32_e32 v42, v42, v43
	v_cndmask_b32_e64 v43, v56, v48, s[46:47]
	v_cndmask_b32_e64 v48, v50, v132, s[46:47]
	v_add_f32_e32 v43, v43, v46
	v_cndmask_b32_e64 v46, v57, v49, s[46:47]
	ds_swizzle_b32 v48, v48 offset:swizzle(SWAP,8)
	v_cndmask_b32_e64 v49, v51, v133, s[46:47]
	ds_swizzle_b32 v49, v49 offset:swizzle(SWAP,8)
	s_waitcnt lgkmcnt(2)
	v_add_f32_e32 v46, v46, v47
	v_cndmask_b32_e64 v47, v132, v50, s[46:47]
	v_cndmask_b32_e64 v50, v52, v134, s[46:47]
	ds_swizzle_b32 v50, v50 offset:swizzle(SWAP,8)
	s_waitcnt lgkmcnt(2)
	v_add_f32_e32 v47, v47, v48
	v_cndmask_b32_e64 v48, v133, v51, s[46:47]
	v_cndmask_b32_e64 v51, v53, v135, s[46:47]
	s_waitcnt lgkmcnt(1)
	v_add_f32_e32 v48, v48, v49
	v_cndmask_b32_e64 v49, v134, v52, s[46:47]
	ds_swizzle_b32 v51, v51 offset:swizzle(SWAP,8)
	v_cndmask_b32_e64 v52, v54, v58, s[46:47]
	ds_swizzle_b32 v52, v52 offset:swizzle(SWAP,8)
	s_waitcnt lgkmcnt(2)
	v_add_f32_e32 v49, v49, v50
	v_cndmask_b32_e64 v50, v135, v53, s[46:47]
	s_waitcnt lgkmcnt(1)
	v_add_f32_e32 v50, v50, v51
	v_cndmask_b32_e64 v51, v58, v54, s[46:47]
	s_waitcnt lgkmcnt(0)
	v_add_f32_e32 v51, v51, v52
	v_cndmask_b32_e64 v53, v42, v48, s[44:45]
	v_cndmask_b32_e64 v42, v48, v42, s[44:45]
	v_cndmask_b32_e64 v48, v49, v43, s[44:45]
	v_cndmask_b32_e64 v43, v43, v49, s[44:45]
	v_cndmask_b32_e64 v49, v46, v50, s[44:45]
	v_cndmask_b32_e64 v52, v47, v51, s[44:45]
	ds_swizzle_b32 v53, v53 offset:swizzle(SWAP,4)
	ds_swizzle_b32 v43, v43 offset:swizzle(SWAP,4)
	ds_swizzle_b32 v49, v49 offset:swizzle(SWAP,4)
	ds_swizzle_b32 v52, v52 offset:swizzle(SWAP,4)
	v_cndmask_b32_e64 v46, v50, v46, s[44:45]
	v_cndmask_b32_e64 v47, v51, v47, s[44:45]
	s_waitcnt lgkmcnt(3)
	v_add_f32_e32 v42, v42, v53
	s_waitcnt lgkmcnt(2)
	v_add_f32_e32 v43, v48, v43
	s_waitcnt lgkmcnt(1)
	v_add_f32_e32 v46, v46, v49
	s_waitcnt lgkmcnt(0)
	v_add_f32_e32 v47, v47, v52
	v_cndmask_b32_e64 v48, v42, v46, s[42:43]
	v_cndmask_b32_e64 v49, v43, v47, s[42:43]
	ds_swizzle_b32 v48, v48 offset:swizzle(SWAP,2)
	ds_swizzle_b32 v49, v49 offset:swizzle(SWAP,2)
	v_cndmask_b32_e64 v42, v46, v42, s[42:43]
	v_cndmask_b32_e64 v43, v47, v43, s[42:43]
	s_waitcnt lgkmcnt(1)
	v_add_f32_e32 v42, v42, v48
	s_waitcnt lgkmcnt(0)
	v_add_f32_e32 v43, v43, v49
	v_cndmask_b32_e64 v46, v42, v43, s[40:41]
	ds_swizzle_b32 v46, v46 offset:swizzle(SWAP,1)
	v_cndmask_b32_e64 v42, v43, v42, s[40:41]
	s_waitcnt lgkmcnt(0)
	v_add_f32_e32 v42, v42, v46
	ds_swizzle_b32 v43, v42 offset:swizzle(SWAP,16)
	s_waitcnt lgkmcnt(0)
	v_add_f32_e32 v46, v42, v43
	ds_read2st64_b32 v[42:43], v45 offset1:8
	v_mov_b32_e32 v47, v46
	s_nop 1
	v_permlane32_swap_b32_e32 v46, v47
	v_add_f32_e32 v46, v46, v47
	s_waitcnt lgkmcnt(0)
	v_mul_f32_e32 v42, v42, v46
	v_mul_f32_e32 v46, 0x3d372713, v42
	v_mul_f32_e32 v46, v42, v46
	v_fma_f32 v46, v42, v46, v42
	v_mul_f32_e32 v46, 0x3f4c422a, v46
	v_cmp_nlt_f32_e64 s[12:13], |v46|, s25
	s_and_saveexec_b64 s[48:49], s[12:13]
	s_xor_b64 s[12:13], exec, s[48:49]
	s_cbranch_execz .LBB0_1233
	v_add_f32_e64 v47, |v46|, |v46|
	v_mul_f32_e32 v48, 0x3fb8aa3b, v47
	v_rndne_f32_e32 v49, v48
	v_sub_f32_e32 v50, v48, v49
	v_fma_f32 v48, v47, s70, -v48
	v_fmac_f32_e32 v48, 0x32a5705f, v47
	v_add_f32_e32 v48, v50, v48
	v_cvt_i32_f32_e32 v49, v49
	v_exp_f32_e32 v48, v48
	v_cmp_ngt_f32_e64 s[48:49], s67, v47
	v_ldexp_f32 v48, v48, v49
	s_nop 0
	v_cndmask_b32_e64 v48, 0, v48, s[48:49]
	v_cmp_nlt_f32_e64 s[48:49], s68, v47
	s_nop 1
	v_cndmask_b32_e64 v47, v205, v48, s[48:49]
	v_add_f32_e32 v47, 1.0, v47
	v_rcp_f32_e32 v47, v47
	s_nop 0
	v_fma_f32 v47, v47, -2.0, 1.0
	s_andn2_saveexec_b64 s[12:13], s[12:13]
	s_cbranch_execnz .LBB0_1234

; #define P4_FOR16(M) M(0) M(1) M(2) M(3) M(4) M(5) M(6) M(7) M(8) M(9) M(10) M(11) M(12) M(13) M(14) M(15)
; #define P4_U(i) { P4_DOT(b##i, part[i]); const int nk_ = __builtin_amdgcn_readlane(ksel, nb + i); P4_LOAD(b##i, Ug, nk_); }
; #define P4_U(i) { P4_DOT(b##i, part[i]); const int nk_ = __builtin_amdgcn_readlane(kn, i); P4_LOAD(b##i, nbase, nk_); }
; __device__ __forceinline__ void peer_gather_f4p(const float* X, const int* __restrict__ IDX, const float* __restrict__ G, ...
;     ...
; #pragma unroll 1
;         for (int bt = 0; bt < 7; ++bt) {
;             const int ksel = (bt + 1 < 4) ? k0 : k1;
;             const int nb = (16 * (bt + 1)) & 63;
;     ...
;             P4_FOR16(P4_U)
;     ...
;             P4_RED(bt);
;         }
.LBB0_1236:
	s_mov_b32 s87, s86
	s_waitcnt vmcnt(15)
	v_cvt_scalef32_pk_bf16_fp4 v42, v64, 1.0
	v_or_b32_e32 v40, s27, v44
	v_cvt_scalef32_pk_bf16_fp4 v44, v64, 1.0 op_sel:[1,0,0]
	v_cvt_scalef32_pk_bf16_fp4 v46, v64, 1.0 op_sel:[0,1,0]
	v_cvt_scalef32_pk_bf16_fp4 v48, v64, 1.0 op_sel:[1,1,0]
	v_dot2_f32_bf16 v41, v42, v6, 0
	v_dot2_f32_bf16 v41, v44, v4, v41
	v_dot2_f32_bf16 v41, v46, v10, v41
	s_cmp_eq_u32 s26, 3
	v_dot2_f32_bf16 v41, v48, v8, v41
	v_cvt_scalef32_pk_bf16_fp4 v44, v65, 1.0
	v_cvt_scalef32_pk_bf16_fp4 v46, v65, 1.0 op_sel:[1,0,0]
	v_cvt_scalef32_pk_bf16_fp4 v48, v65, 1.0 op_sel:[0,1,0]
	v_cvt_scalef32_pk_bf16_fp4 v52, v65, 1.0 op_sel:[1,1,0]
	v_readlane_b32 s26, v2, 0
	v_dot2_f32_bf16 v41, v44, v14, v41
	v_dot2_f32_bf16 v41, v46, v12, v41
	s_cselect_b32 s12, s53, s51
	v_dot2_f32_bf16 v41, v48, v18, v41
	v_dot2_f32_bf16 v41, v52, v16, v41
	v_cvt_scalef32_pk_bf16_fp4 v44, v66, 1.0
	v_cvt_scalef32_pk_bf16_fp4 v46, v66, 1.0 op_sel:[1,0,0]
	v_cvt_scalef32_pk_bf16_fp4 v48, v66, 1.0 op_sel:[0,1,0]
	v_cvt_scalef32_pk_bf16_fp4 v52, v66, 1.0 op_sel:[1,1,0]
	s_cselect_b32 s13, s52, s50
	v_dot2_f32_bf16 v41, v44, v22, v41
	v_dot2_f32_bf16 v41, v46, v20, v41
	s_lshr_b32 s26, s26, 7
	v_dot2_f32_bf16 v41, v48, v26, v41
	v_dot2_f32_bf16 v41, v52, v24, v41
	s_mov_b32 s27, s86
	v_cvt_scalef32_pk_bf16_fp4 v44, v67, 1.0
	v_cvt_scalef32_pk_bf16_fp4 v46, v67, 1.0 op_sel:[1,0,0]
	v_cvt_scalef32_pk_bf16_fp4 v48, v67, 1.0 op_sel:[0,1,0]
	v_cvt_scalef32_pk_bf16_fp4 v52, v67, 1.0 op_sel:[1,1,0]
	s_lshl_b64 s[26:27], s[26:27], 10
	v_dot2_f32_bf16 v41, v44, v30, v41
	v_dot2_f32_bf16 v41, v46, v28, v41
	s_add_u32 s26, s13, s26
	v_dot2_f32_bf16 v41, v48, v36, v41
	v_dot2_f32_bf16 v41, v52, v34, v41
	s_addc_u32 s27, s12, s27
	global_load_dwordx4 v[64:67], v32, s[26:27]
	s_waitcnt vmcnt(15)
	v_cvt_scalef32_pk_bf16_fp4 v42, v68, 1.0
	v_cvt_scalef32_pk_bf16_fp4 v44, v68, 1.0 op_sel:[1,0,0]
	v_cvt_scalef32_pk_bf16_fp4 v46, v68, 1.0 op_sel:[0,1,0]
	v_cvt_scalef32_pk_bf16_fp4 v48, v68, 1.0 op_sel:[1,1,0]
	v_dot2_f32_bf16 v50, v42, v6, 0
	v_dot2_f32_bf16 v42, v44, v4, 0
	v_dot2_f32_bf16 v50, v46, v10, v50
	v_readlane_b32 s26, v2, 1
	v_dot2_f32_bf16 v42, v48, v8, v42
	v_cvt_scalef32_pk_bf16_fp4 v44, v69, 1.0
	v_cvt_scalef32_pk_bf16_fp4 v46, v69, 1.0 op_sel:[1,0,0]
	v_cvt_scalef32_pk_bf16_fp4 v48, v69, 1.0 op_sel:[0,1,0]
	v_cvt_scalef32_pk_bf16_fp4 v52, v69, 1.0 op_sel:[1,1,0]
	s_lshr_b32 s26, s26, 7
	v_dot2_f32_bf16 v50, v44, v14, v50
	v_dot2_f32_bf16 v42, v46, v12, v42
	s_mov_b32 s27, s86
	v_dot2_f32_bf16 v50, v48, v18, v50
	v_dot2_f32_bf16 v42, v52, v16, v42
	v_cvt_scalef32_pk_bf16_fp4 v44, v70, 1.0
	v_cvt_scalef32_pk_bf16_fp4 v46, v70, 1.0 op_sel:[1,0,0]
	v_cvt_scalef32_pk_bf16_fp4 v48, v70, 1.0 op_sel:[0,1,0]
	v_cvt_scalef32_pk_bf16_fp4 v52, v70, 1.0 op_sel:[1,1,0]
	s_lshl_b64 s[26:27], s[26:27], 10
	v_dot2_f32_bf16 v50, v44, v22, v50
	v_dot2_f32_bf16 v42, v46, v20, v42
	s_add_u32 s26, s13, s26
	v_dot2_f32_bf16 v50, v48, v26, v50
	v_dot2_f32_bf16 v42, v52, v24, v42
	v_cvt_scalef32_pk_bf16_fp4 v44, v71, 1.0
	v_cvt_scalef32_pk_bf16_fp4 v46, v71, 1.0 op_sel:[1,0,0]
	v_cvt_scalef32_pk_bf16_fp4 v48, v71, 1.0 op_sel:[0,1,0]
	v_cvt_scalef32_pk_bf16_fp4 v52, v71, 1.0 op_sel:[1,1,0]
	s_addc_u32 s27, s12, s27
	v_dot2_f32_bf16 v50, v44, v30, v50
	v_dot2_f32_bf16 v42, v46, v28, v42
	v_mov_b32_e32 v38, 0
	v_dot2_f32_bf16 v50, v48, v36, v50
	v_dot2_f32_bf16 v42, v52, v34, v42
	s_nop 2
	v_add_f32_e32 v42, v50, v42
	global_load_dwordx4 v[68:71], v32, s[26:27]
	s_waitcnt vmcnt(15)
	v_cvt_scalef32_pk_bf16_fp4 v44, v72, 1.0
	v_cvt_scalef32_pk_bf16_fp4 v46, v72, 1.0 op_sel:[1,0,0]
	v_cvt_scalef32_pk_bf16_fp4 v48, v72, 1.0 op_sel:[0,1,0]
	v_cvt_scalef32_pk_bf16_fp4 v50, v72, 1.0 op_sel:[1,1,0]
	v_readlane_b32 s26, v2, 2
	v_dot2_f32_bf16 v43, v44, v6, 0
	v_dot2_f32_bf16 v43, v46, v4, v43
	v_dot2_f32_bf16 v43, v48, v10, v43
	s_lshr_b32 s26, s26, 7
	v_dot2_f32_bf16 v43, v50, v8, v43
	v_cvt_scalef32_pk_bf16_fp4 v46, v73, 1.0
	v_cvt_scalef32_pk_bf16_fp4 v48, v73, 1.0 op_sel:[1,0,0]
	v_cvt_scalef32_pk_bf16_fp4 v50, v73, 1.0 op_sel:[0,1,0]
	v_cvt_scalef32_pk_bf16_fp4 v54, v73, 1.0 op_sel:[1,1,0]
	s_mov_b32 s27, s86
	v_dot2_f32_bf16 v43, v46, v14, v43
	v_dot2_f32_bf16 v43, v48, v12, v43
	s_lshl_b64 s[26:27], s[26:27], 10
	v_dot2_f32_bf16 v43, v50, v18, v43
	v_dot2_f32_bf16 v43, v54, v16, v43
	v_cvt_scalef32_pk_bf16_fp4 v46, v74, 1.0
	v_cvt_scalef32_pk_bf16_fp4 v48, v74, 1.0 op_sel:[1,0,0]
	v_cvt_scalef32_pk_bf16_fp4 v50, v74, 1.0 op_sel:[0,1,0]
	v_cvt_scalef32_pk_bf16_fp4 v54, v74, 1.0 op_sel:[1,1,0]
	s_add_u32 s26, s13, s26
	v_dot2_f32_bf16 v43, v46, v22, v43
	v_dot2_f32_bf16 v43, v48, v20, v43
	s_addc_u32 s27, s12, s27
	v_dot2_f32_bf16 v43, v50, v26, v43
	v_dot2_f32_bf16 v43, v54, v24, v43
	v_cvt_scalef32_pk_bf16_fp4 v46, v75, 1.0
	v_cvt_scalef32_pk_bf16_fp4 v48, v75, 1.0 op_sel:[1,0,0]
	v_cvt_scalef32_pk_bf16_fp4 v50, v75, 1.0 op_sel:[0,1,0]
	v_cvt_scalef32_pk_bf16_fp4 v54, v75, 1.0 op_sel:[1,1,0]
	s_nop 0
	v_dot2_f32_bf16 v43, v46, v30, v43
	v_dot2_f32_bf16 v43, v48, v28, v43
	s_nop 0
	v_dot2_f32_bf16 v43, v50, v36, v43
	v_dot2_f32_bf16 v43, v54, v34, v43
	s_nop 0
	global_load_dwordx4 v[72:75], v32, s[26:27]
	s_waitcnt vmcnt(15)
; #define P4_FOR16(M) M(0) M(1) M(2) M(3) M(4) M(5) M(6) M(7) M(8) M(9) M(10) M(11) M(12) M(13) M(14) M(15)
; #define P4_U(i) { P4_DOT(b##i, part[i]); const int nk_ = __builtin_amdgcn_readlane(ksel, nb + i); P4_LOAD(b##i, Ug, nk_); }
; #define P4_U(i) { P4_DOT(b##i, part[i]); const int nk_ = __builtin_amdgcn_readlane(kn, i); P4_LOAD(b##i, nbase, nk_); }
; __device__ __forceinline__ void peer_gather_f4p(const float* X, const int* __restrict__ IDX, const float* __restrict__ G, ...
;     ...
; #pragma unroll 1
;         for (int bt = 0; bt < 7; ++bt) {
;             const int ksel = (bt + 1 < 4) ? k0 : k1;
;             const int nb = (16 * (bt + 1)) & 63;
;     ...
;             P4_FOR16(P4_U)
;     ...
;             P4_RED(bt);
;         }
	v_cvt_scalef32_pk_bf16_fp4 v44, v76, 1.0
	v_cvt_scalef32_pk_bf16_fp4 v46, v76, 1.0 op_sel:[1,0,0]
	v_cvt_scalef32_pk_bf16_fp4 v48, v76, 1.0 op_sel:[0,1,0]
	v_cvt_scalef32_pk_bf16_fp4 v50, v76, 1.0 op_sel:[1,1,0]
	v_dot2_f32_bf16 v52, v44, v6, 0
	v_dot2_f32_bf16 v44, v46, v4, 0
	v_dot2_f32_bf16 v52, v48, v10, v52
	v_readlane_b32 s26, v2, 3
	v_dot2_f32_bf16 v44, v50, v8, v44
	v_cvt_scalef32_pk_bf16_fp4 v46, v77, 1.0
	v_cvt_scalef32_pk_bf16_fp4 v48, v77, 1.0 op_sel:[1,0,0]
	v_cvt_scalef32_pk_bf16_fp4 v50, v77, 1.0 op_sel:[0,1,0]
	v_cvt_scalef32_pk_bf16_fp4 v54, v77, 1.0 op_sel:[1,1,0]
	s_lshr_b32 s26, s26, 7
	v_dot2_f32_bf16 v52, v46, v14, v52
	v_dot2_f32_bf16 v44, v48, v12, v44
	s_mov_b32 s27, s86
	v_dot2_f32_bf16 v52, v50, v18, v52
	v_dot2_f32_bf16 v44, v54, v16, v44
	v_cvt_scalef32_pk_bf16_fp4 v46, v78, 1.0
	v_cvt_scalef32_pk_bf16_fp4 v48, v78, 1.0 op_sel:[1,0,0]
	v_cvt_scalef32_pk_bf16_fp4 v50, v78, 1.0 op_sel:[0,1,0]
	v_cvt_scalef32_pk_bf16_fp4 v54, v78, 1.0 op_sel:[1,1,0]
	s_lshl_b64 s[26:27], s[26:27], 10
	v_dot2_f32_bf16 v52, v46, v22, v52
	v_dot2_f32_bf16 v44, v48, v20, v44
	s_add_u32 s26, s13, s26
	v_dot2_f32_bf16 v52, v50, v26, v52
	v_dot2_f32_bf16 v44, v54, v24, v44
	v_cvt_scalef32_pk_bf16_fp4 v46, v79, 1.0
	v_cvt_scalef32_pk_bf16_fp4 v48, v79, 1.0 op_sel:[1,0,0]
	v_cvt_scalef32_pk_bf16_fp4 v50, v79, 1.0 op_sel:[0,1,0]
	v_cvt_scalef32_pk_bf16_fp4 v54, v79, 1.0 op_sel:[1,1,0]
	s_addc_u32 s27, s12, s27
	v_dot2_f32_bf16 v52, v46, v30, v52
	v_dot2_f32_bf16 v44, v48, v28, v44
	s_nop 0
	v_dot2_f32_bf16 v52, v50, v36, v52
	v_dot2_f32_bf16 v44, v54, v34, v44
	s_nop 2
	v_add_f32_e32 v44, v52, v44
	global_load_dwordx4 v[76:79], v32, s[26:27]
	s_waitcnt vmcnt(15)
	v_cvt_scalef32_pk_bf16_fp4 v46, v84, 1.0
	v_cvt_scalef32_pk_bf16_fp4 v48, v84, 1.0 op_sel:[1,0,0]
	v_cvt_scalef32_pk_bf16_fp4 v50, v84, 1.0 op_sel:[0,1,0]
	v_cvt_scalef32_pk_bf16_fp4 v52, v84, 1.0 op_sel:[1,1,0]
	v_readlane_b32 s26, v2, 4
	v_dot2_f32_bf16 v45, v46, v6, 0
	v_dot2_f32_bf16 v45, v48, v4, v45
	v_dot2_f32_bf16 v45, v50, v10, v45
	s_lshr_b32 s26, s26, 7
	v_dot2_f32_bf16 v45, v52, v8, v45
	v_cvt_scalef32_pk_bf16_fp4 v48, v85, 1.0
	v_cvt_scalef32_pk_bf16_fp4 v50, v85, 1.0 op_sel:[1,0,0]
	v_cvt_scalef32_pk_bf16_fp4 v52, v85, 1.0 op_sel:[0,1,0]
	v_cvt_scalef32_pk_bf16_fp4 v56, v85, 1.0 op_sel:[1,1,0]
	s_mov_b32 s27, s86
	v_dot2_f32_bf16 v45, v48, v14, v45
	v_dot2_f32_bf16 v45, v50, v12, v45
	s_lshl_b64 s[26:27], s[26:27], 10
	v_dot2_f32_bf16 v45, v52, v18, v45
	v_dot2_f32_bf16 v45, v56, v16, v45
	v_cvt_scalef32_pk_bf16_fp4 v48, v86, 1.0
	v_cvt_scalef32_pk_bf16_fp4 v50, v86, 1.0 op_sel:[1,0,0]
	v_cvt_scalef32_pk_bf16_fp4 v52, v86, 1.0 op_sel:[0,1,0]
	v_cvt_scalef32_pk_bf16_fp4 v56, v86, 1.0 op_sel:[1,1,0]
	s_add_u32 s26, s13, s26
	v_dot2_f32_bf16 v45, v48, v22, v45
	v_dot2_f32_bf16 v45, v50, v20, v45
	s_addc_u32 s27, s12, s27
	v_dot2_f32_bf16 v45, v52, v26, v45
	v_dot2_f32_bf16 v45, v56, v24, v45
	v_cvt_scalef32_pk_bf16_fp4 v48, v87, 1.0
	v_cvt_scalef32_pk_bf16_fp4 v50, v87, 1.0 op_sel:[1,0,0]
	v_cvt_scalef32_pk_bf16_fp4 v52, v87, 1.0 op_sel:[0,1,0]
	v_cvt_scalef32_pk_bf16_fp4 v56, v87, 1.0 op_sel:[1,1,0]
	s_nop 0
	v_dot2_f32_bf16 v45, v48, v30, v45
	v_dot2_f32_bf16 v45, v50, v28, v45
	s_nop 0
	v_dot2_f32_bf16 v45, v52, v36, v45
	v_dot2_f32_bf16 v45, v56, v34, v45
	s_nop 0
	global_load_dwordx4 v[84:87], v32, s[26:27]
	s_waitcnt vmcnt(15)
	v_cvt_scalef32_pk_bf16_fp4 v46, v88, 1.0
	v_cvt_scalef32_pk_bf16_fp4 v48, v88, 1.0 op_sel:[1,0,0]
	v_cvt_scalef32_pk_bf16_fp4 v50, v88, 1.0 op_sel:[0,1,0]
	v_cvt_scalef32_pk_bf16_fp4 v52, v88, 1.0 op_sel:[1,1,0]
	v_dot2_f32_bf16 v54, v46, v6, 0
	v_dot2_f32_bf16 v46, v48, v4, 0
	v_dot2_f32_bf16 v54, v50, v10, v54
	v_readlane_b32 s26, v2, 5
	v_dot2_f32_bf16 v46, v52, v8, v46
	v_cvt_scalef32_pk_bf16_fp4 v48, v89, 1.0
	v_cvt_scalef32_pk_bf16_fp4 v50, v89, 1.0 op_sel:[1,0,0]
	v_cvt_scalef32_pk_bf16_fp4 v52, v89, 1.0 op_sel:[0,1,0]
	v_cvt_scalef32_pk_bf16_fp4 v56, v89, 1.0 op_sel:[1,1,0]
	s_lshr_b32 s26, s26, 7
	v_dot2_f32_bf16 v54, v48, v14, v54
	v_dot2_f32_bf16 v46, v50, v12, v46
	s_mov_b32 s27, s86
	v_dot2_f32_bf16 v54, v52, v18, v54
	v_dot2_f32_bf16 v46, v56, v16, v46
	v_cvt_scalef32_pk_bf16_fp4 v48, v90, 1.0
	v_cvt_scalef32_pk_bf16_fp4 v50, v90, 1.0 op_sel:[1,0,0]
	v_cvt_scalef32_pk_bf16_fp4 v52, v90, 1.0 op_sel:[0,1,0]
	v_cvt_scalef32_pk_bf16_fp4 v56, v90, 1.0 op_sel:[1,1,0]
	s_lshl_b64 s[26:27], s[26:27], 10
	v_dot2_f32_bf16 v54, v48, v22, v54
	v_dot2_f32_bf16 v46, v50, v20, v46
	s_add_u32 s26, s13, s26
	v_dot2_f32_bf16 v54, v52, v26, v54
	v_dot2_f32_bf16 v46, v56, v24, v46
	v_cvt_scalef32_pk_bf16_fp4 v48, v91, 1.0
	v_cvt_scalef32_pk_bf16_fp4 v50, v91, 1.0 op_sel:[1,0,0]
	v_cvt_scalef32_pk_bf16_fp4 v52, v91, 1.0 op_sel:[0,1,0]
	v_cvt_scalef32_pk_bf16_fp4 v56, v91, 1.0 op_sel:[1,1,0]
	s_addc_u32 s27, s12, s27
	v_dot2_f32_bf16 v54, v48, v30, v54
	v_dot2_f32_bf16 v46, v50, v28, v46
	s_nop 0
	v_dot2_f32_bf16 v54, v52, v36, v54
	v_dot2_f32_bf16 v46, v56, v34, v46
	s_nop 2
	v_add_f32_e32 v46, v54, v46
	global_load_dwordx4 v[88:91], v32, s[26:27]
	s_waitcnt vmcnt(15)
; #define P4_FOR16(M) M(0) M(1) M(2) M(3) M(4) M(5) M(6) M(7) M(8) M(9) M(10) M(11) M(12) M(13) M(14) M(15)
; #define P4_U(i) { P4_DOT(b##i, part[i]); const int nk_ = __builtin_amdgcn_readlane(ksel, nb + i); P4_LOAD(b##i, Ug, nk_); }
; #define P4_U(i) { P4_DOT(b##i, part[i]); const int nk_ = __builtin_amdgcn_readlane(kn, i); P4_LOAD(b##i, nbase, nk_); }
; __device__ __forceinline__ void peer_gather_f4p(const float* X, const int* __restrict__ IDX, const float* __restrict__ G, ...
;     ...
; #pragma unroll 1
;         for (int bt = 0; bt < 7; ++bt) {
;             const int ksel = (bt + 1 < 4) ? k0 : k1;
;             const int nb = (16 * (bt + 1)) & 63;
;     ...
;             P4_FOR16(P4_U)
;     ...
;             P4_RED(bt);
;         }
	v_cvt_scalef32_pk_bf16_fp4 v48, v92, 1.0
	v_cvt_scalef32_pk_bf16_fp4 v50, v92, 1.0 op_sel:[1,0,0]
	v_cvt_scalef32_pk_bf16_fp4 v52, v92, 1.0 op_sel:[0,1,0]
	v_cvt_scalef32_pk_bf16_fp4 v54, v92, 1.0 op_sel:[1,1,0]
	v_readlane_b32 s26, v2, 6
	v_dot2_f32_bf16 v47, v48, v6, 0
	v_dot2_f32_bf16 v47, v50, v4, v47
	v_dot2_f32_bf16 v47, v52, v10, v47
	s_lshr_b32 s26, s26, 7
	v_dot2_f32_bf16 v47, v54, v8, v47
	v_cvt_scalef32_pk_bf16_fp4 v50, v93, 1.0
	v_cvt_scalef32_pk_bf16_fp4 v52, v93, 1.0 op_sel:[1,0,0]
	v_cvt_scalef32_pk_bf16_fp4 v54, v93, 1.0 op_sel:[0,1,0]
	v_cvt_scalef32_pk_bf16_fp4 v58, v93, 1.0 op_sel:[1,1,0]
	s_mov_b32 s27, s86
	v_dot2_f32_bf16 v47, v50, v14, v47
	v_dot2_f32_bf16 v47, v52, v12, v47
	s_lshl_b64 s[26:27], s[26:27], 10
	v_dot2_f32_bf16 v47, v54, v18, v47
	v_dot2_f32_bf16 v47, v58, v16, v47
	v_cvt_scalef32_pk_bf16_fp4 v50, v94, 1.0
	v_cvt_scalef32_pk_bf16_fp4 v52, v94, 1.0 op_sel:[1,0,0]
	v_cvt_scalef32_pk_bf16_fp4 v54, v94, 1.0 op_sel:[0,1,0]
	v_cvt_scalef32_pk_bf16_fp4 v58, v94, 1.0 op_sel:[1,1,0]
	s_add_u32 s26, s13, s26
	v_dot2_f32_bf16 v47, v50, v22, v47
	v_dot2_f32_bf16 v47, v52, v20, v47
	s_addc_u32 s27, s12, s27
	v_dot2_f32_bf16 v47, v54, v26, v47
	v_dot2_f32_bf16 v47, v58, v24, v47
	v_cvt_scalef32_pk_bf16_fp4 v50, v95, 1.0
	v_cvt_scalef32_pk_bf16_fp4 v52, v95, 1.0 op_sel:[1,0,0]
	v_cvt_scalef32_pk_bf16_fp4 v54, v95, 1.0 op_sel:[0,1,0]
	v_cvt_scalef32_pk_bf16_fp4 v58, v95, 1.0 op_sel:[1,1,0]
	s_nop 0
	v_dot2_f32_bf16 v47, v50, v30, v47
	v_dot2_f32_bf16 v47, v52, v28, v47
	s_nop 0
	v_dot2_f32_bf16 v47, v54, v36, v47
	v_dot2_f32_bf16 v47, v58, v34, v47
	s_nop 0
	global_load_dwordx4 v[92:95], v32, s[26:27]
	s_waitcnt vmcnt(15)
	v_cvt_scalef32_pk_bf16_fp4 v48, v96, 1.0
	v_cvt_scalef32_pk_bf16_fp4 v50, v96, 1.0 op_sel:[1,0,0]
	v_cvt_scalef32_pk_bf16_fp4 v52, v96, 1.0 op_sel:[0,1,0]
	v_cvt_scalef32_pk_bf16_fp4 v54, v96, 1.0 op_sel:[1,1,0]
	v_dot2_f32_bf16 v56, v48, v6, 0
	v_dot2_f32_bf16 v48, v50, v4, 0
	v_dot2_f32_bf16 v56, v52, v10, v56
	v_readlane_b32 s26, v2, 7
	v_dot2_f32_bf16 v48, v54, v8, v48
	v_cvt_scalef32_pk_bf16_fp4 v50, v97, 1.0
	v_cvt_scalef32_pk_bf16_fp4 v52, v97, 1.0 op_sel:[1,0,0]
	v_cvt_scalef32_pk_bf16_fp4 v54, v97, 1.0 op_sel:[0,1,0]
	v_cvt_scalef32_pk_bf16_fp4 v58, v97, 1.0 op_sel:[1,1,0]
	s_lshr_b32 s26, s26, 7
	v_dot2_f32_bf16 v56, v50, v14, v56
	v_dot2_f32_bf16 v48, v52, v12, v48
	s_mov_b32 s27, s86
	v_dot2_f32_bf16 v56, v54, v18, v56
	v_dot2_f32_bf16 v48, v58, v16, v48
	v_cvt_scalef32_pk_bf16_fp4 v50, v98, 1.0
	v_cvt_scalef32_pk_bf16_fp4 v52, v98, 1.0 op_sel:[1,0,0]
	v_cvt_scalef32_pk_bf16_fp4 v54, v98, 1.0 op_sel:[0,1,0]
	v_cvt_scalef32_pk_bf16_fp4 v58, v98, 1.0 op_sel:[1,1,0]
	s_lshl_b64 s[26:27], s[26:27], 10
	v_dot2_f32_bf16 v56, v50, v22, v56
	v_dot2_f32_bf16 v48, v52, v20, v48
	s_add_u32 s26, s13, s26
	v_dot2_f32_bf16 v56, v54, v26, v56
	v_dot2_f32_bf16 v48, v58, v24, v48
	v_cvt_scalef32_pk_bf16_fp4 v50, v99, 1.0
	v_cvt_scalef32_pk_bf16_fp4 v52, v99, 1.0 op_sel:[1,0,0]
	v_cvt_scalef32_pk_bf16_fp4 v54, v99, 1.0 op_sel:[0,1,0]
	v_cvt_scalef32_pk_bf16_fp4 v58, v99, 1.0 op_sel:[1,1,0]
	s_addc_u32 s27, s12, s27
	v_dot2_f32_bf16 v56, v50, v30, v56
	v_dot2_f32_bf16 v48, v52, v28, v48
	s_nop 0
	v_dot2_f32_bf16 v56, v54, v36, v56
	v_dot2_f32_bf16 v48, v58, v34, v48
	s_nop 2
	v_add_f32_e32 v48, v56, v48
	global_load_dwordx4 v[96:99], v32, s[26:27]
	s_waitcnt vmcnt(15)
	v_cvt_scalef32_pk_bf16_fp4 v50, v100, 1.0
	v_cvt_scalef32_pk_bf16_fp4 v52, v100, 1.0 op_sel:[1,0,0]
	v_cvt_scalef32_pk_bf16_fp4 v54, v100, 1.0 op_sel:[0,1,0]
	v_cvt_scalef32_pk_bf16_fp4 v56, v100, 1.0 op_sel:[1,1,0]
	v_readlane_b32 s26, v2, 8
	v_dot2_f32_bf16 v49, v50, v6, 0
	v_dot2_f32_bf16 v49, v52, v4, v49
	v_dot2_f32_bf16 v49, v54, v10, v49
	s_lshr_b32 s26, s26, 7
	v_dot2_f32_bf16 v49, v56, v8, v49
	v_cvt_scalef32_pk_bf16_fp4 v52, v101, 1.0
	v_cvt_scalef32_pk_bf16_fp4 v54, v101, 1.0 op_sel:[1,0,0]
	v_cvt_scalef32_pk_bf16_fp4 v56, v101, 1.0 op_sel:[0,1,0]
	v_cvt_scalef32_pk_bf16_fp4 v60, v101, 1.0 op_sel:[1,1,0]
	s_mov_b32 s27, s86
	v_dot2_f32_bf16 v49, v52, v14, v49
	v_dot2_f32_bf16 v49, v54, v12, v49
	s_lshl_b64 s[26:27], s[26:27], 10
	v_dot2_f32_bf16 v49, v56, v18, v49
	v_dot2_f32_bf16 v49, v60, v16, v49
	v_cvt_scalef32_pk_bf16_fp4 v52, v102, 1.0
	v_cvt_scalef32_pk_bf16_fp4 v54, v102, 1.0 op_sel:[1,0,0]
	v_cvt_scalef32_pk_bf16_fp4 v56, v102, 1.0 op_sel:[0,1,0]
	v_cvt_scalef32_pk_bf16_fp4 v60, v102, 1.0 op_sel:[1,1,0]
	s_add_u32 s26, s13, s26
	v_dot2_f32_bf16 v49, v52, v22, v49
	v_dot2_f32_bf16 v49, v54, v20, v49
	s_addc_u32 s27, s12, s27
	v_dot2_f32_bf16 v49, v56, v26, v49
	v_dot2_f32_bf16 v49, v60, v24, v49
	v_cvt_scalef32_pk_bf16_fp4 v52, v103, 1.0
	v_cvt_scalef32_pk_bf16_fp4 v54, v103, 1.0 op_sel:[1,0,0]
	v_cvt_scalef32_pk_bf16_fp4 v56, v103, 1.0 op_sel:[0,1,0]
	v_cvt_scalef32_pk_bf16_fp4 v60, v103, 1.0 op_sel:[1,1,0]
	s_nop 0
	v_dot2_f32_bf16 v49, v52, v30, v49
	v_dot2_f32_bf16 v49, v54, v28, v49
	s_nop 0
	v_dot2_f32_bf16 v49, v56, v36, v49
	v_dot2_f32_bf16 v49, v60, v34, v49
	s_nop 0
	global_load_dwordx4 v[100:103], v32, s[26:27]
	s_waitcnt vmcnt(15)
; #define P4_FOR16(M) M(0) M(1) M(2) M(3) M(4) M(5) M(6) M(7) M(8) M(9) M(10) M(11) M(12) M(13) M(14) M(15)
; #define P4_U(i) { P4_DOT(b##i, part[i]); const int nk_ = __builtin_amdgcn_readlane(ksel, nb + i); P4_LOAD(b##i, Ug, nk_); }
; #define P4_U(i) { P4_DOT(b##i, part[i]); const int nk_ = __builtin_amdgcn_readlane(kn, i); P4_LOAD(b##i, nbase, nk_); }
; __device__ __forceinline__ void peer_gather_f4p(const float* X, const int* __restrict__ IDX, const float* __restrict__ G, ...
;     ...
; #pragma unroll 1
;         for (int bt = 0; bt < 7; ++bt) {
;             const int ksel = (bt + 1 < 4) ? k0 : k1;
;             const int nb = (16 * (bt + 1)) & 63;
;     ...
;             P4_FOR16(P4_U)
;     ...
;             P4_RED(bt);
;         }
	v_cvt_scalef32_pk_bf16_fp4 v50, v104, 1.0
	v_cvt_scalef32_pk_bf16_fp4 v52, v104, 1.0 op_sel:[1,0,0]
	v_cvt_scalef32_pk_bf16_fp4 v54, v104, 1.0 op_sel:[0,1,0]
	v_cvt_scalef32_pk_bf16_fp4 v56, v104, 1.0 op_sel:[1,1,0]
	v_dot2_f32_bf16 v58, v50, v6, 0
	v_dot2_f32_bf16 v50, v52, v4, 0
	v_dot2_f32_bf16 v58, v54, v10, v58
	v_readlane_b32 s26, v2, 9
	v_dot2_f32_bf16 v50, v56, v8, v50
	v_cvt_scalef32_pk_bf16_fp4 v52, v105, 1.0
	v_cvt_scalef32_pk_bf16_fp4 v54, v105, 1.0 op_sel:[1,0,0]
	v_cvt_scalef32_pk_bf16_fp4 v56, v105, 1.0 op_sel:[0,1,0]
	v_cvt_scalef32_pk_bf16_fp4 v60, v105, 1.0 op_sel:[1,1,0]
	s_lshr_b32 s26, s26, 7
	v_dot2_f32_bf16 v58, v52, v14, v58
	v_dot2_f32_bf16 v50, v54, v12, v50
	s_mov_b32 s27, s86
	v_dot2_f32_bf16 v58, v56, v18, v58
	v_dot2_f32_bf16 v50, v60, v16, v50
	v_cvt_scalef32_pk_bf16_fp4 v52, v106, 1.0
	v_cvt_scalef32_pk_bf16_fp4 v54, v106, 1.0 op_sel:[1,0,0]
	v_cvt_scalef32_pk_bf16_fp4 v56, v106, 1.0 op_sel:[0,1,0]
	v_cvt_scalef32_pk_bf16_fp4 v60, v106, 1.0 op_sel:[1,1,0]
	s_lshl_b64 s[26:27], s[26:27], 10
	v_dot2_f32_bf16 v58, v52, v22, v58
	v_dot2_f32_bf16 v50, v54, v20, v50
	s_add_u32 s26, s13, s26
	v_dot2_f32_bf16 v58, v56, v26, v58
	v_dot2_f32_bf16 v50, v60, v24, v50
	v_cvt_scalef32_pk_bf16_fp4 v52, v107, 1.0
	v_cvt_scalef32_pk_bf16_fp4 v54, v107, 1.0 op_sel:[1,0,0]
	v_cvt_scalef32_pk_bf16_fp4 v56, v107, 1.0 op_sel:[0,1,0]
	v_cvt_scalef32_pk_bf16_fp4 v60, v107, 1.0 op_sel:[1,1,0]
	s_addc_u32 s27, s12, s27
	v_dot2_f32_bf16 v58, v52, v30, v58
	v_dot2_f32_bf16 v50, v54, v28, v50
	s_nop 0
	v_dot2_f32_bf16 v58, v56, v36, v58
	v_dot2_f32_bf16 v50, v60, v34, v50
	s_nop 2
	v_add_f32_e32 v50, v58, v50
	global_load_dwordx4 v[104:107], v32, s[26:27]
	s_waitcnt vmcnt(15)
	v_cvt_scalef32_pk_bf16_fp4 v52, v108, 1.0
	v_cvt_scalef32_pk_bf16_fp4 v54, v108, 1.0 op_sel:[1,0,0]
	v_cvt_scalef32_pk_bf16_fp4 v56, v108, 1.0 op_sel:[0,1,0]
	v_cvt_scalef32_pk_bf16_fp4 v58, v108, 1.0 op_sel:[1,1,0]
	v_readlane_b32 s26, v2, 10
	v_dot2_f32_bf16 v51, v52, v6, 0
	v_dot2_f32_bf16 v51, v54, v4, v51
	v_dot2_f32_bf16 v51, v56, v10, v51
	s_lshr_b32 s26, s26, 7
	v_dot2_f32_bf16 v51, v58, v8, v51
	v_cvt_scalef32_pk_bf16_fp4 v54, v109, 1.0
	v_cvt_scalef32_pk_bf16_fp4 v56, v109, 1.0 op_sel:[1,0,0]
	v_cvt_scalef32_pk_bf16_fp4 v58, v109, 1.0 op_sel:[0,1,0]
	v_cvt_scalef32_pk_bf16_fp4 v62, v109, 1.0 op_sel:[1,1,0]
	s_mov_b32 s27, s86
	v_dot2_f32_bf16 v51, v54, v14, v51
	v_dot2_f32_bf16 v51, v56, v12, v51
	s_lshl_b64 s[26:27], s[26:27], 10
	v_dot2_f32_bf16 v51, v58, v18, v51
	v_dot2_f32_bf16 v51, v62, v16, v51
	v_cvt_scalef32_pk_bf16_fp4 v54, v110, 1.0
	v_cvt_scalef32_pk_bf16_fp4 v56, v110, 1.0 op_sel:[1,0,0]
	v_cvt_scalef32_pk_bf16_fp4 v58, v110, 1.0 op_sel:[0,1,0]
	v_cvt_scalef32_pk_bf16_fp4 v62, v110, 1.0 op_sel:[1,1,0]
	s_add_u32 s26, s13, s26
	v_dot2_f32_bf16 v51, v54, v22, v51
	v_dot2_f32_bf16 v51, v56, v20, v51
	s_addc_u32 s27, s12, s27
	v_dot2_f32_bf16 v51, v58, v26, v51
	v_dot2_f32_bf16 v51, v62, v24, v51
	v_cvt_scalef32_pk_bf16_fp4 v54, v111, 1.0
	v_cvt_scalef32_pk_bf16_fp4 v56, v111, 1.0 op_sel:[1,0,0]
	v_cvt_scalef32_pk_bf16_fp4 v58, v111, 1.0 op_sel:[0,1,0]
	v_cvt_scalef32_pk_bf16_fp4 v62, v111, 1.0 op_sel:[1,1,0]
	s_nop 0
	v_dot2_f32_bf16 v51, v54, v30, v51
	v_dot2_f32_bf16 v51, v56, v28, v51
	s_nop 0
	v_dot2_f32_bf16 v51, v58, v36, v51
	v_dot2_f32_bf16 v51, v62, v34, v51
	s_nop 0
	global_load_dwordx4 v[108:111], v32, s[26:27]
	s_waitcnt vmcnt(15)
	v_cvt_scalef32_pk_bf16_fp4 v52, v112, 1.0
	v_cvt_scalef32_pk_bf16_fp4 v54, v112, 1.0 op_sel:[1,0,0]
	v_cvt_scalef32_pk_bf16_fp4 v56, v112, 1.0 op_sel:[0,1,0]
	v_cvt_scalef32_pk_bf16_fp4 v58, v112, 1.0 op_sel:[1,1,0]
	v_dot2_f32_bf16 v80, v52, v6, 0
	v_dot2_f32_bf16 v80, v54, v4, v80
	v_dot2_f32_bf16 v80, v56, v10, v80
	v_readlane_b32 s26, v2, 11
	v_dot2_f32_bf16 v80, v58, v8, v80
	v_cvt_scalef32_pk_bf16_fp4 v54, v113, 1.0
	v_cvt_scalef32_pk_bf16_fp4 v56, v113, 1.0 op_sel:[1,0,0]
	v_cvt_scalef32_pk_bf16_fp4 v58, v113, 1.0 op_sel:[0,1,0]
	v_cvt_scalef32_pk_bf16_fp4 v62, v113, 1.0 op_sel:[1,1,0]
	s_lshr_b32 s26, s26, 7
	v_dot2_f32_bf16 v80, v54, v14, v80
	v_dot2_f32_bf16 v80, v56, v12, v80
	s_mov_b32 s27, s86
	v_dot2_f32_bf16 v80, v58, v18, v80
	v_dot2_f32_bf16 v80, v62, v16, v80
	v_cvt_scalef32_pk_bf16_fp4 v54, v114, 1.0
	v_cvt_scalef32_pk_bf16_fp4 v56, v114, 1.0 op_sel:[1,0,0]
	v_cvt_scalef32_pk_bf16_fp4 v58, v114, 1.0 op_sel:[0,1,0]
	v_cvt_scalef32_pk_bf16_fp4 v62, v114, 1.0 op_sel:[1,1,0]
	s_lshl_b64 s[26:27], s[26:27], 10
	v_dot2_f32_bf16 v80, v54, v22, v80
	v_dot2_f32_bf16 v80, v56, v20, v80
	s_add_u32 s26, s13, s26
	v_dot2_f32_bf16 v80, v58, v26, v80
	v_dot2_f32_bf16 v80, v62, v24, v80
	v_cvt_scalef32_pk_bf16_fp4 v54, v115, 1.0
	v_cvt_scalef32_pk_bf16_fp4 v56, v115, 1.0 op_sel:[1,0,0]
	v_cvt_scalef32_pk_bf16_fp4 v58, v115, 1.0 op_sel:[0,1,0]
	v_cvt_scalef32_pk_bf16_fp4 v62, v115, 1.0 op_sel:[1,1,0]
	s_addc_u32 s27, s12, s27
	v_dot2_f32_bf16 v80, v54, v30, v80
	v_dot2_f32_bf16 v80, v56, v28, v80
	s_nop 0
	v_dot2_f32_bf16 v80, v58, v36, v80
	v_dot2_f32_bf16 v80, v62, v34, v80
	s_nop 0
	global_load_dwordx4 v[112:115], v32, s[26:27]
	s_waitcnt vmcnt(15)
; #define P4_FOR16(M) M(0) M(1) M(2) M(3) M(4) M(5) M(6) M(7) M(8) M(9) M(10) M(11) M(12) M(13) M(14) M(15)
; #define P4_U(i) { P4_DOT(b##i, part[i]); const int nk_ = __builtin_amdgcn_readlane(ksel, nb + i); P4_LOAD(b##i, Ug, nk_); }
; #define P4_U(i) { P4_DOT(b##i, part[i]); const int nk_ = __builtin_amdgcn_readlane(kn, i); P4_LOAD(b##i, nbase, nk_); }
; __device__ __forceinline__ void peer_gather_f4p(const float* X, const int* __restrict__ IDX, const float* __restrict__ G, ...
;     ...
; #pragma unroll 1
;         for (int bt = 0; bt < 7; ++bt) {
;             const int ksel = (bt + 1 < 4) ? k0 : k1;
;             const int nb = (16 * (bt + 1)) & 63;
;     ...
;             P4_FOR16(P4_U)
;     ...
;             P4_RED(bt);
;         }
	v_cvt_scalef32_pk_bf16_fp4 v52, v116, 1.0
	v_cvt_scalef32_pk_bf16_fp4 v54, v116, 1.0 op_sel:[1,0,0]
	v_cvt_scalef32_pk_bf16_fp4 v56, v116, 1.0 op_sel:[0,1,0]
	v_cvt_scalef32_pk_bf16_fp4 v58, v116, 1.0 op_sel:[1,1,0]
	v_dot2_f32_bf16 v81, v52, v6, 0
	v_dot2_f32_bf16 v81, v54, v4, v81
	v_dot2_f32_bf16 v81, v56, v10, v81
	v_readlane_b32 s26, v2, 12
	v_dot2_f32_bf16 v81, v58, v8, v81
	v_cvt_scalef32_pk_bf16_fp4 v54, v117, 1.0
	v_cvt_scalef32_pk_bf16_fp4 v56, v117, 1.0 op_sel:[1,0,0]
	v_cvt_scalef32_pk_bf16_fp4 v58, v117, 1.0 op_sel:[0,1,0]
	v_cvt_scalef32_pk_bf16_fp4 v62, v117, 1.0 op_sel:[1,1,0]
	s_lshr_b32 s26, s26, 7
	v_dot2_f32_bf16 v81, v54, v14, v81
	v_dot2_f32_bf16 v81, v56, v12, v81
	s_mov_b32 s27, s86
	v_dot2_f32_bf16 v81, v58, v18, v81
	v_dot2_f32_bf16 v81, v62, v16, v81
	v_cvt_scalef32_pk_bf16_fp4 v54, v118, 1.0
	v_cvt_scalef32_pk_bf16_fp4 v56, v118, 1.0 op_sel:[1,0,0]
	v_cvt_scalef32_pk_bf16_fp4 v58, v118, 1.0 op_sel:[0,1,0]
	v_cvt_scalef32_pk_bf16_fp4 v62, v118, 1.0 op_sel:[1,1,0]
	s_lshl_b64 s[26:27], s[26:27], 10
	v_dot2_f32_bf16 v81, v54, v22, v81
	v_dot2_f32_bf16 v81, v56, v20, v81
	s_add_u32 s26, s13, s26
	v_dot2_f32_bf16 v81, v58, v26, v81
	v_dot2_f32_bf16 v81, v62, v24, v81
	v_cvt_scalef32_pk_bf16_fp4 v54, v119, 1.0
	v_cvt_scalef32_pk_bf16_fp4 v56, v119, 1.0 op_sel:[1,0,0]
	v_cvt_scalef32_pk_bf16_fp4 v58, v119, 1.0 op_sel:[0,1,0]
	v_cvt_scalef32_pk_bf16_fp4 v62, v119, 1.0 op_sel:[1,1,0]
	s_addc_u32 s27, s12, s27
	v_dot2_f32_bf16 v81, v54, v30, v81
	v_dot2_f32_bf16 v81, v56, v28, v81
	s_nop 0
	v_dot2_f32_bf16 v81, v58, v36, v81
	v_dot2_f32_bf16 v81, v62, v34, v81
	s_nop 0
	global_load_dwordx4 v[116:119], v32, s[26:27]
	s_waitcnt vmcnt(15)
	v_cvt_scalef32_pk_bf16_fp4 v52, v120, 1.0
	v_cvt_scalef32_pk_bf16_fp4 v54, v120, 1.0 op_sel:[1,0,0]
	v_cvt_scalef32_pk_bf16_fp4 v56, v120, 1.0 op_sel:[0,1,0]
	v_cvt_scalef32_pk_bf16_fp4 v58, v120, 1.0 op_sel:[1,1,0]
	v_dot2_f32_bf16 v82, v52, v6, 0
	v_dot2_f32_bf16 v82, v54, v4, v82
	v_dot2_f32_bf16 v82, v56, v10, v82
	v_readlane_b32 s26, v2, 13
	v_dot2_f32_bf16 v82, v58, v8, v82
	v_cvt_scalef32_pk_bf16_fp4 v54, v121, 1.0
	v_cvt_scalef32_pk_bf16_fp4 v56, v121, 1.0 op_sel:[1,0,0]
	v_cvt_scalef32_pk_bf16_fp4 v58, v121, 1.0 op_sel:[0,1,0]
	v_cvt_scalef32_pk_bf16_fp4 v62, v121, 1.0 op_sel:[1,1,0]
	s_lshr_b32 s26, s26, 7
	v_dot2_f32_bf16 v82, v54, v14, v82
	v_dot2_f32_bf16 v82, v56, v12, v82
	s_mov_b32 s27, s86
	v_dot2_f32_bf16 v82, v58, v18, v82
	v_dot2_f32_bf16 v82, v62, v16, v82
	v_cvt_scalef32_pk_bf16_fp4 v54, v122, 1.0
	v_cvt_scalef32_pk_bf16_fp4 v56, v122, 1.0 op_sel:[1,0,0]
	v_cvt_scalef32_pk_bf16_fp4 v58, v122, 1.0 op_sel:[0,1,0]
	v_cvt_scalef32_pk_bf16_fp4 v62, v122, 1.0 op_sel:[1,1,0]
	s_lshl_b64 s[26:27], s[26:27], 10
	v_dot2_f32_bf16 v82, v54, v22, v82
	v_dot2_f32_bf16 v82, v56, v20, v82
	s_add_u32 s26, s13, s26
	v_dot2_f32_bf16 v82, v58, v26, v82
	v_dot2_f32_bf16 v82, v62, v24, v82
	v_cvt_scalef32_pk_bf16_fp4 v54, v123, 1.0
	v_cvt_scalef32_pk_bf16_fp4 v56, v123, 1.0 op_sel:[1,0,0]
	v_cvt_scalef32_pk_bf16_fp4 v58, v123, 1.0 op_sel:[0,1,0]
	v_cvt_scalef32_pk_bf16_fp4 v62, v123, 1.0 op_sel:[1,1,0]
	s_addc_u32 s27, s12, s27
	v_dot2_f32_bf16 v82, v54, v30, v82
	v_dot2_f32_bf16 v82, v56, v28, v82
	s_nop 0
	v_dot2_f32_bf16 v82, v58, v36, v82
	v_dot2_f32_bf16 v82, v62, v34, v82
	s_nop 0
	global_load_dwordx4 v[120:123], v32, s[26:27]
	s_waitcnt vmcnt(15)
	v_cvt_scalef32_pk_bf16_fp4 v52, v124, 1.0
	v_cvt_scalef32_pk_bf16_fp4 v54, v124, 1.0 op_sel:[1,0,0]
	v_cvt_scalef32_pk_bf16_fp4 v56, v124, 1.0 op_sel:[0,1,0]
	v_cvt_scalef32_pk_bf16_fp4 v58, v124, 1.0 op_sel:[1,1,0]
	v_dot2_f32_bf16 v60, v52, v6, 0
	v_dot2_f32_bf16 v52, v54, v4, 0
	v_dot2_f32_bf16 v60, v56, v10, v60
	v_readlane_b32 s26, v2, 14
	v_dot2_f32_bf16 v52, v58, v8, v52
	v_cvt_scalef32_pk_bf16_fp4 v54, v125, 1.0
	v_cvt_scalef32_pk_bf16_fp4 v56, v125, 1.0 op_sel:[1,0,0]
	v_cvt_scalef32_pk_bf16_fp4 v58, v125, 1.0 op_sel:[0,1,0]
	v_cvt_scalef32_pk_bf16_fp4 v62, v125, 1.0 op_sel:[1,1,0]
	s_lshr_b32 s26, s26, 7
	v_dot2_f32_bf16 v60, v54, v14, v60
	v_dot2_f32_bf16 v52, v56, v12, v52
	s_mov_b32 s27, s86
	v_dot2_f32_bf16 v60, v58, v18, v60
	v_dot2_f32_bf16 v52, v62, v16, v52
	v_cvt_scalef32_pk_bf16_fp4 v54, v126, 1.0
	v_cvt_scalef32_pk_bf16_fp4 v56, v126, 1.0 op_sel:[1,0,0]
	v_cvt_scalef32_pk_bf16_fp4 v58, v126, 1.0 op_sel:[0,1,0]
	v_cvt_scalef32_pk_bf16_fp4 v62, v126, 1.0 op_sel:[1,1,0]
	s_lshl_b64 s[26:27], s[26:27], 10
	v_dot2_f32_bf16 v60, v54, v22, v60
	v_dot2_f32_bf16 v52, v56, v20, v52
	s_add_u32 s26, s13, s26
	v_dot2_f32_bf16 v60, v58, v26, v60
	v_dot2_f32_bf16 v52, v62, v24, v52
	v_cvt_scalef32_pk_bf16_fp4 v54, v127, 1.0
	v_cvt_scalef32_pk_bf16_fp4 v56, v127, 1.0 op_sel:[1,0,0]
	v_cvt_scalef32_pk_bf16_fp4 v58, v127, 1.0 op_sel:[0,1,0]
	v_cvt_scalef32_pk_bf16_fp4 v62, v127, 1.0 op_sel:[1,1,0]
	s_addc_u32 s27, s12, s27
	v_dot2_f32_bf16 v60, v54, v30, v60
	v_dot2_f32_bf16 v52, v56, v28, v52
	s_nop 0
	v_dot2_f32_bf16 v60, v58, v36, v60
	v_dot2_f32_bf16 v52, v62, v34, v52
	s_nop 0
	s_nop 2
	v_add_f32_e32 v62, v60, v52
	global_load_dwordx4 v[124:127], v32, s[26:27]
	s_waitcnt vmcnt(15)
	v_cvt_scalef32_pk_bf16_fp4 v52, v128, 1.0
	v_cvt_scalef32_pk_bf16_fp4 v54, v128, 1.0 op_sel:[1,0,0]
	v_cvt_scalef32_pk_bf16_fp4 v56, v128, 1.0 op_sel:[0,1,0]
	v_cvt_scalef32_pk_bf16_fp4 v58, v128, 1.0 op_sel:[1,1,0]
	v_readlane_b32 s26, v2, 15
	v_dot2_f32_bf16 v60, v52, v6, 0
	v_dot2c_f32_bf16_e32 v38, v54, v4
	s_lshr_b32 s26, s26, 7
	v_dot2_f32_bf16 v60, v56, v10, v60
	v_dot2c_f32_bf16_e32 v38, v58, v8
	v_cvt_scalef32_pk_bf16_fp4 v4, v129, 1.0
	v_cvt_scalef32_pk_bf16_fp4 v6, v129, 1.0 op_sel:[1,0,0]
	v_cvt_scalef32_pk_bf16_fp4 v8, v129, 1.0 op_sel:[0,1,0]
	v_cvt_scalef32_pk_bf16_fp4 v10, v129, 1.0 op_sel:[1,1,0]
	s_mov_b32 s27, s86
	v_dot2_f32_bf16 v60, v4, v14, v60
	v_dot2c_f32_bf16_e32 v38, v6, v12
	s_lshl_b64 s[26:27], s[26:27], 10
	v_dot2_f32_bf16 v60, v8, v18, v60
	v_dot2c_f32_bf16_e32 v38, v10, v16
	v_cvt_scalef32_pk_bf16_fp4 v4, v130, 1.0
	v_cvt_scalef32_pk_bf16_fp4 v6, v130, 1.0 op_sel:[1,0,0]
	v_cvt_scalef32_pk_bf16_fp4 v8, v130, 1.0 op_sel:[0,1,0]
	v_cvt_scalef32_pk_bf16_fp4 v10, v130, 1.0 op_sel:[1,1,0]
	s_add_u32 s26, s13, s26
	v_dot2_f32_bf16 v60, v4, v22, v60
	v_dot2c_f32_bf16_e32 v38, v6, v20
	s_addc_u32 s27, s12, s27
	v_dot2_f32_bf16 v60, v8, v26, v60
	v_dot2c_f32_bf16_e32 v38, v10, v24
	v_cvt_scalef32_pk_bf16_fp4 v4, v131, 1.0
	v_cvt_scalef32_pk_bf16_fp4 v6, v131, 1.0 op_sel:[1,0,0]
	v_cvt_scalef32_pk_bf16_fp4 v8, v131, 1.0 op_sel:[0,1,0]
	v_cvt_scalef32_pk_bf16_fp4 v10, v131, 1.0 op_sel:[1,1,0]
	v_cndmask_b32_e64 v2, v49, v41, s[46:47]
	v_dot2_f32_bf16 v60, v4, v30, v60
	v_dot2c_f32_bf16_e32 v38, v6, v28
	v_cndmask_b32_e64 v7, v43, v51, s[46:47]
	v_dot2_f32_bf16 v60, v8, v36, v60
	v_dot2c_f32_bf16_e32 v38, v10, v34
	ds_swizzle_b32 v7, v7 offset:swizzle(SWAP,8)
	s_nop 2
	v_add_f32_e32 v6, v60, v38
	global_load_dwordx4 v[128:131], v32, s[26:27]
	v_cndmask_b32_e64 v4, v41, v49, s[46:47]
	ds_swizzle_b32 v4, v4 offset:swizzle(SWAP,8)
	v_cndmask_b32_e64 v5, v42, v50, s[46:47]
	ds_swizzle_b32 v5, v5 offset:swizzle(SWAP,8)
	v_cndmask_b32_e64 v8, v44, v80, s[46:47]
	ds_swizzle_b32 v8, v8 offset:swizzle(SWAP,8)
	v_cndmask_b32_e64 v9, v45, v81, s[46:47]
	ds_swizzle_b32 v9, v9 offset:swizzle(SWAP,8)
	v_cndmask_b32_e64 v10, v46, v82, s[46:47]
	s_waitcnt lgkmcnt(3)
	v_add_f32_e32 v2, v2, v4
	v_cndmask_b32_e64 v4, v50, v42, s[46:47]
	ds_swizzle_b32 v10, v10 offset:swizzle(SWAP,8)
	v_cndmask_b32_e64 v11, v47, v62, s[46:47]
	s_waitcnt lgkmcnt(3)
	v_add_f32_e32 v4, v4, v5
	v_cndmask_b32_e64 v5, v51, v43, s[46:47]
	ds_swizzle_b32 v11, v11 offset:swizzle(SWAP,8)
	v_add_f32_e32 v5, v5, v7
	v_cndmask_b32_e64 v7, v80, v44, s[46:47]
	s_waitcnt lgkmcnt(3)
	v_add_f32_e32 v7, v7, v8
	v_cndmask_b32_e64 v8, v81, v45, s[46:47]
	s_waitcnt lgkmcnt(2)
	v_add_f32_e32 v8, v8, v9
	v_cndmask_b32_e64 v9, v82, v46, s[46:47]
	s_waitcnt lgkmcnt(1)
	v_add_f32_e32 v9, v9, v10
	v_cndmask_b32_e64 v10, v62, v47, s[46:47]
	s_waitcnt lgkmcnt(0)
	v_add_f32_e32 v10, v10, v11
	v_cndmask_b32_e64 v11, v6, v48, s[46:47]
	v_cndmask_b32_e64 v6, v48, v6, s[46:47]
	ds_swizzle_b32 v6, v6 offset:swizzle(SWAP,8)
	s_waitcnt lgkmcnt(0)
	v_add_f32_e32 v6, v11, v6
	v_cndmask_b32_e64 v11, v8, v2, s[44:45]
	v_cndmask_b32_e64 v2, v2, v8, s[44:45]
	v_cndmask_b32_e64 v8, v9, v4, s[44:45]
	v_cndmask_b32_e64 v4, v4, v9, s[44:45]
	ds_swizzle_b32 v4, v4 offset:swizzle(SWAP,4)
	ds_swizzle_b32 v2, v2 offset:swizzle(SWAP,4)
	s_waitcnt lgkmcnt(1)
	v_add_f32_e32 v4, v8, v4
	v_cndmask_b32_e64 v8, v10, v5, s[44:45]
	v_cndmask_b32_e64 v5, v5, v10, s[44:45]
	ds_swizzle_b32 v5, v5 offset:swizzle(SWAP,4)
	s_waitcnt lgkmcnt(1)
	v_add_f32_e32 v2, v11, v2
	s_waitcnt lgkmcnt(0)
	v_add_f32_e32 v5, v8, v5
	v_cndmask_b32_e64 v8, v6, v7, s[44:45]
	v_cndmask_b32_e64 v6, v7, v6, s[44:45]
	ds_swizzle_b32 v6, v6 offset:swizzle(SWAP,4)
	v_cndmask_b32_e64 v7, v5, v2, s[42:43]
	v_cndmask_b32_e64 v2, v2, v5, s[42:43]
	ds_swizzle_b32 v2, v2 offset:swizzle(SWAP,2)
	s_waitcnt lgkmcnt(1)
	v_add_f32_e32 v6, v8, v6
	v_cndmask_b32_e64 v5, v6, v4, s[42:43]
	v_cndmask_b32_e64 v4, v4, v6, s[42:43]
	ds_swizzle_b32 v4, v4 offset:swizzle(SWAP,2)
	s_waitcnt lgkmcnt(1)
	v_add_f32_e32 v2, v7, v2
	s_waitcnt lgkmcnt(0)
	v_add_f32_e32 v4, v5, v4
	v_cndmask_b32_e64 v5, v4, v2, s[40:41]
	v_cndmask_b32_e64 v2, v2, v4, s[40:41]
	ds_swizzle_b32 v2, v2 offset:swizzle(SWAP,1)
	s_waitcnt lgkmcnt(0)
	v_add_f32_e32 v2, v5, v2
	ds_swizzle_b32 v4, v2 offset:swizzle(SWAP,16)
	s_waitcnt lgkmcnt(0)
	v_add_f32_e32 v2, v2, v4
	v_mov_b32_e32 v4, v2
	s_nop 1
	v_permlane32_swap_b32_e32 v2, v4
	v_add_f32_e32 v6, v2, v4
	v_lshl_add_u32 v2, v40, 2, s14
	v_add_u32_e32 v4, 0xc0, v2
	ds_read2st64_b32 v[4:5], v4 offset0:9 offset1:17
	s_waitcnt lgkmcnt(0)
	v_mul_f32_e32 v4, v4, v6
	v_mul_f32_e32 v6, 0x3d372713, v4
	v_mul_f32_e32 v6, v4, v6
	v_fma_f32 v6, v4, v6, v4
	v_mul_f32_e32 v6, 0x3f4c422a, v6
	v_cmp_nlt_f32_e64 s[12:13], |v6|, s25
	s_and_saveexec_b64 s[26:27], s[12:13]
	s_xor_b64 s[12:13], exec, s[26:27]
	s_cbranch_execz .LBB0_1240
	v_add_f32_e64 v7, |v6|, |v6|
	v_mul_f32_e32 v8, 0x3fb8aa3b, v7
	v_rndne_f32_e32 v9, v8
	v_sub_f32_e32 v10, v8, v9
	v_fma_f32 v8, v7, s70, -v8
	v_fmac_f32_e32 v8, 0x32a5705f, v7
	v_add_f32_e32 v8, v10, v8
	v_cvt_i32_f32_e32 v9, v9
	v_exp_f32_e32 v8, v8
	v_cmp_ngt_f32_e64 s[40:41], s67, v7
	v_ldexp_f32 v8, v8, v9
	s_nop 0
	v_cndmask_b32_e64 v8, 0, v8, s[40:41]
	v_cmp_nlt_f32_e64 s[40:41], s68, v7
	s_nop 1
	v_cndmask_b32_e64 v7, v205, v8, s[40:41]
	v_add_f32_e32 v7, 1.0, v7
	v_rcp_f32_e32 v7, v7
	s_nop 0
	v_fma_f32 v7, v7, -2.0, 1.0
	s_andn2_saveexec_b64 s[12:13], s[12:13]
	s_cbranch_execnz .LBB0_1241
